# GEMM loops: wave priority inverted (MFMA segment runs at priority 0, load segment at priority 1)
# speedup vs baseline: 1.0080x; 1.0080x over previous
.LBB0_220:
	ds_read_b128 v[104:107], v171
	ds_read_b128 v[108:111], v171 offset:1024
	ds_read_b128 v[112:115], v171 offset:2048
	ds_read_b128 v[116:119], v171 offset:3072
	ds_read_b128 v[160:163], v172
	ds_read_b128 v[164:167], v172 offset:1024
	ds_read_b128 v[178:181], v172 offset:2048
	ds_read_b128 v[182:185], v172 offset:3072
	s_add_u32 s26, s24, 0xfffc0080
	s_addc_u32 s27, s25, -1
	s_cmp_eq_u32 s69, 12
	s_cselect_b32 s35, s17, s27
	s_cselect_b32 s34, s65, s26
	s_cselect_b32 s27, s15, s68
	s_cselect_b32 s26, s66, s67
	v_lshl_add_u64 v[202:203], s[24:25], 0, v[152:153]
	s_add_i32 m0, s23, 0xc000
	ds_read_b128 v[186:189], v173
	ds_read_b128 v[190:193], v173 offset:1024
	ds_read_b128 v[194:197], v173 offset:2048
	ds_read_b128 v[198:201], v173 offset:3072
	ds_read_b128 v[206:209], v173 offset:4096
	ds_read_b128 v[210:213], v173 offset:5120
	ds_read_b128 v[214:217], v173 offset:6144
	ds_read_b128 v[218:221], v173 offset:7168
	global_load_lds_dwordx4 v[202:203], off
	v_lshl_add_u64 v[202:203], s[24:25], 0, v[154:155]
	s_add_i32 m0, s23, 0xe000
	s_nop 0
	global_load_lds_dwordx4 v[202:203], off
	s_waitcnt vmcnt(8)
	s_waitcnt lgkmcnt(0)
	s_barrier
	s_setprio 0
	s_waitcnt lgkmcnt(0)
	v_mfma_f32_16x16x32_f16 v[140:143], v[104:107], v[186:189], v[140:143]
	v_mfma_f32_16x16x32_f16 v[136:139], v[112:115], v[186:189], v[136:139]
	v_mfma_f32_16x16x32_f16 v[124:127], v[104:107], v[194:197], v[124:127]
	v_mfma_f32_16x16x32_f16 v[120:123], v[112:115], v[194:197], v[120:123]
	v_mfma_f32_16x16x32_f16 v[92:95], v[104:107], v[206:209], v[92:95]
	v_mfma_f32_16x16x32_f16 v[88:91], v[112:115], v[206:209], v[88:91]
	v_mfma_f32_16x16x32_f16 v[76:79], v[104:107], v[214:217], v[76:79]
	v_mfma_f32_16x16x32_f16 v[72:75], v[112:115], v[214:217], v[72:75]
	v_mfma_f32_16x16x32_f16 v[140:143], v[108:111], v[190:193], v[140:143]
	v_mfma_f32_16x16x32_f16 v[136:139], v[116:119], v[190:193], v[136:139]
	v_mfma_f32_16x16x32_f16 v[124:127], v[108:111], v[198:201], v[124:127]
	v_mfma_f32_16x16x32_f16 v[120:123], v[116:119], v[198:201], v[120:123]
	v_mfma_f32_16x16x32_f16 v[92:95], v[108:111], v[210:213], v[92:95]
	v_mfma_f32_16x16x32_f16 v[88:91], v[116:119], v[210:213], v[88:91]
	v_mfma_f32_16x16x32_f16 v[76:79], v[108:111], v[218:221], v[76:79]
	v_mfma_f32_16x16x32_f16 v[72:75], v[116:119], v[218:221], v[72:75]
	s_setprio 1
	s_setprio 0
	v_mfma_f32_16x16x32_f16 v[132:135], v[160:163], v[186:189], v[132:135]
	v_mfma_f32_16x16x32_f16 v[128:131], v[178:181], v[186:189], v[128:131]
	v_mfma_f32_16x16x32_f16 v[100:103], v[160:163], v[194:197], v[100:103]
	v_mfma_f32_16x16x32_f16 v[96:99], v[178:181], v[194:197], v[96:99]
	v_mfma_f32_16x16x32_f16 v[84:87], v[160:163], v[206:209], v[84:87]
	v_mfma_f32_16x16x32_f16 v[80:83], v[178:181], v[206:209], v[80:83]
	v_mfma_f32_16x16x32_f16 v[68:71], v[160:163], v[214:217], v[68:71]
	v_mfma_f32_16x16x32_f16 v[64:67], v[178:181], v[214:217], v[64:67]
	v_mfma_f32_16x16x32_f16 v[132:135], v[164:167], v[190:193], v[132:135]
	v_mfma_f32_16x16x32_f16 v[128:131], v[182:185], v[190:193], v[128:131]
	v_mfma_f32_16x16x32_f16 v[100:103], v[164:167], v[198:201], v[100:103]
	v_mfma_f32_16x16x32_f16 v[96:99], v[182:185], v[198:201], v[96:99]
	v_mfma_f32_16x16x32_f16 v[84:87], v[164:167], v[210:213], v[84:87]
	v_mfma_f32_16x16x32_f16 v[80:83], v[182:185], v[210:213], v[80:83]
	v_mfma_f32_16x16x32_f16 v[68:71], v[164:167], v[218:221], v[68:71]
	v_mfma_f32_16x16x32_f16 v[64:67], v[182:185], v[218:221], v[64:67]
	s_setprio 1
	s_barrier
	s_add_i32 s70, s60, s44
	v_lshl_add_u64 v[202:203], s[26:27], 0, v[146:147]
	s_mov_b32 m0, s70
	ds_read_b128 v[186:189], v173 offset:16384
	ds_read_b128 v[190:193], v173 offset:17408
	ds_read_b128 v[194:197], v173 offset:18432
	ds_read_b128 v[198:201], v173 offset:19456
	ds_read_b128 v[206:209], v173 offset:20480
	ds_read_b128 v[210:213], v173 offset:21504
	ds_read_b128 v[214:217], v173 offset:22528
	ds_read_b128 v[218:221], v173 offset:23552
	global_load_lds_dwordx4 v[202:203], off
	s_add_i32 m0, s70, 0x2000
	s_add_u32 s70, s26, 0x40000
	v_lshl_add_u64 v[222:223], s[26:27], 0, v[150:151]
	s_addc_u32 s71, s27, 0
	s_add_i32 s72, s61, s44
	global_load_lds_dwordx4 v[222:223], off
	v_lshl_add_u64 v[224:225], s[70:71], 0, v[146:147]
	s_mov_b32 m0, s72
	v_lshl_add_u64 v[226:227], s[34:35], 0, v[148:149]
	global_load_lds_dwordx4 v[224:225], off
	v_lshl_add_u64 v[224:225], s[70:71], 0, v[150:151]
	s_add_i32 m0, s72, 0x2000
	s_nop 0
	global_load_lds_dwordx4 v[224:225], off
	v_lshl_add_u64 v[224:225], s[34:35], 0, v[144:145]
	s_mov_b32 m0, s23
	s_nop 0
	global_load_lds_dwordx4 v[224:225], off
	s_mov_b32 m0, s45
	s_nop 0
	global_load_lds_dwordx4 v[226:227], off
	s_waitcnt vmcnt(8)
	s_waitcnt lgkmcnt(0)
	s_barrier
	s_setprio 0
	s_waitcnt lgkmcnt(0)
	v_mfma_f32_16x16x32_f16 v[60:63], v[104:107], v[186:189], v[60:63]
	v_mfma_f32_16x16x32_f16 v[56:59], v[112:115], v[186:189], v[56:59]
	v_mfma_f32_16x16x32_f16 v[44:47], v[104:107], v[194:197], v[44:47]
	v_mfma_f32_16x16x32_f16 v[40:43], v[112:115], v[194:197], v[40:43]
	v_mfma_f32_16x16x32_f16 v[28:31], v[104:107], v[206:209], v[28:31]
	v_mfma_f32_16x16x32_f16 v[24:27], v[112:115], v[206:209], v[24:27]
	v_mfma_f32_16x16x32_f16 v[12:15], v[104:107], v[214:217], v[12:15]
	v_mfma_f32_16x16x32_f16 v[8:11], v[112:115], v[214:217], v[8:11]
	v_mfma_f32_16x16x32_f16 v[60:63], v[108:111], v[190:193], v[60:63]
	v_mfma_f32_16x16x32_f16 v[56:59], v[116:119], v[190:193], v[56:59]
	v_mfma_f32_16x16x32_f16 v[44:47], v[108:111], v[198:201], v[44:47]
	v_mfma_f32_16x16x32_f16 v[40:43], v[116:119], v[198:201], v[40:43]
	v_mfma_f32_16x16x32_f16 v[28:31], v[108:111], v[210:213], v[28:31]
	v_mfma_f32_16x16x32_f16 v[24:27], v[116:119], v[210:213], v[24:27]
	v_mfma_f32_16x16x32_f16 v[12:15], v[108:111], v[218:221], v[12:15]
	v_mfma_f32_16x16x32_f16 v[8:11], v[116:119], v[218:221], v[8:11]
	s_setprio 1
	s_setprio 0
	v_mfma_f32_16x16x32_f16 v[52:55], v[160:163], v[186:189], v[52:55]
	v_mfma_f32_16x16x32_f16 v[48:51], v[178:181], v[186:189], v[48:51]
	v_mfma_f32_16x16x32_f16 v[36:39], v[160:163], v[194:197], v[36:39]
	v_mfma_f32_16x16x32_f16 v[32:35], v[178:181], v[194:197], v[32:35]
	v_mfma_f32_16x16x32_f16 v[20:23], v[160:163], v[206:209], v[20:23]
	v_mfma_f32_16x16x32_f16 v[16:19], v[178:181], v[206:209], v[16:19]
	v_mfma_f32_16x16x32_f16 v[4:7], v[160:163], v[214:217], v[4:7]
	v_mfma_f32_16x16x32_f16 v[0:3], v[178:181], v[214:217], v[0:3]
	v_mfma_f32_16x16x32_f16 v[52:55], v[164:167], v[190:193], v[52:55]
	v_mfma_f32_16x16x32_f16 v[48:51], v[182:185], v[190:193], v[48:51]
	v_mfma_f32_16x16x32_f16 v[36:39], v[164:167], v[198:201], v[36:39]
	v_mfma_f32_16x16x32_f16 v[32:35], v[182:185], v[198:201], v[32:35]
	v_mfma_f32_16x16x32_f16 v[20:23], v[164:167], v[210:213], v[20:23]
	v_mfma_f32_16x16x32_f16 v[16:19], v[182:185], v[210:213], v[16:19]
	v_mfma_f32_16x16x32_f16 v[4:7], v[164:167], v[218:221], v[4:7]
	v_mfma_f32_16x16x32_f16 v[0:3], v[182:185], v[218:221], v[0:3]
	s_setprio 1
	s_barrier
	s_add_i32 s70, 0, 0x18000
	s_add_i32 s71, 0, 0x1c000
	v_add_u32_e32 v116, s70, v169
	v_add_u32_e32 v177, s71, v169
	ds_read_b128 v[104:107], v116
	ds_read_b128 v[108:111], v116 offset:1024
	ds_read_b128 v[112:115], v116 offset:2048
	ds_read_b128 v[116:119], v116 offset:3072
	ds_read_b128 v[160:163], v177
	ds_read_b128 v[164:167], v177 offset:1024
	ds_read_b128 v[178:181], v177 offset:2048
	ds_read_b128 v[182:185], v177 offset:3072
	s_add_u32 s34, s34, 0x40000
	s_addc_u32 s35, s35, 0
	s_mov_b32 m0, s46
	v_lshl_add_u64 v[228:229], s[34:35], 0, v[144:145]
	ds_read_b128 v[186:189], v173 offset:32768
	ds_read_b128 v[190:193], v173 offset:33792
	ds_read_b128 v[194:197], v173 offset:34816
	ds_read_b128 v[198:201], v173 offset:35840
	ds_read_b128 v[206:209], v173 offset:36864
	ds_read_b128 v[210:213], v173 offset:37888
	ds_read_b128 v[214:217], v173 offset:38912
	ds_read_b128 v[218:221], v173 offset:39936
	global_load_lds_dwordx4 v[228:229], off
	v_lshl_add_u64 v[228:229], s[34:35], 0, v[148:149]
	s_mov_b32 m0, s47
	s_nop 0
	global_load_lds_dwordx4 v[228:229], off
	s_waitcnt vmcnt(8)
	s_waitcnt lgkmcnt(0)
	s_barrier
	s_setprio 0
	s_waitcnt lgkmcnt(0)
	v_mfma_f32_16x16x32_f16 v[140:143], v[104:107], v[186:189], v[140:143]
	v_mfma_f32_16x16x32_f16 v[136:139], v[112:115], v[186:189], v[136:139]
	v_mfma_f32_16x16x32_f16 v[124:127], v[104:107], v[194:197], v[124:127]
	v_mfma_f32_16x16x32_f16 v[120:123], v[112:115], v[194:197], v[120:123]
	v_mfma_f32_16x16x32_f16 v[92:95], v[104:107], v[206:209], v[92:95]
	v_mfma_f32_16x16x32_f16 v[88:91], v[112:115], v[206:209], v[88:91]
	v_mfma_f32_16x16x32_f16 v[76:79], v[104:107], v[214:217], v[76:79]
	v_mfma_f32_16x16x32_f16 v[72:75], v[112:115], v[214:217], v[72:75]
	v_mfma_f32_16x16x32_f16 v[140:143], v[108:111], v[190:193], v[140:143]
	v_mfma_f32_16x16x32_f16 v[136:139], v[116:119], v[190:193], v[136:139]
	v_mfma_f32_16x16x32_f16 v[124:127], v[108:111], v[198:201], v[124:127]
	v_mfma_f32_16x16x32_f16 v[120:123], v[116:119], v[198:201], v[120:123]
	v_mfma_f32_16x16x32_f16 v[92:95], v[108:111], v[210:213], v[92:95]
	v_mfma_f32_16x16x32_f16 v[88:91], v[116:119], v[210:213], v[88:91]
	v_mfma_f32_16x16x32_f16 v[76:79], v[108:111], v[218:221], v[76:79]
	v_mfma_f32_16x16x32_f16 v[72:75], v[116:119], v[218:221], v[72:75]
	s_setprio 1
	s_setprio 0
	v_mfma_f32_16x16x32_f16 v[132:135], v[160:163], v[186:189], v[132:135]
	v_mfma_f32_16x16x32_f16 v[128:131], v[178:181], v[186:189], v[128:131]
	v_mfma_f32_16x16x32_f16 v[100:103], v[160:163], v[194:197], v[100:103]
	v_mfma_f32_16x16x32_f16 v[96:99], v[178:181], v[194:197], v[96:99]
	v_mfma_f32_16x16x32_f16 v[84:87], v[160:163], v[206:209], v[84:87]
	v_mfma_f32_16x16x32_f16 v[80:83], v[178:181], v[206:209], v[80:83]
	v_mfma_f32_16x16x32_f16 v[68:71], v[160:163], v[214:217], v[68:71]
	v_mfma_f32_16x16x32_f16 v[64:67], v[178:181], v[214:217], v[64:67]
	v_mfma_f32_16x16x32_f16 v[132:135], v[164:167], v[190:193], v[132:135]
	v_mfma_f32_16x16x32_f16 v[128:131], v[182:185], v[190:193], v[128:131]
	v_mfma_f32_16x16x32_f16 v[100:103], v[164:167], v[198:201], v[100:103]
	v_mfma_f32_16x16x32_f16 v[96:99], v[182:185], v[198:201], v[96:99]
	v_mfma_f32_16x16x32_f16 v[84:87], v[164:167], v[210:213], v[84:87]
	v_mfma_f32_16x16x32_f16 v[80:83], v[182:185], v[210:213], v[80:83]
	v_mfma_f32_16x16x32_f16 v[68:71], v[164:167], v[218:221], v[68:71]
	v_mfma_f32_16x16x32_f16 v[64:67], v[182:185], v[218:221], v[64:67]
	s_setprio 1
	s_barrier
	s_add_i32 s34, s70, s44
	v_lshl_add_u64 v[202:203], v[202:203], 0, s[10:11]
	s_mov_b32 m0, s34
	ds_read_b128 v[186:189], v173 offset:49152
	ds_read_b128 v[190:193], v173 offset:50176
	ds_read_b128 v[194:197], v173 offset:51200
	ds_read_b128 v[198:201], v173 offset:52224
	ds_read_b128 v[206:209], v173 offset:53248
	ds_read_b128 v[210:213], v173 offset:54272
	ds_read_b128 v[214:217], v173 offset:55296
	ds_read_b128 v[218:221], v173 offset:56320
	global_load_lds_dwordx4 v[202:203], off
	s_add_i32 m0, s34, 0x2000
	s_add_u32 s26, s26, 0x40080
	v_lshl_add_u64 v[202:203], v[222:223], 0, s[10:11]
	s_addc_u32 s27, s27, 0
	s_add_i32 s34, s71, s44
	global_load_lds_dwordx4 v[202:203], off
	v_lshl_add_u64 v[202:203], s[26:27], 0, v[146:147]
	s_mov_b32 m0, s34
	s_nop 0
	global_load_lds_dwordx4 v[202:203], off
	v_lshl_add_u64 v[202:203], s[26:27], 0, v[150:151]
	s_add_i32 m0, s34, 0x2000
	s_nop 0
	global_load_lds_dwordx4 v[202:203], off
	v_lshl_add_u64 v[202:203], v[224:225], 0, s[10:11]
	s_mov_b32 m0, s57
	s_nop 0
	global_load_lds_dwordx4 v[202:203], off
	v_lshl_add_u64 v[202:203], v[226:227], 0, s[10:11]
	s_mov_b32 m0, s58
	s_nop 0
	global_load_lds_dwordx4 v[202:203], off
	s_waitcnt vmcnt(8)
	s_waitcnt lgkmcnt(0)
	s_barrier
	s_setprio 0
	s_waitcnt lgkmcnt(0)
	v_mfma_f32_16x16x32_f16 v[60:63], v[104:107], v[186:189], v[60:63]
	v_mfma_f32_16x16x32_f16 v[56:59], v[112:115], v[186:189], v[56:59]
	v_mfma_f32_16x16x32_f16 v[44:47], v[104:107], v[194:197], v[44:47]
	v_mfma_f32_16x16x32_f16 v[40:43], v[112:115], v[194:197], v[40:43]
	v_mfma_f32_16x16x32_f16 v[28:31], v[104:107], v[206:209], v[28:31]
	v_mfma_f32_16x16x32_f16 v[24:27], v[112:115], v[206:209], v[24:27]
	v_mfma_f32_16x16x32_f16 v[12:15], v[104:107], v[214:217], v[12:15]
	v_mfma_f32_16x16x32_f16 v[8:11], v[112:115], v[214:217], v[8:11]
	v_mfma_f32_16x16x32_f16 v[60:63], v[108:111], v[190:193], v[60:63]
	v_mfma_f32_16x16x32_f16 v[56:59], v[116:119], v[190:193], v[56:59]
	v_mfma_f32_16x16x32_f16 v[44:47], v[108:111], v[198:201], v[44:47]
	v_mfma_f32_16x16x32_f16 v[40:43], v[116:119], v[198:201], v[40:43]
	v_mfma_f32_16x16x32_f16 v[28:31], v[108:111], v[210:213], v[28:31]
	v_mfma_f32_16x16x32_f16 v[24:27], v[116:119], v[210:213], v[24:27]
	v_mfma_f32_16x16x32_f16 v[12:15], v[108:111], v[218:221], v[12:15]
	v_mfma_f32_16x16x32_f16 v[8:11], v[116:119], v[218:221], v[8:11]
	s_setprio 1
	s_setprio 0
	v_mfma_f32_16x16x32_f16 v[52:55], v[160:163], v[186:189], v[52:55]
	v_mfma_f32_16x16x32_f16 v[48:51], v[178:181], v[186:189], v[48:51]
	v_mfma_f32_16x16x32_f16 v[36:39], v[160:163], v[194:197], v[36:39]
	v_mfma_f32_16x16x32_f16 v[32:35], v[178:181], v[194:197], v[32:35]
	v_mfma_f32_16x16x32_f16 v[20:23], v[160:163], v[206:209], v[20:23]
	v_mfma_f32_16x16x32_f16 v[16:19], v[178:181], v[206:209], v[16:19]
	v_mfma_f32_16x16x32_f16 v[4:7], v[160:163], v[214:217], v[4:7]
	v_mfma_f32_16x16x32_f16 v[0:3], v[178:181], v[214:217], v[0:3]
	v_mfma_f32_16x16x32_f16 v[52:55], v[164:167], v[190:193], v[52:55]
	v_mfma_f32_16x16x32_f16 v[48:51], v[182:185], v[190:193], v[48:51]
	v_mfma_f32_16x16x32_f16 v[36:39], v[164:167], v[198:201], v[36:39]
	v_mfma_f32_16x16x32_f16 v[32:35], v[182:185], v[198:201], v[32:35]
	v_mfma_f32_16x16x32_f16 v[20:23], v[164:167], v[210:213], v[20:23]
	v_mfma_f32_16x16x32_f16 v[16:19], v[182:185], v[210:213], v[16:19]
	v_mfma_f32_16x16x32_f16 v[4:7], v[164:167], v[218:221], v[4:7]
	v_mfma_f32_16x16x32_f16 v[0:3], v[182:185], v[218:221], v[0:3]
	s_setprio 1
	s_barrier
	s_add_i32 s69, s69, 2
	s_add_u32 s24, s24, 0x100
	s_addc_u32 s25, s25, 0
	s_add_u32 s67, s67, 0x100
	s_addc_u32 s68, s68, 0
	s_cmp_gt_u32 s69, 13
	s_cbranch_scc0 .LBB0_220
	s_and_b64 vcc, exec, s[12:13]
	s_cbranch_vccz .LBB0_223
	s_barrier

.LBB0_341:
	ds_read_b128 v[80:83], v208
	ds_read_b128 v[84:87], v208 offset:1024
	ds_read_b128 v[92:95], v208 offset:2048
	ds_read_b128 v[96:99], v208 offset:3072
	ds_read_b128 v[144:147], v209
	ds_read_b128 v[148:151], v209 offset:1024
	ds_read_b128 v[152:155], v209 offset:2048
	ds_read_b128 v[156:159], v209 offset:3072
	s_add_u32 s24, s22, 0x100
	s_addc_u32 s25, s23, 0
	s_cmp_eq_u32 s67, 40
	s_cselect_b32 s35, s1, s25
	s_cselect_b32 s34, s0, s24
	s_cselect_b32 s27, s21, s66
	s_cselect_b32 s26, s20, s65
	v_lshl_add_u64 v[202:203], s[22:23], 0, v[168:169]
	s_add_i32 m0, s40, 0xc000
	ds_read_b128 v[178:181], v210
	ds_read_b128 v[182:185], v210 offset:1024
	ds_read_b128 v[186:189], v210 offset:2048
	ds_read_b128 v[190:193], v210 offset:3072
	ds_read_b128 v[194:197], v210 offset:4096
	ds_read_b128 v[198:201], v210 offset:5120
	ds_read_b128 v[212:215], v210 offset:6144
	ds_read_b128 v[216:219], v210 offset:7168
	global_load_lds_dwordx4 v[202:203], off
	v_lshl_add_u64 v[202:203], s[22:23], 0, v[170:171]
	s_add_i32 m0, s40, 0xe000
	s_nop 0
	global_load_lds_dwordx4 v[202:203], off
	s_waitcnt vmcnt(8)
	s_waitcnt lgkmcnt(0)
	s_barrier
	s_setprio 0
	s_waitcnt lgkmcnt(0)
	v_mfma_f32_16x16x32_f16 v[140:143], v[80:83], v[178:181], v[140:143]
	v_mfma_f32_16x16x32_f16 v[136:139], v[92:95], v[178:181], v[136:139]
	v_mfma_f32_16x16x32_f16 v[124:127], v[80:83], v[186:189], v[124:127]
	v_mfma_f32_16x16x32_f16 v[120:123], v[92:95], v[186:189], v[120:123]
	v_mfma_f32_16x16x32_f16 v[108:111], v[80:83], v[194:197], v[108:111]
	v_mfma_f32_16x16x32_f16 v[104:107], v[92:95], v[194:197], v[104:107]
	v_mfma_f32_16x16x32_f16 v[76:79], v[80:83], v[212:215], v[76:79]
	v_mfma_f32_16x16x32_f16 v[72:75], v[92:95], v[212:215], v[72:75]
	v_mfma_f32_16x16x32_f16 v[140:143], v[84:87], v[182:185], v[140:143]
	v_mfma_f32_16x16x32_f16 v[136:139], v[96:99], v[182:185], v[136:139]
	v_mfma_f32_16x16x32_f16 v[124:127], v[84:87], v[190:193], v[124:127]
	v_mfma_f32_16x16x32_f16 v[120:123], v[96:99], v[190:193], v[120:123]
	v_mfma_f32_16x16x32_f16 v[108:111], v[84:87], v[198:201], v[108:111]
	v_mfma_f32_16x16x32_f16 v[104:107], v[96:99], v[198:201], v[104:107]
	v_mfma_f32_16x16x32_f16 v[76:79], v[84:87], v[216:219], v[76:79]
	v_mfma_f32_16x16x32_f16 v[72:75], v[96:99], v[216:219], v[72:75]
	s_setprio 1
	s_setprio 0
	v_mfma_f32_16x16x32_f16 v[132:135], v[144:147], v[178:181], v[132:135]
	v_mfma_f32_16x16x32_f16 v[128:131], v[152:155], v[178:181], v[128:131]
	v_mfma_f32_16x16x32_f16 v[116:119], v[144:147], v[186:189], v[116:119]
	v_mfma_f32_16x16x32_f16 v[112:115], v[152:155], v[186:189], v[112:115]
	v_mfma_f32_16x16x32_f16 v[100:103], v[144:147], v[194:197], v[100:103]
	v_mfma_f32_16x16x32_f16 v[88:91], v[152:155], v[194:197], v[88:91]
	v_mfma_f32_16x16x32_f16 v[68:71], v[144:147], v[212:215], v[68:71]
	v_mfma_f32_16x16x32_f16 v[64:67], v[152:155], v[212:215], v[64:67]
	v_mfma_f32_16x16x32_f16 v[132:135], v[148:151], v[182:185], v[132:135]
	v_mfma_f32_16x16x32_f16 v[128:131], v[156:159], v[182:185], v[128:131]
	v_mfma_f32_16x16x32_f16 v[116:119], v[148:151], v[190:193], v[116:119]
	v_mfma_f32_16x16x32_f16 v[112:115], v[156:159], v[190:193], v[112:115]
	v_mfma_f32_16x16x32_f16 v[100:103], v[148:151], v[198:201], v[100:103]
	v_mfma_f32_16x16x32_f16 v[88:91], v[156:159], v[198:201], v[88:91]
	v_mfma_f32_16x16x32_f16 v[68:71], v[148:151], v[216:219], v[68:71]
	v_mfma_f32_16x16x32_f16 v[64:67], v[156:159], v[216:219], v[64:67]
	s_setprio 1
	s_barrier
	s_add_i32 s22, s59, s33
	v_lshl_add_u64 v[202:203], s[26:27], 0, v[162:163]
	s_mov_b32 m0, s22
	ds_read_b128 v[178:181], v210 offset:16384
	ds_read_b128 v[182:185], v210 offset:17408
	ds_read_b128 v[186:189], v210 offset:18432
	ds_read_b128 v[190:193], v210 offset:19456
	ds_read_b128 v[194:197], v210 offset:20480
	ds_read_b128 v[198:201], v210 offset:21504
	ds_read_b128 v[212:215], v210 offset:22528
	ds_read_b128 v[216:219], v210 offset:23552
	global_load_lds_dwordx4 v[202:203], off
	s_add_i32 m0, s22, 0x2000
	s_add_u32 s22, s26, 0xb0000
	v_lshl_add_u64 v[220:221], s[26:27], 0, v[166:167]
	s_addc_u32 s23, s27, 0
	s_add_i32 s68, s60, s33
	global_load_lds_dwordx4 v[220:221], off
	v_lshl_add_u64 v[222:223], s[22:23], 0, v[162:163]
	s_mov_b32 m0, s68
	v_lshl_add_u64 v[224:225], s[34:35], 0, v[164:165]
	global_load_lds_dwordx4 v[222:223], off
	v_lshl_add_u64 v[222:223], s[22:23], 0, v[166:167]
	s_add_i32 m0, s68, 0x2000
	s_nop 0
	global_load_lds_dwordx4 v[222:223], off
	v_lshl_add_u64 v[222:223], s[34:35], 0, v[160:161]
	s_mov_b32 m0, s40
	s_nop 0
	global_load_lds_dwordx4 v[222:223], off
	s_mov_b32 m0, s41
	s_nop 0
	global_load_lds_dwordx4 v[224:225], off
	s_waitcnt vmcnt(8)
	s_waitcnt lgkmcnt(0)
	s_barrier
	s_setprio 0
	s_waitcnt lgkmcnt(0)
	v_mfma_f32_16x16x32_f16 v[60:63], v[80:83], v[178:181], v[60:63]
	v_mfma_f32_16x16x32_f16 v[56:59], v[92:95], v[178:181], v[56:59]
	v_mfma_f32_16x16x32_f16 v[44:47], v[80:83], v[186:189], v[44:47]
	v_mfma_f32_16x16x32_f16 v[40:43], v[92:95], v[186:189], v[40:43]
	v_mfma_f32_16x16x32_f16 v[28:31], v[80:83], v[194:197], v[28:31]
	v_mfma_f32_16x16x32_f16 v[24:27], v[92:95], v[194:197], v[24:27]
	v_mfma_f32_16x16x32_f16 v[12:15], v[80:83], v[212:215], v[12:15]
	v_mfma_f32_16x16x32_f16 v[8:11], v[92:95], v[212:215], v[8:11]
	v_mfma_f32_16x16x32_f16 v[60:63], v[84:87], v[182:185], v[60:63]
	v_mfma_f32_16x16x32_f16 v[56:59], v[96:99], v[182:185], v[56:59]
	v_mfma_f32_16x16x32_f16 v[44:47], v[84:87], v[190:193], v[44:47]
	v_mfma_f32_16x16x32_f16 v[40:43], v[96:99], v[190:193], v[40:43]
	v_mfma_f32_16x16x32_f16 v[28:31], v[84:87], v[198:201], v[28:31]
	v_mfma_f32_16x16x32_f16 v[24:27], v[96:99], v[198:201], v[24:27]
	v_mfma_f32_16x16x32_f16 v[12:15], v[84:87], v[216:219], v[12:15]
	v_mfma_f32_16x16x32_f16 v[8:11], v[96:99], v[216:219], v[8:11]
	s_setprio 1
	s_setprio 0
	v_mfma_f32_16x16x32_f16 v[52:55], v[144:147], v[178:181], v[52:55]
	v_mfma_f32_16x16x32_f16 v[48:51], v[152:155], v[178:181], v[48:51]
	v_mfma_f32_16x16x32_f16 v[36:39], v[144:147], v[186:189], v[36:39]
	v_mfma_f32_16x16x32_f16 v[32:35], v[152:155], v[186:189], v[32:35]
	v_mfma_f32_16x16x32_f16 v[20:23], v[144:147], v[194:197], v[20:23]
	v_mfma_f32_16x16x32_f16 v[16:19], v[152:155], v[194:197], v[16:19]
	v_mfma_f32_16x16x32_f16 v[4:7], v[144:147], v[212:215], v[4:7]
	v_mfma_f32_16x16x32_f16 v[0:3], v[152:155], v[212:215], v[0:3]
	v_mfma_f32_16x16x32_f16 v[52:55], v[148:151], v[182:185], v[52:55]
	v_mfma_f32_16x16x32_f16 v[48:51], v[156:159], v[182:185], v[48:51]
	v_mfma_f32_16x16x32_f16 v[36:39], v[148:151], v[190:193], v[36:39]
	v_mfma_f32_16x16x32_f16 v[32:35], v[156:159], v[190:193], v[32:35]
	v_mfma_f32_16x16x32_f16 v[20:23], v[148:151], v[198:201], v[20:23]
	v_mfma_f32_16x16x32_f16 v[16:19], v[156:159], v[198:201], v[16:19]
	v_mfma_f32_16x16x32_f16 v[4:7], v[148:151], v[216:219], v[4:7]
	v_mfma_f32_16x16x32_f16 v[0:3], v[156:159], v[216:219], v[0:3]
	s_setprio 1
	s_barrier
	s_add_i32 s68, 0, 0x18000
	s_add_i32 s69, 0, 0x1c000
	v_add_u32_e32 v96, s68, v206
	v_add_u32_e32 v156, s69, v206
	ds_read_b128 v[80:83], v96
	ds_read_b128 v[84:87], v96 offset:1024
	ds_read_b128 v[92:95], v96 offset:2048
	ds_read_b128 v[96:99], v96 offset:3072
	ds_read_b128 v[144:147], v156
	ds_read_b128 v[148:151], v156 offset:1024
	ds_read_b128 v[152:155], v156 offset:2048
	ds_read_b128 v[156:159], v156 offset:3072
	s_add_u32 s22, s34, 0xb0000
	s_addc_u32 s23, s35, 0
	s_mov_b32 m0, s44
	v_lshl_add_u64 v[226:227], s[22:23], 0, v[160:161]
	ds_read_b128 v[178:181], v210 offset:32768
	ds_read_b128 v[182:185], v210 offset:33792
	ds_read_b128 v[186:189], v210 offset:34816
	ds_read_b128 v[190:193], v210 offset:35840
	ds_read_b128 v[194:197], v210 offset:36864
	ds_read_b128 v[198:201], v210 offset:37888
	ds_read_b128 v[212:215], v210 offset:38912
	ds_read_b128 v[216:219], v210 offset:39936
	global_load_lds_dwordx4 v[226:227], off
	v_lshl_add_u64 v[226:227], s[22:23], 0, v[164:165]
	s_mov_b32 m0, s45
	s_nop 0
	global_load_lds_dwordx4 v[226:227], off
	s_waitcnt vmcnt(8)
	s_waitcnt lgkmcnt(0)
	s_barrier
	s_setprio 0
	s_waitcnt lgkmcnt(0)
	v_mfma_f32_16x16x32_f16 v[140:143], v[80:83], v[178:181], v[140:143]
	v_mfma_f32_16x16x32_f16 v[136:139], v[92:95], v[178:181], v[136:139]
	v_mfma_f32_16x16x32_f16 v[124:127], v[80:83], v[186:189], v[124:127]
	v_mfma_f32_16x16x32_f16 v[120:123], v[92:95], v[186:189], v[120:123]
	v_mfma_f32_16x16x32_f16 v[108:111], v[80:83], v[194:197], v[108:111]
	v_mfma_f32_16x16x32_f16 v[104:107], v[92:95], v[194:197], v[104:107]
	v_mfma_f32_16x16x32_f16 v[76:79], v[80:83], v[212:215], v[76:79]
	v_mfma_f32_16x16x32_f16 v[72:75], v[92:95], v[212:215], v[72:75]
	v_mfma_f32_16x16x32_f16 v[140:143], v[84:87], v[182:185], v[140:143]
	v_mfma_f32_16x16x32_f16 v[136:139], v[96:99], v[182:185], v[136:139]
	v_mfma_f32_16x16x32_f16 v[124:127], v[84:87], v[190:193], v[124:127]
	v_mfma_f32_16x16x32_f16 v[120:123], v[96:99], v[190:193], v[120:123]
	v_mfma_f32_16x16x32_f16 v[108:111], v[84:87], v[198:201], v[108:111]
	v_mfma_f32_16x16x32_f16 v[104:107], v[96:99], v[198:201], v[104:107]
	v_mfma_f32_16x16x32_f16 v[76:79], v[84:87], v[216:219], v[76:79]
	v_mfma_f32_16x16x32_f16 v[72:75], v[96:99], v[216:219], v[72:75]
	s_setprio 1
	s_setprio 0
	v_mfma_f32_16x16x32_f16 v[132:135], v[144:147], v[178:181], v[132:135]
	v_mfma_f32_16x16x32_f16 v[128:131], v[152:155], v[178:181], v[128:131]
	v_mfma_f32_16x16x32_f16 v[116:119], v[144:147], v[186:189], v[116:119]
	v_mfma_f32_16x16x32_f16 v[112:115], v[152:155], v[186:189], v[112:115]
	v_mfma_f32_16x16x32_f16 v[100:103], v[144:147], v[194:197], v[100:103]
	v_mfma_f32_16x16x32_f16 v[88:91], v[152:155], v[194:197], v[88:91]
	v_mfma_f32_16x16x32_f16 v[68:71], v[144:147], v[212:215], v[68:71]
	v_mfma_f32_16x16x32_f16 v[64:67], v[152:155], v[212:215], v[64:67]
	v_mfma_f32_16x16x32_f16 v[132:135], v[148:151], v[182:185], v[132:135]
	v_mfma_f32_16x16x32_f16 v[128:131], v[156:159], v[182:185], v[128:131]
	v_mfma_f32_16x16x32_f16 v[116:119], v[148:151], v[190:193], v[116:119]
	v_mfma_f32_16x16x32_f16 v[112:115], v[156:159], v[190:193], v[112:115]
	v_mfma_f32_16x16x32_f16 v[100:103], v[148:151], v[198:201], v[100:103]
	v_mfma_f32_16x16x32_f16 v[88:91], v[156:159], v[198:201], v[88:91]
	v_mfma_f32_16x16x32_f16 v[68:71], v[148:151], v[216:219], v[68:71]
	v_mfma_f32_16x16x32_f16 v[64:67], v[156:159], v[216:219], v[64:67]
	s_setprio 1
	s_barrier
	s_add_i32 s22, s68, s33
	v_lshl_add_u64 v[202:203], v[202:203], 0, s[16:17]
	s_mov_b32 m0, s22
	ds_read_b128 v[178:181], v210 offset:49152
	ds_read_b128 v[182:185], v210 offset:50176
	ds_read_b128 v[186:189], v210 offset:51200
	ds_read_b128 v[190:193], v210 offset:52224
	ds_read_b128 v[194:197], v210 offset:53248
	ds_read_b128 v[198:201], v210 offset:54272
	ds_read_b128 v[212:215], v210 offset:55296
	ds_read_b128 v[216:219], v210 offset:56320
	global_load_lds_dwordx4 v[202:203], off
	s_add_i32 m0, s22, 0x2000
	s_add_u32 s22, s26, 0xb0080
	v_lshl_add_u64 v[202:203], v[220:221], 0, s[16:17]
	s_addc_u32 s23, s27, 0
	s_add_i32 s26, s69, s33
	global_load_lds_dwordx4 v[202:203], off
	v_lshl_add_u64 v[202:203], s[22:23], 0, v[162:163]
	s_mov_b32 m0, s26
	s_nop 0
	global_load_lds_dwordx4 v[202:203], off
	v_lshl_add_u64 v[202:203], s[22:23], 0, v[166:167]
	s_add_i32 m0, s26, 0x2000
	s_nop 0
	global_load_lds_dwordx4 v[202:203], off
	v_lshl_add_u64 v[202:203], v[222:223], 0, s[16:17]
	s_mov_b32 m0, s55
	s_nop 0
	global_load_lds_dwordx4 v[202:203], off
	v_lshl_add_u64 v[202:203], v[224:225], 0, s[16:17]
	s_mov_b32 m0, s56
	s_nop 0
	global_load_lds_dwordx4 v[202:203], off
	s_waitcnt vmcnt(8)
	s_waitcnt lgkmcnt(0)
	s_barrier
	s_setprio 0
	s_waitcnt lgkmcnt(0)
	v_mfma_f32_16x16x32_f16 v[60:63], v[80:83], v[178:181], v[60:63]
	v_mfma_f32_16x16x32_f16 v[56:59], v[92:95], v[178:181], v[56:59]
	v_mfma_f32_16x16x32_f16 v[44:47], v[80:83], v[186:189], v[44:47]
	v_mfma_f32_16x16x32_f16 v[40:43], v[92:95], v[186:189], v[40:43]
	v_mfma_f32_16x16x32_f16 v[28:31], v[80:83], v[194:197], v[28:31]
	v_mfma_f32_16x16x32_f16 v[24:27], v[92:95], v[194:197], v[24:27]
	v_mfma_f32_16x16x32_f16 v[12:15], v[80:83], v[212:215], v[12:15]
	v_mfma_f32_16x16x32_f16 v[8:11], v[92:95], v[212:215], v[8:11]
	v_mfma_f32_16x16x32_f16 v[60:63], v[84:87], v[182:185], v[60:63]
	v_mfma_f32_16x16x32_f16 v[56:59], v[96:99], v[182:185], v[56:59]
	v_mfma_f32_16x16x32_f16 v[44:47], v[84:87], v[190:193], v[44:47]
	v_mfma_f32_16x16x32_f16 v[40:43], v[96:99], v[190:193], v[40:43]
	v_mfma_f32_16x16x32_f16 v[28:31], v[84:87], v[198:201], v[28:31]
	v_mfma_f32_16x16x32_f16 v[24:27], v[96:99], v[198:201], v[24:27]
	v_mfma_f32_16x16x32_f16 v[12:15], v[84:87], v[216:219], v[12:15]
	v_mfma_f32_16x16x32_f16 v[8:11], v[96:99], v[216:219], v[8:11]
	s_setprio 1
	s_setprio 0
	v_mfma_f32_16x16x32_f16 v[52:55], v[144:147], v[178:181], v[52:55]
	v_mfma_f32_16x16x32_f16 v[48:51], v[152:155], v[178:181], v[48:51]
	v_mfma_f32_16x16x32_f16 v[36:39], v[144:147], v[186:189], v[36:39]
	v_mfma_f32_16x16x32_f16 v[32:35], v[152:155], v[186:189], v[32:35]
	v_mfma_f32_16x16x32_f16 v[20:23], v[144:147], v[194:197], v[20:23]
	v_mfma_f32_16x16x32_f16 v[16:19], v[152:155], v[194:197], v[16:19]
	v_mfma_f32_16x16x32_f16 v[4:7], v[144:147], v[212:215], v[4:7]
	v_mfma_f32_16x16x32_f16 v[0:3], v[152:155], v[212:215], v[0:3]
	v_mfma_f32_16x16x32_f16 v[52:55], v[148:151], v[182:185], v[52:55]
	v_mfma_f32_16x16x32_f16 v[48:51], v[156:159], v[182:185], v[48:51]
	v_mfma_f32_16x16x32_f16 v[36:39], v[148:151], v[190:193], v[36:39]
	v_mfma_f32_16x16x32_f16 v[32:35], v[156:159], v[190:193], v[32:35]
	v_mfma_f32_16x16x32_f16 v[20:23], v[148:151], v[198:201], v[20:23]
	v_mfma_f32_16x16x32_f16 v[16:19], v[156:159], v[198:201], v[16:19]
	v_mfma_f32_16x16x32_f16 v[4:7], v[148:151], v[216:219], v[4:7]
	v_mfma_f32_16x16x32_f16 v[0:3], v[156:159], v[216:219], v[0:3]
	s_setprio 1
	s_barrier
	s_add_i32 s67, s67, 2
	s_add_u32 s65, s65, 0x100
	s_addc_u32 s66, s66, 0
	s_cmp_gt_u32 s67, 41
	s_mov_b64 s[22:23], s[24:25]
	s_cbranch_scc0 .LBB0_341
	s_and_b64 vcc, exec, s[18:19]
	s_cbranch_vccz .LBB0_344
	s_barrier

.LBB0_464:
	ds_read_b128 v[128:131], v167
	ds_read_b128 v[132:135], v167 offset:1024
	ds_read_b128 v[136:139], v167 offset:2048
	ds_read_b128 v[140:143], v167 offset:3072
	ds_read_b128 v[160:163], v168
	ds_read_b128 v[172:175], v168 offset:1024
	ds_read_b128 v[178:181], v168 offset:2048
	ds_read_b128 v[182:185], v168 offset:3072
	s_add_u32 s44, s40, 0xfffc0080
	s_addc_u32 s45, s41, -1
	s_cmp_eq_u32 s73, 12
	s_cselect_b32 s47, s23, s45
	s_cselect_b32 s46, s69, s44
	s_cselect_b32 s45, s21, s72
	s_cselect_b32 s44, s70, s71
	v_lshl_add_u64 v[202:203], s[40:41], 0, v[152:153]
	s_add_i32 m0, s35, 0xc000
	ds_read_b128 v[186:189], v169
	ds_read_b128 v[190:193], v169 offset:1024
	ds_read_b128 v[194:197], v169 offset:2048
	ds_read_b128 v[198:201], v169 offset:3072
	ds_read_b128 v[206:209], v169 offset:4096
	ds_read_b128 v[210:213], v169 offset:5120
	ds_read_b128 v[214:217], v169 offset:6144
	ds_read_b128 v[218:221], v169 offset:7168
	global_load_lds_dwordx4 v[202:203], off
	v_lshl_add_u64 v[202:203], s[40:41], 0, v[154:155]
	s_add_i32 m0, s35, 0xe000
	s_nop 0
	global_load_lds_dwordx4 v[202:203], off
	s_waitcnt vmcnt(8)
	s_waitcnt lgkmcnt(0)
	s_barrier
	s_setprio 0
	s_waitcnt lgkmcnt(0)
	v_mfma_f32_16x16x32_f16 v[124:127], v[128:131], v[186:189], v[124:127]
	v_mfma_f32_16x16x32_f16 v[120:123], v[136:139], v[186:189], v[120:123]
	v_mfma_f32_16x16x32_f16 v[108:111], v[128:131], v[194:197], v[108:111]
	v_mfma_f32_16x16x32_f16 v[104:107], v[136:139], v[194:197], v[104:107]
	v_mfma_f32_16x16x32_f16 v[92:95], v[128:131], v[206:209], v[92:95]
	v_mfma_f32_16x16x32_f16 v[88:91], v[136:139], v[206:209], v[88:91]
	v_mfma_f32_16x16x32_f16 v[84:87], v[128:131], v[214:217], v[84:87]
	v_mfma_f32_16x16x32_f16 v[76:79], v[136:139], v[214:217], v[76:79]
	v_mfma_f32_16x16x32_f16 v[124:127], v[132:135], v[190:193], v[124:127]
	v_mfma_f32_16x16x32_f16 v[120:123], v[140:143], v[190:193], v[120:123]
	v_mfma_f32_16x16x32_f16 v[108:111], v[132:135], v[198:201], v[108:111]
	v_mfma_f32_16x16x32_f16 v[104:107], v[140:143], v[198:201], v[104:107]
	v_mfma_f32_16x16x32_f16 v[92:95], v[132:135], v[210:213], v[92:95]
	v_mfma_f32_16x16x32_f16 v[88:91], v[140:143], v[210:213], v[88:91]
	v_mfma_f32_16x16x32_f16 v[84:87], v[132:135], v[218:221], v[84:87]
	v_mfma_f32_16x16x32_f16 v[76:79], v[140:143], v[218:221], v[76:79]
	s_setprio 1
	s_setprio 0
	v_mfma_f32_16x16x32_f16 v[116:119], v[160:163], v[186:189], v[116:119]
	v_mfma_f32_16x16x32_f16 v[112:115], v[178:181], v[186:189], v[112:115]
	v_mfma_f32_16x16x32_f16 v[100:103], v[160:163], v[194:197], v[100:103]
	v_mfma_f32_16x16x32_f16 v[96:99], v[178:181], v[194:197], v[96:99]
	v_mfma_f32_16x16x32_f16 v[80:83], v[160:163], v[206:209], v[80:83]
	v_mfma_f32_16x16x32_f16 v[72:75], v[178:181], v[206:209], v[72:75]
	v_mfma_f32_16x16x32_f16 v[68:71], v[160:163], v[214:217], v[68:71]
	v_mfma_f32_16x16x32_f16 v[64:67], v[178:181], v[214:217], v[64:67]
	v_mfma_f32_16x16x32_f16 v[116:119], v[172:175], v[190:193], v[116:119]
	v_mfma_f32_16x16x32_f16 v[112:115], v[182:185], v[190:193], v[112:115]
	v_mfma_f32_16x16x32_f16 v[100:103], v[172:175], v[198:201], v[100:103]
	v_mfma_f32_16x16x32_f16 v[96:99], v[182:185], v[198:201], v[96:99]
	v_mfma_f32_16x16x32_f16 v[80:83], v[172:175], v[210:213], v[80:83]
	v_mfma_f32_16x16x32_f16 v[72:75], v[182:185], v[210:213], v[72:75]
	v_mfma_f32_16x16x32_f16 v[68:71], v[172:175], v[218:221], v[68:71]
	v_mfma_f32_16x16x32_f16 v[64:67], v[182:185], v[218:221], v[64:67]
	s_setprio 1
	s_barrier
	s_add_i32 s74, s62, s48
	v_lshl_add_u64 v[202:203], s[44:45], 0, v[146:147]
	s_mov_b32 m0, s74
	ds_read_b128 v[186:189], v169 offset:16384
	ds_read_b128 v[190:193], v169 offset:17408
	ds_read_b128 v[194:197], v169 offset:18432
	ds_read_b128 v[198:201], v169 offset:19456
	ds_read_b128 v[206:209], v169 offset:20480
	ds_read_b128 v[210:213], v169 offset:21504
	ds_read_b128 v[214:217], v169 offset:22528
	ds_read_b128 v[218:221], v169 offset:23552
	global_load_lds_dwordx4 v[202:203], off
	s_add_i32 m0, s74, 0x2000
	s_add_u32 s74, s44, 0x40000
	v_lshl_add_u64 v[222:223], s[44:45], 0, v[150:151]
	s_addc_u32 s75, s45, 0
	s_add_i32 s76, s63, s48
	global_load_lds_dwordx4 v[222:223], off
	v_lshl_add_u64 v[224:225], s[74:75], 0, v[146:147]
	s_mov_b32 m0, s76
	v_lshl_add_u64 v[226:227], s[46:47], 0, v[148:149]
	global_load_lds_dwordx4 v[224:225], off
	v_lshl_add_u64 v[224:225], s[74:75], 0, v[150:151]
	s_add_i32 m0, s76, 0x2000
	s_nop 0
	global_load_lds_dwordx4 v[224:225], off
	v_lshl_add_u64 v[224:225], s[46:47], 0, v[144:145]
	s_mov_b32 m0, s35
	s_nop 0
	global_load_lds_dwordx4 v[224:225], off
	s_mov_b32 m0, s49
	s_nop 0
	global_load_lds_dwordx4 v[226:227], off
	s_waitcnt vmcnt(8)
	s_waitcnt lgkmcnt(0)
	s_barrier
	s_setprio 0
	s_waitcnt lgkmcnt(0)
	v_mfma_f32_16x16x32_f16 v[60:63], v[128:131], v[186:189], v[60:63]
	v_mfma_f32_16x16x32_f16 v[56:59], v[136:139], v[186:189], v[56:59]
	v_mfma_f32_16x16x32_f16 v[44:47], v[128:131], v[194:197], v[44:47]
	v_mfma_f32_16x16x32_f16 v[40:43], v[136:139], v[194:197], v[40:43]
	v_mfma_f32_16x16x32_f16 v[28:31], v[128:131], v[206:209], v[28:31]
	v_mfma_f32_16x16x32_f16 v[24:27], v[136:139], v[206:209], v[24:27]
	v_mfma_f32_16x16x32_f16 v[12:15], v[128:131], v[214:217], v[12:15]
	v_mfma_f32_16x16x32_f16 v[8:11], v[136:139], v[214:217], v[8:11]
	v_mfma_f32_16x16x32_f16 v[60:63], v[132:135], v[190:193], v[60:63]
	v_mfma_f32_16x16x32_f16 v[56:59], v[140:143], v[190:193], v[56:59]
	v_mfma_f32_16x16x32_f16 v[44:47], v[132:135], v[198:201], v[44:47]
	v_mfma_f32_16x16x32_f16 v[40:43], v[140:143], v[198:201], v[40:43]
	v_mfma_f32_16x16x32_f16 v[28:31], v[132:135], v[210:213], v[28:31]
	v_mfma_f32_16x16x32_f16 v[24:27], v[140:143], v[210:213], v[24:27]
	v_mfma_f32_16x16x32_f16 v[12:15], v[132:135], v[218:221], v[12:15]
	v_mfma_f32_16x16x32_f16 v[8:11], v[140:143], v[218:221], v[8:11]
	s_setprio 1
	s_setprio 0
	v_mfma_f32_16x16x32_f16 v[52:55], v[160:163], v[186:189], v[52:55]
	v_mfma_f32_16x16x32_f16 v[48:51], v[178:181], v[186:189], v[48:51]
	v_mfma_f32_16x16x32_f16 v[36:39], v[160:163], v[194:197], v[36:39]
	v_mfma_f32_16x16x32_f16 v[32:35], v[178:181], v[194:197], v[32:35]
	v_mfma_f32_16x16x32_f16 v[20:23], v[160:163], v[206:209], v[20:23]
	v_mfma_f32_16x16x32_f16 v[16:19], v[178:181], v[206:209], v[16:19]
	v_mfma_f32_16x16x32_f16 v[4:7], v[160:163], v[214:217], v[4:7]
	v_mfma_f32_16x16x32_f16 v[0:3], v[178:181], v[214:217], v[0:3]
	v_mfma_f32_16x16x32_f16 v[52:55], v[172:175], v[190:193], v[52:55]
	v_mfma_f32_16x16x32_f16 v[48:51], v[182:185], v[190:193], v[48:51]
	v_mfma_f32_16x16x32_f16 v[36:39], v[172:175], v[198:201], v[36:39]
	v_mfma_f32_16x16x32_f16 v[32:35], v[182:185], v[198:201], v[32:35]
	v_mfma_f32_16x16x32_f16 v[20:23], v[172:175], v[210:213], v[20:23]
	v_mfma_f32_16x16x32_f16 v[16:19], v[182:185], v[210:213], v[16:19]
	v_mfma_f32_16x16x32_f16 v[4:7], v[172:175], v[218:221], v[4:7]
	v_mfma_f32_16x16x32_f16 v[0:3], v[182:185], v[218:221], v[0:3]
	s_setprio 1
	s_barrier
	s_add_i32 s74, 0, 0x18000
	s_add_i32 s75, 0, 0x1c000
	v_add_u32_e32 v140, s74, v165
	v_add_u32_e32 v177, s75, v165
	ds_read_b128 v[128:131], v140
	ds_read_b128 v[132:135], v140 offset:1024
	ds_read_b128 v[136:139], v140 offset:2048
	ds_read_b128 v[140:143], v140 offset:3072
	ds_read_b128 v[160:163], v177
	ds_read_b128 v[172:175], v177 offset:1024
	ds_read_b128 v[178:181], v177 offset:2048
	ds_read_b128 v[182:185], v177 offset:3072
	s_add_u32 s46, s46, 0x40000
	s_addc_u32 s47, s47, 0
	s_mov_b32 m0, s54
	v_lshl_add_u64 v[228:229], s[46:47], 0, v[144:145]
	ds_read_b128 v[186:189], v169 offset:32768
	ds_read_b128 v[190:193], v169 offset:33792
	ds_read_b128 v[194:197], v169 offset:34816
	ds_read_b128 v[198:201], v169 offset:35840
	ds_read_b128 v[206:209], v169 offset:36864
	ds_read_b128 v[210:213], v169 offset:37888
	ds_read_b128 v[214:217], v169 offset:38912
	ds_read_b128 v[218:221], v169 offset:39936
	global_load_lds_dwordx4 v[228:229], off
	v_lshl_add_u64 v[228:229], s[46:47], 0, v[148:149]
	s_mov_b32 m0, s55
	s_nop 0
	global_load_lds_dwordx4 v[228:229], off
	s_waitcnt vmcnt(8)
	s_waitcnt lgkmcnt(0)
	s_barrier
	s_setprio 0
	s_waitcnt lgkmcnt(0)
	v_mfma_f32_16x16x32_f16 v[124:127], v[128:131], v[186:189], v[124:127]
	v_mfma_f32_16x16x32_f16 v[120:123], v[136:139], v[186:189], v[120:123]
	v_mfma_f32_16x16x32_f16 v[108:111], v[128:131], v[194:197], v[108:111]
	v_mfma_f32_16x16x32_f16 v[104:107], v[136:139], v[194:197], v[104:107]
	v_mfma_f32_16x16x32_f16 v[92:95], v[128:131], v[206:209], v[92:95]
	v_mfma_f32_16x16x32_f16 v[88:91], v[136:139], v[206:209], v[88:91]
	v_mfma_f32_16x16x32_f16 v[84:87], v[128:131], v[214:217], v[84:87]
	v_mfma_f32_16x16x32_f16 v[76:79], v[136:139], v[214:217], v[76:79]
	v_mfma_f32_16x16x32_f16 v[124:127], v[132:135], v[190:193], v[124:127]
	v_mfma_f32_16x16x32_f16 v[120:123], v[140:143], v[190:193], v[120:123]
	v_mfma_f32_16x16x32_f16 v[108:111], v[132:135], v[198:201], v[108:111]
	v_mfma_f32_16x16x32_f16 v[104:107], v[140:143], v[198:201], v[104:107]
	v_mfma_f32_16x16x32_f16 v[92:95], v[132:135], v[210:213], v[92:95]
	v_mfma_f32_16x16x32_f16 v[88:91], v[140:143], v[210:213], v[88:91]
	v_mfma_f32_16x16x32_f16 v[84:87], v[132:135], v[218:221], v[84:87]
	v_mfma_f32_16x16x32_f16 v[76:79], v[140:143], v[218:221], v[76:79]
	s_setprio 1
	s_setprio 0
	v_mfma_f32_16x16x32_f16 v[116:119], v[160:163], v[186:189], v[116:119]
	v_mfma_f32_16x16x32_f16 v[112:115], v[178:181], v[186:189], v[112:115]
	v_mfma_f32_16x16x32_f16 v[100:103], v[160:163], v[194:197], v[100:103]
	v_mfma_f32_16x16x32_f16 v[96:99], v[178:181], v[194:197], v[96:99]
	v_mfma_f32_16x16x32_f16 v[80:83], v[160:163], v[206:209], v[80:83]
	v_mfma_f32_16x16x32_f16 v[72:75], v[178:181], v[206:209], v[72:75]
	v_mfma_f32_16x16x32_f16 v[68:71], v[160:163], v[214:217], v[68:71]
	v_mfma_f32_16x16x32_f16 v[64:67], v[178:181], v[214:217], v[64:67]
	v_mfma_f32_16x16x32_f16 v[116:119], v[172:175], v[190:193], v[116:119]
	v_mfma_f32_16x16x32_f16 v[112:115], v[182:185], v[190:193], v[112:115]
	v_mfma_f32_16x16x32_f16 v[100:103], v[172:175], v[198:201], v[100:103]
	v_mfma_f32_16x16x32_f16 v[96:99], v[182:185], v[198:201], v[96:99]
	v_mfma_f32_16x16x32_f16 v[80:83], v[172:175], v[210:213], v[80:83]
	v_mfma_f32_16x16x32_f16 v[72:75], v[182:185], v[210:213], v[72:75]
	v_mfma_f32_16x16x32_f16 v[68:71], v[172:175], v[218:221], v[68:71]
	v_mfma_f32_16x16x32_f16 v[64:67], v[182:185], v[218:221], v[64:67]
	s_setprio 1
	s_barrier
	s_add_i32 s46, s74, s48
	v_lshl_add_u64 v[202:203], v[202:203], 0, s[4:5]
	s_mov_b32 m0, s46
	ds_read_b128 v[186:189], v169 offset:49152
	ds_read_b128 v[190:193], v169 offset:50176
	ds_read_b128 v[194:197], v169 offset:51200
	ds_read_b128 v[198:201], v169 offset:52224
	ds_read_b128 v[206:209], v169 offset:53248
	ds_read_b128 v[210:213], v169 offset:54272
	ds_read_b128 v[214:217], v169 offset:55296
	ds_read_b128 v[218:221], v169 offset:56320
	global_load_lds_dwordx4 v[202:203], off
	s_add_i32 m0, s46, 0x2000
	s_add_u32 s44, s44, 0x40080
	v_lshl_add_u64 v[202:203], v[222:223], 0, s[4:5]
	s_addc_u32 s45, s45, 0
	s_add_i32 s46, s75, s48
	global_load_lds_dwordx4 v[202:203], off
	v_lshl_add_u64 v[202:203], s[44:45], 0, v[146:147]
	s_mov_b32 m0, s46
	s_nop 0
	global_load_lds_dwordx4 v[202:203], off
	v_lshl_add_u64 v[202:203], s[44:45], 0, v[150:151]
	s_add_i32 m0, s46, 0x2000
	s_nop 0
	global_load_lds_dwordx4 v[202:203], off
	v_lshl_add_u64 v[202:203], v[224:225], 0, s[4:5]
	s_mov_b32 m0, s59
	s_nop 0
	global_load_lds_dwordx4 v[202:203], off
	v_lshl_add_u64 v[202:203], v[226:227], 0, s[4:5]
	s_mov_b32 m0, s60
	s_nop 0
	global_load_lds_dwordx4 v[202:203], off
	s_waitcnt vmcnt(8)
	s_waitcnt lgkmcnt(0)
	s_barrier
	s_setprio 0
	s_waitcnt lgkmcnt(0)
	v_mfma_f32_16x16x32_f16 v[60:63], v[128:131], v[186:189], v[60:63]
	v_mfma_f32_16x16x32_f16 v[56:59], v[136:139], v[186:189], v[56:59]
	v_mfma_f32_16x16x32_f16 v[44:47], v[128:131], v[194:197], v[44:47]
	v_mfma_f32_16x16x32_f16 v[40:43], v[136:139], v[194:197], v[40:43]
	v_mfma_f32_16x16x32_f16 v[28:31], v[128:131], v[206:209], v[28:31]
	v_mfma_f32_16x16x32_f16 v[24:27], v[136:139], v[206:209], v[24:27]
	v_mfma_f32_16x16x32_f16 v[12:15], v[128:131], v[214:217], v[12:15]
	v_mfma_f32_16x16x32_f16 v[8:11], v[136:139], v[214:217], v[8:11]
	v_mfma_f32_16x16x32_f16 v[60:63], v[132:135], v[190:193], v[60:63]
	v_mfma_f32_16x16x32_f16 v[56:59], v[140:143], v[190:193], v[56:59]
	v_mfma_f32_16x16x32_f16 v[44:47], v[132:135], v[198:201], v[44:47]
	v_mfma_f32_16x16x32_f16 v[40:43], v[140:143], v[198:201], v[40:43]
	v_mfma_f32_16x16x32_f16 v[28:31], v[132:135], v[210:213], v[28:31]
	v_mfma_f32_16x16x32_f16 v[24:27], v[140:143], v[210:213], v[24:27]
	v_mfma_f32_16x16x32_f16 v[12:15], v[132:135], v[218:221], v[12:15]
	v_mfma_f32_16x16x32_f16 v[8:11], v[140:143], v[218:221], v[8:11]
	s_setprio 1
	s_setprio 0
	v_mfma_f32_16x16x32_f16 v[52:55], v[160:163], v[186:189], v[52:55]
	v_mfma_f32_16x16x32_f16 v[48:51], v[178:181], v[186:189], v[48:51]
	v_mfma_f32_16x16x32_f16 v[36:39], v[160:163], v[194:197], v[36:39]
	v_mfma_f32_16x16x32_f16 v[32:35], v[178:181], v[194:197], v[32:35]
	v_mfma_f32_16x16x32_f16 v[20:23], v[160:163], v[206:209], v[20:23]
	v_mfma_f32_16x16x32_f16 v[16:19], v[178:181], v[206:209], v[16:19]
	v_mfma_f32_16x16x32_f16 v[4:7], v[160:163], v[214:217], v[4:7]
	v_mfma_f32_16x16x32_f16 v[0:3], v[178:181], v[214:217], v[0:3]
	v_mfma_f32_16x16x32_f16 v[52:55], v[172:175], v[190:193], v[52:55]
	v_mfma_f32_16x16x32_f16 v[48:51], v[182:185], v[190:193], v[48:51]
	v_mfma_f32_16x16x32_f16 v[36:39], v[172:175], v[198:201], v[36:39]
	v_mfma_f32_16x16x32_f16 v[32:35], v[182:185], v[198:201], v[32:35]
	v_mfma_f32_16x16x32_f16 v[20:23], v[172:175], v[210:213], v[20:23]
	v_mfma_f32_16x16x32_f16 v[16:19], v[182:185], v[210:213], v[16:19]
	v_mfma_f32_16x16x32_f16 v[4:7], v[172:175], v[218:221], v[4:7]
	v_mfma_f32_16x16x32_f16 v[0:3], v[182:185], v[218:221], v[0:3]
	s_setprio 1
	s_barrier
	s_add_i32 s73, s73, 2
	s_add_u32 s40, s40, 0x100
	s_addc_u32 s41, s41, 0
	s_add_u32 s71, s71, 0x100
	s_addc_u32 s72, s72, 0
	s_cmp_gt_u32 s73, 13
	s_cbranch_scc0 .LBB0_464
	s_and_b64 vcc, exec, s[10:11]
	s_cbranch_vccz .LBB0_467
	s_barrier

.LBB0_734:
	ds_read_b128 v[84:87], v208
	ds_read_b128 v[88:91], v208 offset:1024
	ds_read_b128 v[92:95], v208 offset:2048
	ds_read_b128 v[100:103], v208 offset:3072
	ds_read_b128 v[144:147], v209
	ds_read_b128 v[148:151], v209 offset:1024
	ds_read_b128 v[152:155], v209 offset:2048
	ds_read_b128 v[156:159], v209 offset:3072
	s_add_u32 s40, s34, 0xfffc0080
	s_addc_u32 s41, s35, -1
	s_cmp_eq_u32 s71, 12
	s_cselect_b32 s45, s19, s41
	s_cselect_b32 s44, s25, s40
	s_cselect_b32 s41, s17, s70
	s_cselect_b32 s40, s68, s69
	v_lshl_add_u64 v[202:203], s[34:35], 0, v[178:179]
	s_add_i32 m0, s27, 0xc000
	ds_read_b128 v[160:163], v210
	ds_read_b128 v[164:167], v210 offset:1024
	ds_read_b128 v[186:189], v210 offset:2048
	ds_read_b128 v[190:193], v210 offset:3072
	ds_read_b128 v[194:197], v210 offset:4096
	ds_read_b128 v[198:201], v210 offset:5120
	ds_read_b128 v[212:215], v210 offset:6144
	ds_read_b128 v[216:219], v210 offset:7168
	global_load_lds_dwordx4 v[202:203], off
	v_lshl_add_u64 v[202:203], s[34:35], 0, v[180:181]
	s_add_i32 m0, s27, 0xe000
	s_nop 0
	global_load_lds_dwordx4 v[202:203], off
	s_waitcnt vmcnt(8)
	s_waitcnt lgkmcnt(0)
	s_barrier
	s_setprio 0
	s_waitcnt lgkmcnt(0)
	v_mfma_f32_16x16x32_f16 v[136:139], v[84:87], v[160:163], v[136:139]
	v_mfma_f32_16x16x32_f16 v[128:131], v[92:95], v[160:163], v[128:131]
	v_mfma_f32_16x16x32_f16 v[124:127], v[84:87], v[186:189], v[124:127]
	v_mfma_f32_16x16x32_f16 v[116:119], v[92:95], v[186:189], v[116:119]
	v_mfma_f32_16x16x32_f16 v[108:111], v[84:87], v[194:197], v[108:111]
	v_mfma_f32_16x16x32_f16 v[96:99], v[92:95], v[194:197], v[96:99]
	v_mfma_f32_16x16x32_f16 v[76:79], v[84:87], v[212:215], v[76:79]
	v_mfma_f32_16x16x32_f16 v[68:71], v[92:95], v[212:215], v[68:71]
	v_mfma_f32_16x16x32_f16 v[136:139], v[88:91], v[164:167], v[136:139]
	v_mfma_f32_16x16x32_f16 v[128:131], v[100:103], v[164:167], v[128:131]
	v_mfma_f32_16x16x32_f16 v[124:127], v[88:91], v[190:193], v[124:127]
	v_mfma_f32_16x16x32_f16 v[116:119], v[100:103], v[190:193], v[116:119]
	v_mfma_f32_16x16x32_f16 v[108:111], v[88:91], v[198:201], v[108:111]
	v_mfma_f32_16x16x32_f16 v[96:99], v[100:103], v[198:201], v[96:99]
	v_mfma_f32_16x16x32_f16 v[76:79], v[88:91], v[216:219], v[76:79]
	v_mfma_f32_16x16x32_f16 v[68:71], v[100:103], v[216:219], v[68:71]
	s_setprio 1
	s_setprio 0
	v_mfma_f32_16x16x32_f16 v[140:143], v[144:147], v[160:163], v[140:143]
	v_mfma_f32_16x16x32_f16 v[132:135], v[152:155], v[160:163], v[132:135]
	v_mfma_f32_16x16x32_f16 v[120:123], v[144:147], v[186:189], v[120:123]
	v_mfma_f32_16x16x32_f16 v[112:115], v[152:155], v[186:189], v[112:115]
	v_mfma_f32_16x16x32_f16 v[104:107], v[144:147], v[194:197], v[104:107]
	v_mfma_f32_16x16x32_f16 v[80:83], v[152:155], v[194:197], v[80:83]
	v_mfma_f32_16x16x32_f16 v[72:75], v[144:147], v[212:215], v[72:75]
	v_mfma_f32_16x16x32_f16 v[64:67], v[152:155], v[212:215], v[64:67]
	v_mfma_f32_16x16x32_f16 v[140:143], v[148:151], v[164:167], v[140:143]
	v_mfma_f32_16x16x32_f16 v[132:135], v[156:159], v[164:167], v[132:135]
	v_mfma_f32_16x16x32_f16 v[120:123], v[148:151], v[190:193], v[120:123]
	v_mfma_f32_16x16x32_f16 v[112:115], v[156:159], v[190:193], v[112:115]
	v_mfma_f32_16x16x32_f16 v[104:107], v[148:151], v[198:201], v[104:107]
	v_mfma_f32_16x16x32_f16 v[80:83], v[156:159], v[198:201], v[80:83]
	v_mfma_f32_16x16x32_f16 v[72:75], v[148:151], v[216:219], v[72:75]
	v_mfma_f32_16x16x32_f16 v[64:67], v[156:159], v[216:219], v[64:67]
	s_setprio 1
	s_barrier
	s_add_i32 s72, s66, s49
	v_lshl_add_u64 v[202:203], s[40:41], 0, v[170:171]
	s_mov_b32 m0, s72
	ds_read_b128 v[160:163], v210 offset:16384
	ds_read_b128 v[164:167], v210 offset:17408
	ds_read_b128 v[186:189], v210 offset:18432
	ds_read_b128 v[190:193], v210 offset:19456
	ds_read_b128 v[194:197], v210 offset:20480
	ds_read_b128 v[198:201], v210 offset:21504
	ds_read_b128 v[212:215], v210 offset:22528
	ds_read_b128 v[216:219], v210 offset:23552
	global_load_lds_dwordx4 v[202:203], off
	s_add_i32 m0, s72, 0x2000
	s_add_u32 s72, s40, 0x40000
	v_lshl_add_u64 v[220:221], s[40:41], 0, v[174:175]
	s_addc_u32 s73, s41, 0
	s_add_i32 s74, s67, s49
	global_load_lds_dwordx4 v[220:221], off
	v_lshl_add_u64 v[222:223], s[72:73], 0, v[170:171]
	s_mov_b32 m0, s74
	v_lshl_add_u64 v[224:225], s[44:45], 0, v[172:173]
	global_load_lds_dwordx4 v[222:223], off
	v_lshl_add_u64 v[222:223], s[72:73], 0, v[174:175]
	s_add_i32 m0, s74, 0x2000
	s_nop 0
	global_load_lds_dwordx4 v[222:223], off
	v_lshl_add_u64 v[222:223], s[44:45], 0, v[168:169]
	s_mov_b32 m0, s27
	s_nop 0
	global_load_lds_dwordx4 v[222:223], off
	s_mov_b32 m0, s54
	s_nop 0
	global_load_lds_dwordx4 v[224:225], off
	s_waitcnt vmcnt(8)
	s_waitcnt lgkmcnt(0)
	s_barrier
	s_setprio 0
	s_waitcnt lgkmcnt(0)
	v_mfma_f32_16x16x32_f16 v[60:63], v[84:87], v[160:163], v[60:63]
	v_mfma_f32_16x16x32_f16 v[52:55], v[92:95], v[160:163], v[52:55]
	v_mfma_f32_16x16x32_f16 v[44:47], v[84:87], v[186:189], v[44:47]
	v_mfma_f32_16x16x32_f16 v[36:39], v[92:95], v[186:189], v[36:39]
	v_mfma_f32_16x16x32_f16 v[28:31], v[84:87], v[194:197], v[28:31]
	v_mfma_f32_16x16x32_f16 v[20:23], v[92:95], v[194:197], v[20:23]
	v_mfma_f32_16x16x32_f16 v[12:15], v[84:87], v[212:215], v[12:15]
	v_mfma_f32_16x16x32_f16 v[4:7], v[92:95], v[212:215], v[4:7]
	v_mfma_f32_16x16x32_f16 v[60:63], v[88:91], v[164:167], v[60:63]
	v_mfma_f32_16x16x32_f16 v[52:55], v[100:103], v[164:167], v[52:55]
	v_mfma_f32_16x16x32_f16 v[44:47], v[88:91], v[190:193], v[44:47]
	v_mfma_f32_16x16x32_f16 v[36:39], v[100:103], v[190:193], v[36:39]
	v_mfma_f32_16x16x32_f16 v[28:31], v[88:91], v[198:201], v[28:31]
	v_mfma_f32_16x16x32_f16 v[20:23], v[100:103], v[198:201], v[20:23]
	v_mfma_f32_16x16x32_f16 v[12:15], v[88:91], v[216:219], v[12:15]
	v_mfma_f32_16x16x32_f16 v[4:7], v[100:103], v[216:219], v[4:7]
	s_setprio 1
	s_setprio 0
	v_mfma_f32_16x16x32_f16 v[56:59], v[144:147], v[160:163], v[56:59]
	v_mfma_f32_16x16x32_f16 v[48:51], v[152:155], v[160:163], v[48:51]
	v_mfma_f32_16x16x32_f16 v[40:43], v[144:147], v[186:189], v[40:43]
	v_mfma_f32_16x16x32_f16 v[32:35], v[152:155], v[186:189], v[32:35]
	v_mfma_f32_16x16x32_f16 v[24:27], v[144:147], v[194:197], v[24:27]
	v_mfma_f32_16x16x32_f16 v[16:19], v[152:155], v[194:197], v[16:19]
	v_mfma_f32_16x16x32_f16 v[8:11], v[144:147], v[212:215], v[8:11]
	v_mfma_f32_16x16x32_f16 v[0:3], v[152:155], v[212:215], v[0:3]
	v_mfma_f32_16x16x32_f16 v[56:59], v[148:151], v[164:167], v[56:59]
	v_mfma_f32_16x16x32_f16 v[48:51], v[156:159], v[164:167], v[48:51]
	v_mfma_f32_16x16x32_f16 v[40:43], v[148:151], v[190:193], v[40:43]
	v_mfma_f32_16x16x32_f16 v[32:35], v[156:159], v[190:193], v[32:35]
	v_mfma_f32_16x16x32_f16 v[24:27], v[148:151], v[198:201], v[24:27]
	v_mfma_f32_16x16x32_f16 v[16:19], v[156:159], v[198:201], v[16:19]
	v_mfma_f32_16x16x32_f16 v[8:11], v[148:151], v[216:219], v[8:11]
	v_mfma_f32_16x16x32_f16 v[0:3], v[156:159], v[216:219], v[0:3]
	s_setprio 1
	s_barrier
	s_add_i32 s72, 0, 0x18000
	s_add_i32 s73, 0, 0x1c000
	v_add_u32_e32 v100, s72, v206
	v_add_u32_e32 v156, s73, v206
	ds_read_b128 v[84:87], v100
	ds_read_b128 v[88:91], v100 offset:1024
	ds_read_b128 v[92:95], v100 offset:2048
	ds_read_b128 v[100:103], v100 offset:3072
	ds_read_b128 v[144:147], v156
	ds_read_b128 v[148:151], v156 offset:1024
	ds_read_b128 v[152:155], v156 offset:2048
	ds_read_b128 v[156:159], v156 offset:3072
	s_add_u32 s44, s44, 0x40000
	s_addc_u32 s45, s45, 0
	s_mov_b32 m0, s55
	v_lshl_add_u64 v[226:227], s[44:45], 0, v[168:169]
	ds_read_b128 v[160:163], v210 offset:32768
	ds_read_b128 v[164:167], v210 offset:33792
	ds_read_b128 v[186:189], v210 offset:34816
	ds_read_b128 v[190:193], v210 offset:35840
	ds_read_b128 v[194:197], v210 offset:36864
	ds_read_b128 v[198:201], v210 offset:37888
	ds_read_b128 v[212:215], v210 offset:38912
	ds_read_b128 v[216:219], v210 offset:39936
	global_load_lds_dwordx4 v[226:227], off
	v_lshl_add_u64 v[226:227], s[44:45], 0, v[172:173]
	s_mov_b32 m0, s56
	s_nop 0
	global_load_lds_dwordx4 v[226:227], off
	s_waitcnt vmcnt(8)
	s_waitcnt lgkmcnt(0)
	s_barrier
	s_setprio 0
	s_waitcnt lgkmcnt(0)
	v_mfma_f32_16x16x32_f16 v[136:139], v[84:87], v[160:163], v[136:139]
	v_mfma_f32_16x16x32_f16 v[128:131], v[92:95], v[160:163], v[128:131]
	v_mfma_f32_16x16x32_f16 v[124:127], v[84:87], v[186:189], v[124:127]
	v_mfma_f32_16x16x32_f16 v[116:119], v[92:95], v[186:189], v[116:119]
	v_mfma_f32_16x16x32_f16 v[108:111], v[84:87], v[194:197], v[108:111]
	v_mfma_f32_16x16x32_f16 v[96:99], v[92:95], v[194:197], v[96:99]
	v_mfma_f32_16x16x32_f16 v[76:79], v[84:87], v[212:215], v[76:79]
	v_mfma_f32_16x16x32_f16 v[68:71], v[92:95], v[212:215], v[68:71]
	v_mfma_f32_16x16x32_f16 v[136:139], v[88:91], v[164:167], v[136:139]
	v_mfma_f32_16x16x32_f16 v[128:131], v[100:103], v[164:167], v[128:131]
	v_mfma_f32_16x16x32_f16 v[124:127], v[88:91], v[190:193], v[124:127]
	v_mfma_f32_16x16x32_f16 v[116:119], v[100:103], v[190:193], v[116:119]
	v_mfma_f32_16x16x32_f16 v[108:111], v[88:91], v[198:201], v[108:111]
	v_mfma_f32_16x16x32_f16 v[96:99], v[100:103], v[198:201], v[96:99]
	v_mfma_f32_16x16x32_f16 v[76:79], v[88:91], v[216:219], v[76:79]
	v_mfma_f32_16x16x32_f16 v[68:71], v[100:103], v[216:219], v[68:71]
	s_setprio 1
	s_setprio 0
	v_mfma_f32_16x16x32_f16 v[140:143], v[144:147], v[160:163], v[140:143]
	v_mfma_f32_16x16x32_f16 v[132:135], v[152:155], v[160:163], v[132:135]
	v_mfma_f32_16x16x32_f16 v[120:123], v[144:147], v[186:189], v[120:123]
	v_mfma_f32_16x16x32_f16 v[112:115], v[152:155], v[186:189], v[112:115]
	v_mfma_f32_16x16x32_f16 v[104:107], v[144:147], v[194:197], v[104:107]
	v_mfma_f32_16x16x32_f16 v[80:83], v[152:155], v[194:197], v[80:83]
	v_mfma_f32_16x16x32_f16 v[72:75], v[144:147], v[212:215], v[72:75]
	v_mfma_f32_16x16x32_f16 v[64:67], v[152:155], v[212:215], v[64:67]
	v_mfma_f32_16x16x32_f16 v[140:143], v[148:151], v[164:167], v[140:143]
	v_mfma_f32_16x16x32_f16 v[132:135], v[156:159], v[164:167], v[132:135]
	v_mfma_f32_16x16x32_f16 v[120:123], v[148:151], v[190:193], v[120:123]
	v_mfma_f32_16x16x32_f16 v[112:115], v[156:159], v[190:193], v[112:115]
	v_mfma_f32_16x16x32_f16 v[104:107], v[148:151], v[198:201], v[104:107]
	v_mfma_f32_16x16x32_f16 v[80:83], v[156:159], v[198:201], v[80:83]
	v_mfma_f32_16x16x32_f16 v[72:75], v[148:151], v[216:219], v[72:75]
	v_mfma_f32_16x16x32_f16 v[64:67], v[156:159], v[216:219], v[64:67]
	s_setprio 1
	s_barrier
	s_add_i32 s44, s72, s49
	v_lshl_add_u64 v[202:203], v[202:203], 0, s[12:13]
	s_mov_b32 m0, s44
	ds_read_b128 v[160:163], v210 offset:49152
	ds_read_b128 v[164:167], v210 offset:50176
	ds_read_b128 v[186:189], v210 offset:51200
	ds_read_b128 v[190:193], v210 offset:52224
	ds_read_b128 v[194:197], v210 offset:53248
	ds_read_b128 v[198:201], v210 offset:54272
	ds_read_b128 v[212:215], v210 offset:55296
	ds_read_b128 v[216:219], v210 offset:56320
	global_load_lds_dwordx4 v[202:203], off
	s_add_i32 m0, s44, 0x2000
	s_add_u32 s40, s40, 0x40080
	v_lshl_add_u64 v[202:203], v[220:221], 0, s[12:13]
	s_addc_u32 s41, s41, 0
	s_add_i32 s44, s73, s49
	global_load_lds_dwordx4 v[202:203], off
	v_lshl_add_u64 v[202:203], s[40:41], 0, v[170:171]
	s_mov_b32 m0, s44
	s_nop 0
	global_load_lds_dwordx4 v[202:203], off
	v_lshl_add_u64 v[202:203], s[40:41], 0, v[174:175]
	s_add_i32 m0, s44, 0x2000
	s_nop 0
	global_load_lds_dwordx4 v[202:203], off
	v_lshl_add_u64 v[202:203], v[222:223], 0, s[12:13]
	s_mov_b32 m0, s62
	s_nop 0
	global_load_lds_dwordx4 v[202:203], off
	v_lshl_add_u64 v[202:203], v[224:225], 0, s[12:13]
	s_mov_b32 m0, s63
	s_nop 0
	global_load_lds_dwordx4 v[202:203], off
	s_waitcnt vmcnt(8)
	s_waitcnt lgkmcnt(0)
	s_barrier
	s_setprio 0
	s_waitcnt lgkmcnt(0)
	v_mfma_f32_16x16x32_f16 v[60:63], v[84:87], v[160:163], v[60:63]
	v_mfma_f32_16x16x32_f16 v[52:55], v[92:95], v[160:163], v[52:55]
	v_mfma_f32_16x16x32_f16 v[44:47], v[84:87], v[186:189], v[44:47]
	v_mfma_f32_16x16x32_f16 v[36:39], v[92:95], v[186:189], v[36:39]
	v_mfma_f32_16x16x32_f16 v[28:31], v[84:87], v[194:197], v[28:31]
	v_mfma_f32_16x16x32_f16 v[20:23], v[92:95], v[194:197], v[20:23]
	v_mfma_f32_16x16x32_f16 v[12:15], v[84:87], v[212:215], v[12:15]
	v_mfma_f32_16x16x32_f16 v[4:7], v[92:95], v[212:215], v[4:7]
	v_mfma_f32_16x16x32_f16 v[60:63], v[88:91], v[164:167], v[60:63]
	v_mfma_f32_16x16x32_f16 v[52:55], v[100:103], v[164:167], v[52:55]
	v_mfma_f32_16x16x32_f16 v[44:47], v[88:91], v[190:193], v[44:47]
	v_mfma_f32_16x16x32_f16 v[36:39], v[100:103], v[190:193], v[36:39]
	v_mfma_f32_16x16x32_f16 v[28:31], v[88:91], v[198:201], v[28:31]
	v_mfma_f32_16x16x32_f16 v[20:23], v[100:103], v[198:201], v[20:23]
	v_mfma_f32_16x16x32_f16 v[12:15], v[88:91], v[216:219], v[12:15]
	v_mfma_f32_16x16x32_f16 v[4:7], v[100:103], v[216:219], v[4:7]
	s_setprio 1
	s_setprio 0
	v_mfma_f32_16x16x32_f16 v[56:59], v[144:147], v[160:163], v[56:59]
	v_mfma_f32_16x16x32_f16 v[48:51], v[152:155], v[160:163], v[48:51]
	v_mfma_f32_16x16x32_f16 v[40:43], v[144:147], v[186:189], v[40:43]
	v_mfma_f32_16x16x32_f16 v[32:35], v[152:155], v[186:189], v[32:35]
	v_mfma_f32_16x16x32_f16 v[24:27], v[144:147], v[194:197], v[24:27]
	v_mfma_f32_16x16x32_f16 v[16:19], v[152:155], v[194:197], v[16:19]
	v_mfma_f32_16x16x32_f16 v[8:11], v[144:147], v[212:215], v[8:11]
	v_mfma_f32_16x16x32_f16 v[0:3], v[152:155], v[212:215], v[0:3]
	v_mfma_f32_16x16x32_f16 v[56:59], v[148:151], v[164:167], v[56:59]
	v_mfma_f32_16x16x32_f16 v[48:51], v[156:159], v[164:167], v[48:51]
	v_mfma_f32_16x16x32_f16 v[40:43], v[148:151], v[190:193], v[40:43]
	v_mfma_f32_16x16x32_f16 v[32:35], v[156:159], v[190:193], v[32:35]
	v_mfma_f32_16x16x32_f16 v[24:27], v[148:151], v[198:201], v[24:27]
	v_mfma_f32_16x16x32_f16 v[16:19], v[156:159], v[198:201], v[16:19]
	v_mfma_f32_16x16x32_f16 v[8:11], v[148:151], v[216:219], v[8:11]
	v_mfma_f32_16x16x32_f16 v[0:3], v[156:159], v[216:219], v[0:3]
	s_setprio 1
	s_barrier
	s_add_i32 s71, s71, 2
	s_add_u32 s34, s34, 0x100
	s_addc_u32 s35, s35, 0
	s_add_u32 s69, s69, 0x100
	s_addc_u32 s70, s70, 0
	s_cmp_gt_u32 s71, 13
	s_cbranch_scc0 .LBB0_734
	s_and_b64 vcc, exec, s[14:15]
	s_cbranch_vccz .LBB0_737
	s_barrier

.LBB0_873:
	ds_read_b128 v[104:107], v171
	ds_read_b128 v[108:111], v171 offset:1024
	ds_read_b128 v[112:115], v171 offset:2048
	ds_read_b128 v[116:119], v171 offset:3072
	ds_read_b128 v[160:163], v172
	ds_read_b128 v[164:167], v172 offset:1024
	ds_read_b128 v[178:181], v172 offset:2048
	ds_read_b128 v[182:185], v172 offset:3072
	s_add_u32 s26, s24, 0xfffc0080
	s_addc_u32 s27, s25, -1
	s_cmp_eq_u32 s67, 12
	s_cselect_b32 s35, s17, s27
	s_cselect_b32 s34, s63, s26
	s_cselect_b32 s27, s15, s66
	s_cselect_b32 s26, s64, s65
	v_lshl_add_u64 v[202:203], s[24:25], 0, v[152:153]
	s_add_i32 m0, s23, 0xc000
	ds_read_b128 v[186:189], v173
	ds_read_b128 v[190:193], v173 offset:1024
	ds_read_b128 v[194:197], v173 offset:2048
	ds_read_b128 v[198:201], v173 offset:3072
	ds_read_b128 v[206:209], v173 offset:4096
	ds_read_b128 v[210:213], v173 offset:5120
	ds_read_b128 v[214:217], v173 offset:6144
	ds_read_b128 v[218:221], v173 offset:7168
	global_load_lds_dwordx4 v[202:203], off
	v_lshl_add_u64 v[202:203], s[24:25], 0, v[154:155]
	s_add_i32 m0, s23, 0xe000
	s_nop 0
	global_load_lds_dwordx4 v[202:203], off
	s_waitcnt vmcnt(8)
	s_waitcnt lgkmcnt(0)
	s_barrier
	s_setprio 0
	s_waitcnt lgkmcnt(0)
	v_mfma_f32_16x16x32_f16 v[140:143], v[104:107], v[186:189], v[140:143]
	v_mfma_f32_16x16x32_f16 v[136:139], v[112:115], v[186:189], v[136:139]
	v_mfma_f32_16x16x32_f16 v[124:127], v[104:107], v[194:197], v[124:127]
	v_mfma_f32_16x16x32_f16 v[120:123], v[112:115], v[194:197], v[120:123]
	v_mfma_f32_16x16x32_f16 v[92:95], v[104:107], v[206:209], v[92:95]
	v_mfma_f32_16x16x32_f16 v[88:91], v[112:115], v[206:209], v[88:91]
	v_mfma_f32_16x16x32_f16 v[76:79], v[104:107], v[214:217], v[76:79]
	v_mfma_f32_16x16x32_f16 v[72:75], v[112:115], v[214:217], v[72:75]
	v_mfma_f32_16x16x32_f16 v[140:143], v[108:111], v[190:193], v[140:143]
	v_mfma_f32_16x16x32_f16 v[136:139], v[116:119], v[190:193], v[136:139]
	v_mfma_f32_16x16x32_f16 v[124:127], v[108:111], v[198:201], v[124:127]
	v_mfma_f32_16x16x32_f16 v[120:123], v[116:119], v[198:201], v[120:123]
	v_mfma_f32_16x16x32_f16 v[92:95], v[108:111], v[210:213], v[92:95]
	v_mfma_f32_16x16x32_f16 v[88:91], v[116:119], v[210:213], v[88:91]
	v_mfma_f32_16x16x32_f16 v[76:79], v[108:111], v[218:221], v[76:79]
	v_mfma_f32_16x16x32_f16 v[72:75], v[116:119], v[218:221], v[72:75]
	s_setprio 1
	s_setprio 0
	v_mfma_f32_16x16x32_f16 v[132:135], v[160:163], v[186:189], v[132:135]
	v_mfma_f32_16x16x32_f16 v[128:131], v[178:181], v[186:189], v[128:131]
	v_mfma_f32_16x16x32_f16 v[100:103], v[160:163], v[194:197], v[100:103]
	v_mfma_f32_16x16x32_f16 v[96:99], v[178:181], v[194:197], v[96:99]
	v_mfma_f32_16x16x32_f16 v[84:87], v[160:163], v[206:209], v[84:87]
	v_mfma_f32_16x16x32_f16 v[80:83], v[178:181], v[206:209], v[80:83]
	v_mfma_f32_16x16x32_f16 v[68:71], v[160:163], v[214:217], v[68:71]
	v_mfma_f32_16x16x32_f16 v[64:67], v[178:181], v[214:217], v[64:67]
	v_mfma_f32_16x16x32_f16 v[132:135], v[164:167], v[190:193], v[132:135]
	v_mfma_f32_16x16x32_f16 v[128:131], v[182:185], v[190:193], v[128:131]
	v_mfma_f32_16x16x32_f16 v[100:103], v[164:167], v[198:201], v[100:103]
	v_mfma_f32_16x16x32_f16 v[96:99], v[182:185], v[198:201], v[96:99]
	v_mfma_f32_16x16x32_f16 v[84:87], v[164:167], v[210:213], v[84:87]
	v_mfma_f32_16x16x32_f16 v[80:83], v[182:185], v[210:213], v[80:83]
	v_mfma_f32_16x16x32_f16 v[68:71], v[164:167], v[218:221], v[68:71]
	v_mfma_f32_16x16x32_f16 v[64:67], v[182:185], v[218:221], v[64:67]
	s_setprio 1
	s_barrier
	s_add_i32 s68, s58, s44
	v_lshl_add_u64 v[202:203], s[26:27], 0, v[146:147]
	s_mov_b32 m0, s68
	ds_read_b128 v[186:189], v173 offset:16384
	ds_read_b128 v[190:193], v173 offset:17408
	ds_read_b128 v[194:197], v173 offset:18432
	ds_read_b128 v[198:201], v173 offset:19456
	ds_read_b128 v[206:209], v173 offset:20480
	ds_read_b128 v[210:213], v173 offset:21504
	ds_read_b128 v[214:217], v173 offset:22528
	ds_read_b128 v[218:221], v173 offset:23552
	global_load_lds_dwordx4 v[202:203], off
	s_add_i32 m0, s68, 0x2000
	s_add_u32 s68, s26, 0x40000
	v_lshl_add_u64 v[222:223], s[26:27], 0, v[150:151]
	s_addc_u32 s69, s27, 0
	s_add_i32 s70, s59, s44
	global_load_lds_dwordx4 v[222:223], off
	v_lshl_add_u64 v[224:225], s[68:69], 0, v[146:147]
	s_mov_b32 m0, s70
	v_lshl_add_u64 v[226:227], s[34:35], 0, v[148:149]
	global_load_lds_dwordx4 v[224:225], off
	v_lshl_add_u64 v[224:225], s[68:69], 0, v[150:151]
	s_add_i32 m0, s70, 0x2000
	s_nop 0
	global_load_lds_dwordx4 v[224:225], off
	v_lshl_add_u64 v[224:225], s[34:35], 0, v[144:145]
	s_mov_b32 m0, s23
	s_nop 0
	global_load_lds_dwordx4 v[224:225], off
	s_mov_b32 m0, s45
	s_nop 0
	global_load_lds_dwordx4 v[226:227], off
	s_waitcnt vmcnt(8)
	s_waitcnt lgkmcnt(0)
	s_barrier
	s_setprio 0
	s_waitcnt lgkmcnt(0)
	v_mfma_f32_16x16x32_f16 v[60:63], v[104:107], v[186:189], v[60:63]
	v_mfma_f32_16x16x32_f16 v[56:59], v[112:115], v[186:189], v[56:59]
	v_mfma_f32_16x16x32_f16 v[44:47], v[104:107], v[194:197], v[44:47]
	v_mfma_f32_16x16x32_f16 v[40:43], v[112:115], v[194:197], v[40:43]
	v_mfma_f32_16x16x32_f16 v[28:31], v[104:107], v[206:209], v[28:31]
	v_mfma_f32_16x16x32_f16 v[24:27], v[112:115], v[206:209], v[24:27]
	v_mfma_f32_16x16x32_f16 v[12:15], v[104:107], v[214:217], v[12:15]
	v_mfma_f32_16x16x32_f16 v[8:11], v[112:115], v[214:217], v[8:11]
	v_mfma_f32_16x16x32_f16 v[60:63], v[108:111], v[190:193], v[60:63]
	v_mfma_f32_16x16x32_f16 v[56:59], v[116:119], v[190:193], v[56:59]
	v_mfma_f32_16x16x32_f16 v[44:47], v[108:111], v[198:201], v[44:47]
	v_mfma_f32_16x16x32_f16 v[40:43], v[116:119], v[198:201], v[40:43]
	v_mfma_f32_16x16x32_f16 v[28:31], v[108:111], v[210:213], v[28:31]
	v_mfma_f32_16x16x32_f16 v[24:27], v[116:119], v[210:213], v[24:27]
	v_mfma_f32_16x16x32_f16 v[12:15], v[108:111], v[218:221], v[12:15]
	v_mfma_f32_16x16x32_f16 v[8:11], v[116:119], v[218:221], v[8:11]
	s_setprio 1
	s_setprio 0
	v_mfma_f32_16x16x32_f16 v[52:55], v[160:163], v[186:189], v[52:55]
	v_mfma_f32_16x16x32_f16 v[48:51], v[178:181], v[186:189], v[48:51]
	v_mfma_f32_16x16x32_f16 v[36:39], v[160:163], v[194:197], v[36:39]
	v_mfma_f32_16x16x32_f16 v[32:35], v[178:181], v[194:197], v[32:35]
	v_mfma_f32_16x16x32_f16 v[20:23], v[160:163], v[206:209], v[20:23]
	v_mfma_f32_16x16x32_f16 v[16:19], v[178:181], v[206:209], v[16:19]
	v_mfma_f32_16x16x32_f16 v[4:7], v[160:163], v[214:217], v[4:7]
	v_mfma_f32_16x16x32_f16 v[0:3], v[178:181], v[214:217], v[0:3]
	v_mfma_f32_16x16x32_f16 v[52:55], v[164:167], v[190:193], v[52:55]
	v_mfma_f32_16x16x32_f16 v[48:51], v[182:185], v[190:193], v[48:51]
	v_mfma_f32_16x16x32_f16 v[36:39], v[164:167], v[198:201], v[36:39]
	v_mfma_f32_16x16x32_f16 v[32:35], v[182:185], v[198:201], v[32:35]
	v_mfma_f32_16x16x32_f16 v[20:23], v[164:167], v[210:213], v[20:23]
	v_mfma_f32_16x16x32_f16 v[16:19], v[182:185], v[210:213], v[16:19]
	v_mfma_f32_16x16x32_f16 v[4:7], v[164:167], v[218:221], v[4:7]
	v_mfma_f32_16x16x32_f16 v[0:3], v[182:185], v[218:221], v[0:3]
	s_setprio 1
	s_barrier
	s_add_i32 s68, 0, 0x18000
	s_add_i32 s69, 0, 0x1c000
	v_add_u32_e32 v116, s68, v169
	v_add_u32_e32 v177, s69, v169
	ds_read_b128 v[104:107], v116
	ds_read_b128 v[108:111], v116 offset:1024
	ds_read_b128 v[112:115], v116 offset:2048
	ds_read_b128 v[116:119], v116 offset:3072
	ds_read_b128 v[160:163], v177
	ds_read_b128 v[164:167], v177 offset:1024
	ds_read_b128 v[178:181], v177 offset:2048
	ds_read_b128 v[182:185], v177 offset:3072
	s_add_u32 s34, s34, 0x40000
	s_addc_u32 s35, s35, 0
	s_mov_b32 m0, s46
	v_lshl_add_u64 v[228:229], s[34:35], 0, v[144:145]
	ds_read_b128 v[186:189], v173 offset:32768
	ds_read_b128 v[190:193], v173 offset:33792
	ds_read_b128 v[194:197], v173 offset:34816
	ds_read_b128 v[198:201], v173 offset:35840
	ds_read_b128 v[206:209], v173 offset:36864
	ds_read_b128 v[210:213], v173 offset:37888
	ds_read_b128 v[214:217], v173 offset:38912
	ds_read_b128 v[218:221], v173 offset:39936
	global_load_lds_dwordx4 v[228:229], off
	v_lshl_add_u64 v[228:229], s[34:35], 0, v[148:149]
	s_mov_b32 m0, s47
	s_nop 0
	global_load_lds_dwordx4 v[228:229], off
	s_waitcnt vmcnt(8)
	s_waitcnt lgkmcnt(0)
	s_barrier
	s_setprio 0
	s_waitcnt lgkmcnt(0)
	v_mfma_f32_16x16x32_f16 v[140:143], v[104:107], v[186:189], v[140:143]
	v_mfma_f32_16x16x32_f16 v[136:139], v[112:115], v[186:189], v[136:139]
	v_mfma_f32_16x16x32_f16 v[124:127], v[104:107], v[194:197], v[124:127]
	v_mfma_f32_16x16x32_f16 v[120:123], v[112:115], v[194:197], v[120:123]
	v_mfma_f32_16x16x32_f16 v[92:95], v[104:107], v[206:209], v[92:95]
	v_mfma_f32_16x16x32_f16 v[88:91], v[112:115], v[206:209], v[88:91]
	v_mfma_f32_16x16x32_f16 v[76:79], v[104:107], v[214:217], v[76:79]
	v_mfma_f32_16x16x32_f16 v[72:75], v[112:115], v[214:217], v[72:75]
	v_mfma_f32_16x16x32_f16 v[140:143], v[108:111], v[190:193], v[140:143]
	v_mfma_f32_16x16x32_f16 v[136:139], v[116:119], v[190:193], v[136:139]
	v_mfma_f32_16x16x32_f16 v[124:127], v[108:111], v[198:201], v[124:127]
	v_mfma_f32_16x16x32_f16 v[120:123], v[116:119], v[198:201], v[120:123]
	v_mfma_f32_16x16x32_f16 v[92:95], v[108:111], v[210:213], v[92:95]
	v_mfma_f32_16x16x32_f16 v[88:91], v[116:119], v[210:213], v[88:91]
	v_mfma_f32_16x16x32_f16 v[76:79], v[108:111], v[218:221], v[76:79]
	v_mfma_f32_16x16x32_f16 v[72:75], v[116:119], v[218:221], v[72:75]
	s_setprio 1
	s_setprio 0
	v_mfma_f32_16x16x32_f16 v[132:135], v[160:163], v[186:189], v[132:135]
	v_mfma_f32_16x16x32_f16 v[128:131], v[178:181], v[186:189], v[128:131]
	v_mfma_f32_16x16x32_f16 v[100:103], v[160:163], v[194:197], v[100:103]
	v_mfma_f32_16x16x32_f16 v[96:99], v[178:181], v[194:197], v[96:99]
	v_mfma_f32_16x16x32_f16 v[84:87], v[160:163], v[206:209], v[84:87]
	v_mfma_f32_16x16x32_f16 v[80:83], v[178:181], v[206:209], v[80:83]
	v_mfma_f32_16x16x32_f16 v[68:71], v[160:163], v[214:217], v[68:71]
	v_mfma_f32_16x16x32_f16 v[64:67], v[178:181], v[214:217], v[64:67]
	v_mfma_f32_16x16x32_f16 v[132:135], v[164:167], v[190:193], v[132:135]
	v_mfma_f32_16x16x32_f16 v[128:131], v[182:185], v[190:193], v[128:131]
	v_mfma_f32_16x16x32_f16 v[100:103], v[164:167], v[198:201], v[100:103]
	v_mfma_f32_16x16x32_f16 v[96:99], v[182:185], v[198:201], v[96:99]
	v_mfma_f32_16x16x32_f16 v[84:87], v[164:167], v[210:213], v[84:87]
	v_mfma_f32_16x16x32_f16 v[80:83], v[182:185], v[210:213], v[80:83]
	v_mfma_f32_16x16x32_f16 v[68:71], v[164:167], v[218:221], v[68:71]
	v_mfma_f32_16x16x32_f16 v[64:67], v[182:185], v[218:221], v[64:67]
	s_setprio 1
	s_barrier
	s_add_i32 s34, s68, s44
	v_lshl_add_u64 v[202:203], v[202:203], 0, s[10:11]
	s_mov_b32 m0, s34
	ds_read_b128 v[186:189], v173 offset:49152
	ds_read_b128 v[190:193], v173 offset:50176
	ds_read_b128 v[194:197], v173 offset:51200
	ds_read_b128 v[198:201], v173 offset:52224
	ds_read_b128 v[206:209], v173 offset:53248
	ds_read_b128 v[210:213], v173 offset:54272
	ds_read_b128 v[214:217], v173 offset:55296
	ds_read_b128 v[218:221], v173 offset:56320
	global_load_lds_dwordx4 v[202:203], off
	s_add_i32 m0, s34, 0x2000
	s_add_u32 s26, s26, 0x40080
	v_lshl_add_u64 v[202:203], v[222:223], 0, s[10:11]
	s_addc_u32 s27, s27, 0
	s_add_i32 s34, s69, s44
	global_load_lds_dwordx4 v[202:203], off
	v_lshl_add_u64 v[202:203], s[26:27], 0, v[146:147]
	s_mov_b32 m0, s34
	s_nop 0
	global_load_lds_dwordx4 v[202:203], off
	v_lshl_add_u64 v[202:203], s[26:27], 0, v[150:151]
	s_add_i32 m0, s34, 0x2000
	s_nop 0
	global_load_lds_dwordx4 v[202:203], off
	v_lshl_add_u64 v[202:203], v[224:225], 0, s[10:11]
	s_mov_b32 m0, s55
	s_nop 0
	global_load_lds_dwordx4 v[202:203], off
	v_lshl_add_u64 v[202:203], v[226:227], 0, s[10:11]
	s_mov_b32 m0, s56
	s_nop 0
	global_load_lds_dwordx4 v[202:203], off
	s_waitcnt vmcnt(8)
	s_waitcnt lgkmcnt(0)
	s_barrier
	s_setprio 0
	s_waitcnt lgkmcnt(0)
	v_mfma_f32_16x16x32_f16 v[60:63], v[104:107], v[186:189], v[60:63]
	v_mfma_f32_16x16x32_f16 v[56:59], v[112:115], v[186:189], v[56:59]
	v_mfma_f32_16x16x32_f16 v[44:47], v[104:107], v[194:197], v[44:47]
	v_mfma_f32_16x16x32_f16 v[40:43], v[112:115], v[194:197], v[40:43]
	v_mfma_f32_16x16x32_f16 v[28:31], v[104:107], v[206:209], v[28:31]
	v_mfma_f32_16x16x32_f16 v[24:27], v[112:115], v[206:209], v[24:27]
	v_mfma_f32_16x16x32_f16 v[12:15], v[104:107], v[214:217], v[12:15]
	v_mfma_f32_16x16x32_f16 v[8:11], v[112:115], v[214:217], v[8:11]
	v_mfma_f32_16x16x32_f16 v[60:63], v[108:111], v[190:193], v[60:63]
	v_mfma_f32_16x16x32_f16 v[56:59], v[116:119], v[190:193], v[56:59]
	v_mfma_f32_16x16x32_f16 v[44:47], v[108:111], v[198:201], v[44:47]
	v_mfma_f32_16x16x32_f16 v[40:43], v[116:119], v[198:201], v[40:43]
	v_mfma_f32_16x16x32_f16 v[28:31], v[108:111], v[210:213], v[28:31]
	v_mfma_f32_16x16x32_f16 v[24:27], v[116:119], v[210:213], v[24:27]
	v_mfma_f32_16x16x32_f16 v[12:15], v[108:111], v[218:221], v[12:15]
	v_mfma_f32_16x16x32_f16 v[8:11], v[116:119], v[218:221], v[8:11]
	s_setprio 1
	s_setprio 0
	v_mfma_f32_16x16x32_f16 v[52:55], v[160:163], v[186:189], v[52:55]
	v_mfma_f32_16x16x32_f16 v[48:51], v[178:181], v[186:189], v[48:51]
	v_mfma_f32_16x16x32_f16 v[36:39], v[160:163], v[194:197], v[36:39]
	v_mfma_f32_16x16x32_f16 v[32:35], v[178:181], v[194:197], v[32:35]
	v_mfma_f32_16x16x32_f16 v[20:23], v[160:163], v[206:209], v[20:23]
	v_mfma_f32_16x16x32_f16 v[16:19], v[178:181], v[206:209], v[16:19]
	v_mfma_f32_16x16x32_f16 v[4:7], v[160:163], v[214:217], v[4:7]
	v_mfma_f32_16x16x32_f16 v[0:3], v[178:181], v[214:217], v[0:3]
	v_mfma_f32_16x16x32_f16 v[52:55], v[164:167], v[190:193], v[52:55]
	v_mfma_f32_16x16x32_f16 v[48:51], v[182:185], v[190:193], v[48:51]
	v_mfma_f32_16x16x32_f16 v[36:39], v[164:167], v[198:201], v[36:39]
	v_mfma_f32_16x16x32_f16 v[32:35], v[182:185], v[198:201], v[32:35]
	v_mfma_f32_16x16x32_f16 v[20:23], v[164:167], v[210:213], v[20:23]
	v_mfma_f32_16x16x32_f16 v[16:19], v[182:185], v[210:213], v[16:19]
	v_mfma_f32_16x16x32_f16 v[4:7], v[164:167], v[218:221], v[4:7]
	v_mfma_f32_16x16x32_f16 v[0:3], v[182:185], v[218:221], v[0:3]
	s_setprio 1
	s_barrier
	s_add_i32 s67, s67, 2
	s_add_u32 s24, s24, 0x100
	s_addc_u32 s25, s25, 0
	s_add_u32 s65, s65, 0x100
	s_addc_u32 s66, s66, 0
	s_cmp_gt_u32 s67, 13
	s_cbranch_scc0 .LBB0_873
	s_and_b64 vcc, exec, s[12:13]
	s_cbranch_vccz .LBB0_876
	s_barrier

.LBB0_1220:
	ds_read_b128 v[80:83], v208
	ds_read_b128 v[84:87], v208 offset:1024
	ds_read_b128 v[92:95], v208 offset:2048
	ds_read_b128 v[96:99], v208 offset:3072
	ds_read_b128 v[144:147], v209
	ds_read_b128 v[148:151], v209 offset:1024
	ds_read_b128 v[152:155], v209 offset:2048
	ds_read_b128 v[156:159], v209 offset:3072
	s_add_u32 s24, s22, 0x100
	s_addc_u32 s25, s23, 0
	s_cmp_eq_u32 s63, 40
	s_cselect_b32 s35, s1, s25
	s_cselect_b32 s34, s0, s24
	s_cselect_b32 s27, s21, s62
	s_cselect_b32 s26, s20, s61
	v_lshl_add_u64 v[202:203], s[22:23], 0, v[168:169]
	s_add_i32 m0, s40, 0xc000
	ds_read_b128 v[178:181], v210
	ds_read_b128 v[182:185], v210 offset:1024
	ds_read_b128 v[186:189], v210 offset:2048
	ds_read_b128 v[190:193], v210 offset:3072
	ds_read_b128 v[194:197], v210 offset:4096
	ds_read_b128 v[198:201], v210 offset:5120
	ds_read_b128 v[212:215], v210 offset:6144
	ds_read_b128 v[216:219], v210 offset:7168
	global_load_lds_dwordx4 v[202:203], off
	v_lshl_add_u64 v[202:203], s[22:23], 0, v[170:171]
	s_add_i32 m0, s40, 0xe000
	s_nop 0
	global_load_lds_dwordx4 v[202:203], off
	s_waitcnt vmcnt(8)
	s_waitcnt lgkmcnt(0)
	s_barrier
	s_setprio 0
	s_waitcnt lgkmcnt(0)
	v_mfma_f32_16x16x32_f16 v[140:143], v[80:83], v[178:181], v[140:143]
	v_mfma_f32_16x16x32_f16 v[136:139], v[92:95], v[178:181], v[136:139]
	v_mfma_f32_16x16x32_f16 v[124:127], v[80:83], v[186:189], v[124:127]
	v_mfma_f32_16x16x32_f16 v[120:123], v[92:95], v[186:189], v[120:123]
	v_mfma_f32_16x16x32_f16 v[108:111], v[80:83], v[194:197], v[108:111]
	v_mfma_f32_16x16x32_f16 v[104:107], v[92:95], v[194:197], v[104:107]
	v_mfma_f32_16x16x32_f16 v[76:79], v[80:83], v[212:215], v[76:79]
	v_mfma_f32_16x16x32_f16 v[72:75], v[92:95], v[212:215], v[72:75]
	v_mfma_f32_16x16x32_f16 v[140:143], v[84:87], v[182:185], v[140:143]
	v_mfma_f32_16x16x32_f16 v[136:139], v[96:99], v[182:185], v[136:139]
	v_mfma_f32_16x16x32_f16 v[124:127], v[84:87], v[190:193], v[124:127]
	v_mfma_f32_16x16x32_f16 v[120:123], v[96:99], v[190:193], v[120:123]
	v_mfma_f32_16x16x32_f16 v[108:111], v[84:87], v[198:201], v[108:111]
	v_mfma_f32_16x16x32_f16 v[104:107], v[96:99], v[198:201], v[104:107]
	v_mfma_f32_16x16x32_f16 v[76:79], v[84:87], v[216:219], v[76:79]
	v_mfma_f32_16x16x32_f16 v[72:75], v[96:99], v[216:219], v[72:75]
	s_setprio 1
	s_setprio 0
	v_mfma_f32_16x16x32_f16 v[132:135], v[144:147], v[178:181], v[132:135]
	v_mfma_f32_16x16x32_f16 v[128:131], v[152:155], v[178:181], v[128:131]
	v_mfma_f32_16x16x32_f16 v[116:119], v[144:147], v[186:189], v[116:119]
	v_mfma_f32_16x16x32_f16 v[112:115], v[152:155], v[186:189], v[112:115]
	v_mfma_f32_16x16x32_f16 v[100:103], v[144:147], v[194:197], v[100:103]
	v_mfma_f32_16x16x32_f16 v[88:91], v[152:155], v[194:197], v[88:91]
	v_mfma_f32_16x16x32_f16 v[68:71], v[144:147], v[212:215], v[68:71]
	v_mfma_f32_16x16x32_f16 v[64:67], v[152:155], v[212:215], v[64:67]
	v_mfma_f32_16x16x32_f16 v[132:135], v[148:151], v[182:185], v[132:135]
	v_mfma_f32_16x16x32_f16 v[128:131], v[156:159], v[182:185], v[128:131]
	v_mfma_f32_16x16x32_f16 v[116:119], v[148:151], v[190:193], v[116:119]
	v_mfma_f32_16x16x32_f16 v[112:115], v[156:159], v[190:193], v[112:115]
	v_mfma_f32_16x16x32_f16 v[100:103], v[148:151], v[198:201], v[100:103]
	v_mfma_f32_16x16x32_f16 v[88:91], v[156:159], v[198:201], v[88:91]
	v_mfma_f32_16x16x32_f16 v[68:71], v[148:151], v[216:219], v[68:71]
	v_mfma_f32_16x16x32_f16 v[64:67], v[156:159], v[216:219], v[64:67]
	s_setprio 1
	s_barrier
	s_add_i32 s22, s55, s33
	v_lshl_add_u64 v[202:203], s[26:27], 0, v[162:163]
	s_mov_b32 m0, s22
	ds_read_b128 v[178:181], v210 offset:16384
	ds_read_b128 v[182:185], v210 offset:17408
	ds_read_b128 v[186:189], v210 offset:18432
	ds_read_b128 v[190:193], v210 offset:19456
	ds_read_b128 v[194:197], v210 offset:20480
	ds_read_b128 v[198:201], v210 offset:21504
	ds_read_b128 v[212:215], v210 offset:22528
	ds_read_b128 v[216:219], v210 offset:23552
	global_load_lds_dwordx4 v[202:203], off
	s_add_i32 m0, s22, 0x2000
	s_add_u32 s22, s26, 0xb0000
	v_lshl_add_u64 v[220:221], s[26:27], 0, v[166:167]
	s_addc_u32 s23, s27, 0
	s_add_i32 s64, s56, s33
	global_load_lds_dwordx4 v[220:221], off
	v_lshl_add_u64 v[222:223], s[22:23], 0, v[162:163]
	s_mov_b32 m0, s64
	v_lshl_add_u64 v[224:225], s[34:35], 0, v[164:165]
	global_load_lds_dwordx4 v[222:223], off
	v_lshl_add_u64 v[222:223], s[22:23], 0, v[166:167]
	s_add_i32 m0, s64, 0x2000
	s_nop 0
	global_load_lds_dwordx4 v[222:223], off
	v_lshl_add_u64 v[222:223], s[34:35], 0, v[160:161]
	s_mov_b32 m0, s40
	s_nop 0
	global_load_lds_dwordx4 v[222:223], off
	s_mov_b32 m0, s41
	s_nop 0
	global_load_lds_dwordx4 v[224:225], off
	s_waitcnt vmcnt(8)
	s_waitcnt lgkmcnt(0)
	s_barrier
	s_setprio 0
	s_waitcnt lgkmcnt(0)
	v_mfma_f32_16x16x32_f16 v[60:63], v[80:83], v[178:181], v[60:63]
	v_mfma_f32_16x16x32_f16 v[56:59], v[92:95], v[178:181], v[56:59]
	v_mfma_f32_16x16x32_f16 v[44:47], v[80:83], v[186:189], v[44:47]
	v_mfma_f32_16x16x32_f16 v[40:43], v[92:95], v[186:189], v[40:43]
	v_mfma_f32_16x16x32_f16 v[28:31], v[80:83], v[194:197], v[28:31]
	v_mfma_f32_16x16x32_f16 v[24:27], v[92:95], v[194:197], v[24:27]
	v_mfma_f32_16x16x32_f16 v[12:15], v[80:83], v[212:215], v[12:15]
	v_mfma_f32_16x16x32_f16 v[8:11], v[92:95], v[212:215], v[8:11]
	v_mfma_f32_16x16x32_f16 v[60:63], v[84:87], v[182:185], v[60:63]
	v_mfma_f32_16x16x32_f16 v[56:59], v[96:99], v[182:185], v[56:59]
	v_mfma_f32_16x16x32_f16 v[44:47], v[84:87], v[190:193], v[44:47]
	v_mfma_f32_16x16x32_f16 v[40:43], v[96:99], v[190:193], v[40:43]
	v_mfma_f32_16x16x32_f16 v[28:31], v[84:87], v[198:201], v[28:31]
	v_mfma_f32_16x16x32_f16 v[24:27], v[96:99], v[198:201], v[24:27]
	v_mfma_f32_16x16x32_f16 v[12:15], v[84:87], v[216:219], v[12:15]
	v_mfma_f32_16x16x32_f16 v[8:11], v[96:99], v[216:219], v[8:11]
	s_setprio 1
	s_setprio 0
	v_mfma_f32_16x16x32_f16 v[52:55], v[144:147], v[178:181], v[52:55]
	v_mfma_f32_16x16x32_f16 v[48:51], v[152:155], v[178:181], v[48:51]
	v_mfma_f32_16x16x32_f16 v[36:39], v[144:147], v[186:189], v[36:39]
	v_mfma_f32_16x16x32_f16 v[32:35], v[152:155], v[186:189], v[32:35]
	v_mfma_f32_16x16x32_f16 v[20:23], v[144:147], v[194:197], v[20:23]
	v_mfma_f32_16x16x32_f16 v[16:19], v[152:155], v[194:197], v[16:19]
	v_mfma_f32_16x16x32_f16 v[4:7], v[144:147], v[212:215], v[4:7]
	v_mfma_f32_16x16x32_f16 v[0:3], v[152:155], v[212:215], v[0:3]
	v_mfma_f32_16x16x32_f16 v[52:55], v[148:151], v[182:185], v[52:55]
	v_mfma_f32_16x16x32_f16 v[48:51], v[156:159], v[182:185], v[48:51]
	v_mfma_f32_16x16x32_f16 v[36:39], v[148:151], v[190:193], v[36:39]
	v_mfma_f32_16x16x32_f16 v[32:35], v[156:159], v[190:193], v[32:35]
	v_mfma_f32_16x16x32_f16 v[20:23], v[148:151], v[198:201], v[20:23]
	v_mfma_f32_16x16x32_f16 v[16:19], v[156:159], v[198:201], v[16:19]
	v_mfma_f32_16x16x32_f16 v[4:7], v[148:151], v[216:219], v[4:7]
	v_mfma_f32_16x16x32_f16 v[0:3], v[156:159], v[216:219], v[0:3]
	s_setprio 1
	s_barrier
	s_add_i32 s64, 0, 0x18000
	s_add_i32 s65, 0, 0x1c000
	v_add_u32_e32 v96, s64, v206
	v_add_u32_e32 v156, s65, v206
	ds_read_b128 v[80:83], v96
	ds_read_b128 v[84:87], v96 offset:1024
	ds_read_b128 v[92:95], v96 offset:2048
	ds_read_b128 v[96:99], v96 offset:3072
	ds_read_b128 v[144:147], v156
	ds_read_b128 v[148:151], v156 offset:1024
	ds_read_b128 v[152:155], v156 offset:2048
	ds_read_b128 v[156:159], v156 offset:3072
	s_add_u32 s22, s34, 0xb0000
	s_addc_u32 s23, s35, 0
	s_mov_b32 m0, s44
	v_lshl_add_u64 v[226:227], s[22:23], 0, v[160:161]
	ds_read_b128 v[178:181], v210 offset:32768
	ds_read_b128 v[182:185], v210 offset:33792
	ds_read_b128 v[186:189], v210 offset:34816
	ds_read_b128 v[190:193], v210 offset:35840
	ds_read_b128 v[194:197], v210 offset:36864
	ds_read_b128 v[198:201], v210 offset:37888
	ds_read_b128 v[212:215], v210 offset:38912
	ds_read_b128 v[216:219], v210 offset:39936
	global_load_lds_dwordx4 v[226:227], off
	v_lshl_add_u64 v[226:227], s[22:23], 0, v[164:165]
	s_mov_b32 m0, s45
	s_nop 0
	global_load_lds_dwordx4 v[226:227], off
	s_waitcnt vmcnt(8)
	s_waitcnt lgkmcnt(0)
	s_barrier
	s_setprio 0
	s_waitcnt lgkmcnt(0)
	v_mfma_f32_16x16x32_f16 v[140:143], v[80:83], v[178:181], v[140:143]
	v_mfma_f32_16x16x32_f16 v[136:139], v[92:95], v[178:181], v[136:139]
	v_mfma_f32_16x16x32_f16 v[124:127], v[80:83], v[186:189], v[124:127]
	v_mfma_f32_16x16x32_f16 v[120:123], v[92:95], v[186:189], v[120:123]
	v_mfma_f32_16x16x32_f16 v[108:111], v[80:83], v[194:197], v[108:111]
	v_mfma_f32_16x16x32_f16 v[104:107], v[92:95], v[194:197], v[104:107]
	v_mfma_f32_16x16x32_f16 v[76:79], v[80:83], v[212:215], v[76:79]
	v_mfma_f32_16x16x32_f16 v[72:75], v[92:95], v[212:215], v[72:75]
	v_mfma_f32_16x16x32_f16 v[140:143], v[84:87], v[182:185], v[140:143]
	v_mfma_f32_16x16x32_f16 v[136:139], v[96:99], v[182:185], v[136:139]
	v_mfma_f32_16x16x32_f16 v[124:127], v[84:87], v[190:193], v[124:127]
	v_mfma_f32_16x16x32_f16 v[120:123], v[96:99], v[190:193], v[120:123]
	v_mfma_f32_16x16x32_f16 v[108:111], v[84:87], v[198:201], v[108:111]
	v_mfma_f32_16x16x32_f16 v[104:107], v[96:99], v[198:201], v[104:107]
	v_mfma_f32_16x16x32_f16 v[76:79], v[84:87], v[216:219], v[76:79]
	v_mfma_f32_16x16x32_f16 v[72:75], v[96:99], v[216:219], v[72:75]
	s_setprio 1
	s_setprio 0
	v_mfma_f32_16x16x32_f16 v[132:135], v[144:147], v[178:181], v[132:135]
	v_mfma_f32_16x16x32_f16 v[128:131], v[152:155], v[178:181], v[128:131]
	v_mfma_f32_16x16x32_f16 v[116:119], v[144:147], v[186:189], v[116:119]
	v_mfma_f32_16x16x32_f16 v[112:115], v[152:155], v[186:189], v[112:115]
	v_mfma_f32_16x16x32_f16 v[100:103], v[144:147], v[194:197], v[100:103]
	v_mfma_f32_16x16x32_f16 v[88:91], v[152:155], v[194:197], v[88:91]
	v_mfma_f32_16x16x32_f16 v[68:71], v[144:147], v[212:215], v[68:71]
	v_mfma_f32_16x16x32_f16 v[64:67], v[152:155], v[212:215], v[64:67]
	v_mfma_f32_16x16x32_f16 v[132:135], v[148:151], v[182:185], v[132:135]
	v_mfma_f32_16x16x32_f16 v[128:131], v[156:159], v[182:185], v[128:131]
	v_mfma_f32_16x16x32_f16 v[116:119], v[148:151], v[190:193], v[116:119]
	v_mfma_f32_16x16x32_f16 v[112:115], v[156:159], v[190:193], v[112:115]
	v_mfma_f32_16x16x32_f16 v[100:103], v[148:151], v[198:201], v[100:103]
	v_mfma_f32_16x16x32_f16 v[88:91], v[156:159], v[198:201], v[88:91]
	v_mfma_f32_16x16x32_f16 v[68:71], v[148:151], v[216:219], v[68:71]
	v_mfma_f32_16x16x32_f16 v[64:67], v[156:159], v[216:219], v[64:67]
	s_setprio 1
	s_barrier
	s_add_i32 s22, s64, s33
	v_lshl_add_u64 v[202:203], v[202:203], 0, s[16:17]
	s_mov_b32 m0, s22
	ds_read_b128 v[178:181], v210 offset:49152
	ds_read_b128 v[182:185], v210 offset:50176
	ds_read_b128 v[186:189], v210 offset:51200
	ds_read_b128 v[190:193], v210 offset:52224
	ds_read_b128 v[194:197], v210 offset:53248
	ds_read_b128 v[198:201], v210 offset:54272
	ds_read_b128 v[212:215], v210 offset:55296
	ds_read_b128 v[216:219], v210 offset:56320
	global_load_lds_dwordx4 v[202:203], off
	s_add_i32 m0, s22, 0x2000
	s_add_u32 s22, s26, 0xb0080
	v_lshl_add_u64 v[202:203], v[220:221], 0, s[16:17]
	s_addc_u32 s23, s27, 0
	s_add_i32 s26, s65, s33
	global_load_lds_dwordx4 v[202:203], off
	v_lshl_add_u64 v[202:203], s[22:23], 0, v[162:163]
	s_mov_b32 m0, s26
	s_nop 0
	global_load_lds_dwordx4 v[202:203], off
	v_lshl_add_u64 v[202:203], s[22:23], 0, v[166:167]
	s_add_i32 m0, s26, 0x2000
	s_nop 0
	global_load_lds_dwordx4 v[202:203], off
	v_lshl_add_u64 v[202:203], v[222:223], 0, s[16:17]
	s_mov_b32 m0, s51
	s_nop 0
	global_load_lds_dwordx4 v[202:203], off
	v_lshl_add_u64 v[202:203], v[224:225], 0, s[16:17]
	s_mov_b32 m0, s52
	s_nop 0
	global_load_lds_dwordx4 v[202:203], off
	s_waitcnt vmcnt(8)
	s_waitcnt lgkmcnt(0)
	s_barrier
	s_setprio 0
	s_waitcnt lgkmcnt(0)
	v_mfma_f32_16x16x32_f16 v[60:63], v[80:83], v[178:181], v[60:63]
	v_mfma_f32_16x16x32_f16 v[56:59], v[92:95], v[178:181], v[56:59]
	v_mfma_f32_16x16x32_f16 v[44:47], v[80:83], v[186:189], v[44:47]
	v_mfma_f32_16x16x32_f16 v[40:43], v[92:95], v[186:189], v[40:43]
	v_mfma_f32_16x16x32_f16 v[28:31], v[80:83], v[194:197], v[28:31]
	v_mfma_f32_16x16x32_f16 v[24:27], v[92:95], v[194:197], v[24:27]
	v_mfma_f32_16x16x32_f16 v[12:15], v[80:83], v[212:215], v[12:15]
	v_mfma_f32_16x16x32_f16 v[8:11], v[92:95], v[212:215], v[8:11]
	v_mfma_f32_16x16x32_f16 v[60:63], v[84:87], v[182:185], v[60:63]
	v_mfma_f32_16x16x32_f16 v[56:59], v[96:99], v[182:185], v[56:59]
	v_mfma_f32_16x16x32_f16 v[44:47], v[84:87], v[190:193], v[44:47]
	v_mfma_f32_16x16x32_f16 v[40:43], v[96:99], v[190:193], v[40:43]
	v_mfma_f32_16x16x32_f16 v[28:31], v[84:87], v[198:201], v[28:31]
	v_mfma_f32_16x16x32_f16 v[24:27], v[96:99], v[198:201], v[24:27]
	v_mfma_f32_16x16x32_f16 v[12:15], v[84:87], v[216:219], v[12:15]
	v_mfma_f32_16x16x32_f16 v[8:11], v[96:99], v[216:219], v[8:11]
	s_setprio 1
	s_setprio 0
	v_mfma_f32_16x16x32_f16 v[52:55], v[144:147], v[178:181], v[52:55]
	v_mfma_f32_16x16x32_f16 v[48:51], v[152:155], v[178:181], v[48:51]
	v_mfma_f32_16x16x32_f16 v[36:39], v[144:147], v[186:189], v[36:39]
	v_mfma_f32_16x16x32_f16 v[32:35], v[152:155], v[186:189], v[32:35]
	v_mfma_f32_16x16x32_f16 v[20:23], v[144:147], v[194:197], v[20:23]
	v_mfma_f32_16x16x32_f16 v[16:19], v[152:155], v[194:197], v[16:19]
	v_mfma_f32_16x16x32_f16 v[4:7], v[144:147], v[212:215], v[4:7]
	v_mfma_f32_16x16x32_f16 v[0:3], v[152:155], v[212:215], v[0:3]
	v_mfma_f32_16x16x32_f16 v[52:55], v[148:151], v[182:185], v[52:55]
	v_mfma_f32_16x16x32_f16 v[48:51], v[156:159], v[182:185], v[48:51]
	v_mfma_f32_16x16x32_f16 v[36:39], v[148:151], v[190:193], v[36:39]
	v_mfma_f32_16x16x32_f16 v[32:35], v[156:159], v[190:193], v[32:35]
	v_mfma_f32_16x16x32_f16 v[20:23], v[148:151], v[198:201], v[20:23]
	v_mfma_f32_16x16x32_f16 v[16:19], v[156:159], v[198:201], v[16:19]
	v_mfma_f32_16x16x32_f16 v[4:7], v[148:151], v[216:219], v[4:7]
	v_mfma_f32_16x16x32_f16 v[0:3], v[156:159], v[216:219], v[0:3]
	s_setprio 1
	s_barrier
	s_add_i32 s63, s63, 2
	s_add_u32 s61, s61, 0x100
	s_addc_u32 s62, s62, 0
	s_cmp_gt_u32 s63, 41
	s_mov_b64 s[22:23], s[24:25]
	s_cbranch_scc0 .LBB0_1220
	s_and_b64 vcc, exec, s[18:19]
	s_cbranch_vccz .LBB0_1223
	s_barrier

.LBB0_1333:
	ds_read_b128 v[128:131], v167
	ds_read_b128 v[132:135], v167 offset:1024
	ds_read_b128 v[136:139], v167 offset:2048
	ds_read_b128 v[140:143], v167 offset:3072
	ds_read_b128 v[160:163], v168
	ds_read_b128 v[172:175], v168 offset:1024
	ds_read_b128 v[178:181], v168 offset:2048
	ds_read_b128 v[182:185], v168 offset:3072
	s_add_u32 s48, s46, 0xfffc0080
	s_addc_u32 s49, s47, -1
	s_cmp_eq_u32 s76, 12
	s_cselect_b32 s51, s35, s49
	s_cselect_b32 s50, s72, s48
	s_cselect_b32 s49, s27, s75
	s_cselect_b32 s48, s73, s74
	v_lshl_add_u64 v[202:203], s[46:47], 0, v[152:153]
	s_add_i32 m0, s54, 0xc000
	ds_read_b128 v[186:189], v169
	ds_read_b128 v[190:193], v169 offset:1024
	ds_read_b128 v[194:197], v169 offset:2048
	ds_read_b128 v[198:201], v169 offset:3072
	ds_read_b128 v[206:209], v169 offset:4096
	ds_read_b128 v[210:213], v169 offset:5120
	ds_read_b128 v[214:217], v169 offset:6144
	ds_read_b128 v[218:221], v169 offset:7168
	global_load_lds_dwordx4 v[202:203], off
	v_lshl_add_u64 v[202:203], s[46:47], 0, v[154:155]
	s_add_i32 m0, s54, 0xe000
	s_nop 0
	global_load_lds_dwordx4 v[202:203], off
	s_waitcnt vmcnt(8)
	s_waitcnt lgkmcnt(0)
	s_barrier
	s_setprio 0
	s_waitcnt lgkmcnt(0)
	v_mfma_f32_16x16x32_f16 v[124:127], v[128:131], v[186:189], v[124:127]
	v_mfma_f32_16x16x32_f16 v[120:123], v[136:139], v[186:189], v[120:123]
	v_mfma_f32_16x16x32_f16 v[108:111], v[128:131], v[194:197], v[108:111]
	v_mfma_f32_16x16x32_f16 v[104:107], v[136:139], v[194:197], v[104:107]
	v_mfma_f32_16x16x32_f16 v[92:95], v[128:131], v[206:209], v[92:95]
	v_mfma_f32_16x16x32_f16 v[88:91], v[136:139], v[206:209], v[88:91]
	v_mfma_f32_16x16x32_f16 v[84:87], v[128:131], v[214:217], v[84:87]
	v_mfma_f32_16x16x32_f16 v[76:79], v[136:139], v[214:217], v[76:79]
	v_mfma_f32_16x16x32_f16 v[124:127], v[132:135], v[190:193], v[124:127]
	v_mfma_f32_16x16x32_f16 v[120:123], v[140:143], v[190:193], v[120:123]
	v_mfma_f32_16x16x32_f16 v[108:111], v[132:135], v[198:201], v[108:111]
	v_mfma_f32_16x16x32_f16 v[104:107], v[140:143], v[198:201], v[104:107]
	v_mfma_f32_16x16x32_f16 v[92:95], v[132:135], v[210:213], v[92:95]
	v_mfma_f32_16x16x32_f16 v[88:91], v[140:143], v[210:213], v[88:91]
	v_mfma_f32_16x16x32_f16 v[84:87], v[132:135], v[218:221], v[84:87]
	v_mfma_f32_16x16x32_f16 v[76:79], v[140:143], v[218:221], v[76:79]
	s_setprio 1
	s_setprio 0
	v_mfma_f32_16x16x32_f16 v[116:119], v[160:163], v[186:189], v[116:119]
	v_mfma_f32_16x16x32_f16 v[112:115], v[178:181], v[186:189], v[112:115]
	v_mfma_f32_16x16x32_f16 v[100:103], v[160:163], v[194:197], v[100:103]
	v_mfma_f32_16x16x32_f16 v[96:99], v[178:181], v[194:197], v[96:99]
	v_mfma_f32_16x16x32_f16 v[80:83], v[160:163], v[206:209], v[80:83]
	v_mfma_f32_16x16x32_f16 v[72:75], v[178:181], v[206:209], v[72:75]
	v_mfma_f32_16x16x32_f16 v[68:71], v[160:163], v[214:217], v[68:71]
	v_mfma_f32_16x16x32_f16 v[64:67], v[178:181], v[214:217], v[64:67]
	v_mfma_f32_16x16x32_f16 v[116:119], v[172:175], v[190:193], v[116:119]
	v_mfma_f32_16x16x32_f16 v[112:115], v[182:185], v[190:193], v[112:115]
	v_mfma_f32_16x16x32_f16 v[100:103], v[172:175], v[198:201], v[100:103]
	v_mfma_f32_16x16x32_f16 v[96:99], v[182:185], v[198:201], v[96:99]
	v_mfma_f32_16x16x32_f16 v[80:83], v[172:175], v[210:213], v[80:83]
	v_mfma_f32_16x16x32_f16 v[72:75], v[182:185], v[210:213], v[72:75]
	v_mfma_f32_16x16x32_f16 v[68:71], v[172:175], v[218:221], v[68:71]
	v_mfma_f32_16x16x32_f16 v[64:67], v[182:185], v[218:221], v[64:67]
	s_setprio 1
	s_barrier
	s_add_i32 s77, s64, s33
	v_lshl_add_u64 v[202:203], s[48:49], 0, v[148:149]
	s_mov_b32 m0, s77
	ds_read_b128 v[186:189], v169 offset:16384
	ds_read_b128 v[190:193], v169 offset:17408
	ds_read_b128 v[194:197], v169 offset:18432
	ds_read_b128 v[198:201], v169 offset:19456
	ds_read_b128 v[206:209], v169 offset:20480
	ds_read_b128 v[210:213], v169 offset:21504
	ds_read_b128 v[214:217], v169 offset:22528
	ds_read_b128 v[218:221], v169 offset:23552
	global_load_lds_dwordx4 v[202:203], off
	s_add_i32 m0, s77, 0x2000
	s_add_u32 s78, s48, 0x40000
	v_lshl_add_u64 v[222:223], s[48:49], 0, v[144:145]
	s_addc_u32 s79, s49, 0
	s_add_i32 s77, s65, s33
	global_load_lds_dwordx4 v[222:223], off
	v_lshl_add_u64 v[224:225], s[78:79], 0, v[148:149]
	s_mov_b32 m0, s77
	v_lshl_add_u64 v[226:227], s[50:51], 0, v[146:147]
	global_load_lds_dwordx4 v[224:225], off
	v_lshl_add_u64 v[224:225], s[78:79], 0, v[144:145]
	s_add_i32 m0, s77, 0x2000
	s_nop 0
	global_load_lds_dwordx4 v[224:225], off
	v_lshl_add_u64 v[224:225], s[50:51], 0, v[150:151]
	s_mov_b32 m0, s54
	s_nop 0
	global_load_lds_dwordx4 v[224:225], off
	s_mov_b32 m0, s55
	s_nop 0
	global_load_lds_dwordx4 v[226:227], off
	s_waitcnt vmcnt(8)
	s_waitcnt lgkmcnt(0)
	s_barrier
	s_setprio 0
	s_waitcnt lgkmcnt(0)
	v_mfma_f32_16x16x32_f16 v[60:63], v[128:131], v[186:189], v[60:63]
	v_mfma_f32_16x16x32_f16 v[56:59], v[136:139], v[186:189], v[56:59]
	v_mfma_f32_16x16x32_f16 v[44:47], v[128:131], v[194:197], v[44:47]
	v_mfma_f32_16x16x32_f16 v[40:43], v[136:139], v[194:197], v[40:43]
	v_mfma_f32_16x16x32_f16 v[28:31], v[128:131], v[206:209], v[28:31]
	v_mfma_f32_16x16x32_f16 v[24:27], v[136:139], v[206:209], v[24:27]
	v_mfma_f32_16x16x32_f16 v[12:15], v[128:131], v[214:217], v[12:15]
	v_mfma_f32_16x16x32_f16 v[8:11], v[136:139], v[214:217], v[8:11]
	v_mfma_f32_16x16x32_f16 v[60:63], v[132:135], v[190:193], v[60:63]
	v_mfma_f32_16x16x32_f16 v[56:59], v[140:143], v[190:193], v[56:59]
	v_mfma_f32_16x16x32_f16 v[44:47], v[132:135], v[198:201], v[44:47]
	v_mfma_f32_16x16x32_f16 v[40:43], v[140:143], v[198:201], v[40:43]
	v_mfma_f32_16x16x32_f16 v[28:31], v[132:135], v[210:213], v[28:31]
	v_mfma_f32_16x16x32_f16 v[24:27], v[140:143], v[210:213], v[24:27]
	v_mfma_f32_16x16x32_f16 v[12:15], v[132:135], v[218:221], v[12:15]
	v_mfma_f32_16x16x32_f16 v[8:11], v[140:143], v[218:221], v[8:11]
	s_setprio 1
	s_setprio 0
	v_mfma_f32_16x16x32_f16 v[52:55], v[160:163], v[186:189], v[52:55]
	v_mfma_f32_16x16x32_f16 v[48:51], v[178:181], v[186:189], v[48:51]
	v_mfma_f32_16x16x32_f16 v[36:39], v[160:163], v[194:197], v[36:39]
	v_mfma_f32_16x16x32_f16 v[32:35], v[178:181], v[194:197], v[32:35]
	v_mfma_f32_16x16x32_f16 v[20:23], v[160:163], v[206:209], v[20:23]
	v_mfma_f32_16x16x32_f16 v[16:19], v[178:181], v[206:209], v[16:19]
	v_mfma_f32_16x16x32_f16 v[4:7], v[160:163], v[214:217], v[4:7]
	v_mfma_f32_16x16x32_f16 v[0:3], v[178:181], v[214:217], v[0:3]
	v_mfma_f32_16x16x32_f16 v[52:55], v[172:175], v[190:193], v[52:55]
	v_mfma_f32_16x16x32_f16 v[48:51], v[182:185], v[190:193], v[48:51]
	v_mfma_f32_16x16x32_f16 v[36:39], v[172:175], v[198:201], v[36:39]
	v_mfma_f32_16x16x32_f16 v[32:35], v[182:185], v[198:201], v[32:35]
	v_mfma_f32_16x16x32_f16 v[20:23], v[172:175], v[210:213], v[20:23]
	v_mfma_f32_16x16x32_f16 v[16:19], v[182:185], v[210:213], v[16:19]
	v_mfma_f32_16x16x32_f16 v[4:7], v[172:175], v[218:221], v[4:7]
	v_mfma_f32_16x16x32_f16 v[0:3], v[182:185], v[218:221], v[0:3]
	s_setprio 1
	s_barrier
	s_add_i32 s77, 0, 0x18000
	s_add_i32 s78, 0, 0x1c000
	v_add_u32_e32 v140, s77, v165
	v_add_u32_e32 v177, s78, v165
	ds_read_b128 v[128:131], v140
	ds_read_b128 v[132:135], v140 offset:1024
	ds_read_b128 v[136:139], v140 offset:2048
	ds_read_b128 v[140:143], v140 offset:3072
	ds_read_b128 v[160:163], v177
	ds_read_b128 v[172:175], v177 offset:1024
	ds_read_b128 v[178:181], v177 offset:2048
	ds_read_b128 v[182:185], v177 offset:3072
	s_add_u32 s50, s50, 0x40000
	s_addc_u32 s51, s51, 0
	s_mov_b32 m0, s56
	v_lshl_add_u64 v[228:229], s[50:51], 0, v[150:151]
	ds_read_b128 v[186:189], v169 offset:32768
	ds_read_b128 v[190:193], v169 offset:33792
	ds_read_b128 v[194:197], v169 offset:34816
	ds_read_b128 v[198:201], v169 offset:35840
	ds_read_b128 v[206:209], v169 offset:36864
	ds_read_b128 v[210:213], v169 offset:37888
	ds_read_b128 v[214:217], v169 offset:38912
	ds_read_b128 v[218:221], v169 offset:39936
	global_load_lds_dwordx4 v[228:229], off
	v_lshl_add_u64 v[228:229], s[50:51], 0, v[146:147]
	s_mov_b32 m0, s57
	s_nop 0
	global_load_lds_dwordx4 v[228:229], off
	s_waitcnt vmcnt(8)
	s_waitcnt lgkmcnt(0)
	s_barrier
	s_setprio 0
	s_waitcnt lgkmcnt(0)
	v_mfma_f32_16x16x32_f16 v[124:127], v[128:131], v[186:189], v[124:127]
	v_mfma_f32_16x16x32_f16 v[120:123], v[136:139], v[186:189], v[120:123]
	v_mfma_f32_16x16x32_f16 v[108:111], v[128:131], v[194:197], v[108:111]
	v_mfma_f32_16x16x32_f16 v[104:107], v[136:139], v[194:197], v[104:107]
	v_mfma_f32_16x16x32_f16 v[92:95], v[128:131], v[206:209], v[92:95]
	v_mfma_f32_16x16x32_f16 v[88:91], v[136:139], v[206:209], v[88:91]
	v_mfma_f32_16x16x32_f16 v[84:87], v[128:131], v[214:217], v[84:87]
	v_mfma_f32_16x16x32_f16 v[76:79], v[136:139], v[214:217], v[76:79]
	v_mfma_f32_16x16x32_f16 v[124:127], v[132:135], v[190:193], v[124:127]
	v_mfma_f32_16x16x32_f16 v[120:123], v[140:143], v[190:193], v[120:123]
	v_mfma_f32_16x16x32_f16 v[108:111], v[132:135], v[198:201], v[108:111]
	v_mfma_f32_16x16x32_f16 v[104:107], v[140:143], v[198:201], v[104:107]
	v_mfma_f32_16x16x32_f16 v[92:95], v[132:135], v[210:213], v[92:95]
	v_mfma_f32_16x16x32_f16 v[88:91], v[140:143], v[210:213], v[88:91]
	v_mfma_f32_16x16x32_f16 v[84:87], v[132:135], v[218:221], v[84:87]
	v_mfma_f32_16x16x32_f16 v[76:79], v[140:143], v[218:221], v[76:79]
	s_setprio 1
	s_setprio 0
	v_mfma_f32_16x16x32_f16 v[116:119], v[160:163], v[186:189], v[116:119]
	v_mfma_f32_16x16x32_f16 v[112:115], v[178:181], v[186:189], v[112:115]
	v_mfma_f32_16x16x32_f16 v[100:103], v[160:163], v[194:197], v[100:103]
	v_mfma_f32_16x16x32_f16 v[96:99], v[178:181], v[194:197], v[96:99]
	v_mfma_f32_16x16x32_f16 v[80:83], v[160:163], v[206:209], v[80:83]
	v_mfma_f32_16x16x32_f16 v[72:75], v[178:181], v[206:209], v[72:75]
	v_mfma_f32_16x16x32_f16 v[68:71], v[160:163], v[214:217], v[68:71]
	v_mfma_f32_16x16x32_f16 v[64:67], v[178:181], v[214:217], v[64:67]
	v_mfma_f32_16x16x32_f16 v[116:119], v[172:175], v[190:193], v[116:119]
	v_mfma_f32_16x16x32_f16 v[112:115], v[182:185], v[190:193], v[112:115]
	v_mfma_f32_16x16x32_f16 v[100:103], v[172:175], v[198:201], v[100:103]
	v_mfma_f32_16x16x32_f16 v[96:99], v[182:185], v[198:201], v[96:99]
	v_mfma_f32_16x16x32_f16 v[80:83], v[172:175], v[210:213], v[80:83]
	v_mfma_f32_16x16x32_f16 v[72:75], v[182:185], v[210:213], v[72:75]
	v_mfma_f32_16x16x32_f16 v[68:71], v[172:175], v[218:221], v[68:71]
	v_mfma_f32_16x16x32_f16 v[64:67], v[182:185], v[218:221], v[64:67]
	s_setprio 1
	s_barrier
	s_add_i32 s50, s77, s33
	v_lshl_add_u64 v[202:203], v[202:203], 0, s[12:13]
	s_mov_b32 m0, s50
	ds_read_b128 v[186:189], v169 offset:49152
	ds_read_b128 v[190:193], v169 offset:50176
	ds_read_b128 v[194:197], v169 offset:51200
	ds_read_b128 v[198:201], v169 offset:52224
	ds_read_b128 v[206:209], v169 offset:53248
	ds_read_b128 v[210:213], v169 offset:54272
	ds_read_b128 v[214:217], v169 offset:55296
	ds_read_b128 v[218:221], v169 offset:56320
	global_load_lds_dwordx4 v[202:203], off
	s_add_i32 m0, s50, 0x2000
	s_add_u32 s48, s48, 0x40080
	v_lshl_add_u64 v[202:203], v[222:223], 0, s[12:13]
	s_addc_u32 s49, s49, 0
	s_add_i32 s50, s78, s33
	global_load_lds_dwordx4 v[202:203], off
	v_lshl_add_u64 v[202:203], s[48:49], 0, v[148:149]
	s_mov_b32 m0, s50
	s_nop 0
	global_load_lds_dwordx4 v[202:203], off
	v_lshl_add_u64 v[202:203], s[48:49], 0, v[144:145]
	s_add_i32 m0, s50, 0x2000
	s_nop 0
	global_load_lds_dwordx4 v[202:203], off
	v_lshl_add_u64 v[202:203], v[224:225], 0, s[12:13]
	s_mov_b32 m0, s61
	s_nop 0
	global_load_lds_dwordx4 v[202:203], off
	v_lshl_add_u64 v[202:203], v[226:227], 0, s[12:13]
	s_mov_b32 m0, s62
	s_nop 0
	global_load_lds_dwordx4 v[202:203], off
	s_waitcnt vmcnt(8)
	s_waitcnt lgkmcnt(0)
	s_barrier
	s_setprio 0
	s_waitcnt lgkmcnt(0)
	v_mfma_f32_16x16x32_f16 v[60:63], v[128:131], v[186:189], v[60:63]
	v_mfma_f32_16x16x32_f16 v[56:59], v[136:139], v[186:189], v[56:59]
	v_mfma_f32_16x16x32_f16 v[44:47], v[128:131], v[194:197], v[44:47]
	v_mfma_f32_16x16x32_f16 v[40:43], v[136:139], v[194:197], v[40:43]
	v_mfma_f32_16x16x32_f16 v[28:31], v[128:131], v[206:209], v[28:31]
	v_mfma_f32_16x16x32_f16 v[24:27], v[136:139], v[206:209], v[24:27]
	v_mfma_f32_16x16x32_f16 v[12:15], v[128:131], v[214:217], v[12:15]
	v_mfma_f32_16x16x32_f16 v[8:11], v[136:139], v[214:217], v[8:11]
	v_mfma_f32_16x16x32_f16 v[60:63], v[132:135], v[190:193], v[60:63]
	v_mfma_f32_16x16x32_f16 v[56:59], v[140:143], v[190:193], v[56:59]
	v_mfma_f32_16x16x32_f16 v[44:47], v[132:135], v[198:201], v[44:47]
	v_mfma_f32_16x16x32_f16 v[40:43], v[140:143], v[198:201], v[40:43]
	v_mfma_f32_16x16x32_f16 v[28:31], v[132:135], v[210:213], v[28:31]
	v_mfma_f32_16x16x32_f16 v[24:27], v[140:143], v[210:213], v[24:27]
	v_mfma_f32_16x16x32_f16 v[12:15], v[132:135], v[218:221], v[12:15]
	v_mfma_f32_16x16x32_f16 v[8:11], v[140:143], v[218:221], v[8:11]
	s_setprio 1
	s_setprio 0
	v_mfma_f32_16x16x32_f16 v[52:55], v[160:163], v[186:189], v[52:55]
	v_mfma_f32_16x16x32_f16 v[48:51], v[178:181], v[186:189], v[48:51]
	v_mfma_f32_16x16x32_f16 v[36:39], v[160:163], v[194:197], v[36:39]
	v_mfma_f32_16x16x32_f16 v[32:35], v[178:181], v[194:197], v[32:35]
	v_mfma_f32_16x16x32_f16 v[20:23], v[160:163], v[206:209], v[20:23]
	v_mfma_f32_16x16x32_f16 v[16:19], v[178:181], v[206:209], v[16:19]
	v_mfma_f32_16x16x32_f16 v[4:7], v[160:163], v[214:217], v[4:7]
	v_mfma_f32_16x16x32_f16 v[0:3], v[178:181], v[214:217], v[0:3]
	v_mfma_f32_16x16x32_f16 v[52:55], v[172:175], v[190:193], v[52:55]
	v_mfma_f32_16x16x32_f16 v[48:51], v[182:185], v[190:193], v[48:51]
	v_mfma_f32_16x16x32_f16 v[36:39], v[172:175], v[198:201], v[36:39]
	v_mfma_f32_16x16x32_f16 v[32:35], v[182:185], v[198:201], v[32:35]
	v_mfma_f32_16x16x32_f16 v[20:23], v[172:175], v[210:213], v[20:23]
	v_mfma_f32_16x16x32_f16 v[16:19], v[182:185], v[210:213], v[16:19]
	v_mfma_f32_16x16x32_f16 v[4:7], v[172:175], v[218:221], v[4:7]
	v_mfma_f32_16x16x32_f16 v[0:3], v[182:185], v[218:221], v[0:3]
	s_setprio 1
	s_barrier
	s_add_i32 s76, s76, 2
	s_add_u32 s46, s46, 0x100
	s_addc_u32 s47, s47, 0
	s_add_u32 s74, s74, 0x100
	s_addc_u32 s75, s75, 0
	s_cmp_gt_u32 s76, 13
	s_cbranch_scc0 .LBB0_1333
	s_and_b64 vcc, exec, s[14:15]
	s_cbranch_vccz .LBB0_1336
	s_barrier

.LBB0_1498:
	ds_read_b128 v[80:83], v208
	ds_read_b128 v[84:87], v208 offset:1024
	ds_read_b128 v[88:91], v208 offset:2048
	ds_read_b128 v[92:95], v208 offset:3072
	ds_read_b128 v[96:99], v209
	ds_read_b128 v[104:107], v209 offset:1024
	ds_read_b128 v[108:111], v209 offset:2048
	ds_read_b128 v[112:115], v209 offset:3072
	s_add_u32 s40, s34, 0xfffc0080
	s_addc_u32 s41, s35, -1
	s_cmp_eq_u32 s65, 12
	s_cselect_b32 s45, s19, s41
	s_cselect_b32 s44, s25, s40
	s_cselect_b32 s41, s17, s64
	s_cselect_b32 s40, s62, s63
	v_lshl_add_u64 v[202:203], s[34:35], 0, v[186:187]
	s_add_i32 m0, s27, 0xc000
	ds_read_b128 v[160:163], v210
	ds_read_b128 v[164:167], v210 offset:1024
	ds_read_b128 v[168:171], v210 offset:2048
	ds_read_b128 v[172:175], v210 offset:3072
	ds_read_b128 v[194:197], v210 offset:4096
	ds_read_b128 v[198:201], v210 offset:5120
	ds_read_b128 v[212:215], v210 offset:6144
	ds_read_b128 v[216:219], v210 offset:7168
	global_load_lds_dwordx4 v[202:203], off
	v_lshl_add_u64 v[202:203], s[34:35], 0, v[188:189]
	s_add_i32 m0, s27, 0xe000
	s_nop 0
	global_load_lds_dwordx4 v[202:203], off
	s_waitcnt vmcnt(8)
	s_waitcnt lgkmcnt(0)
	s_barrier
	s_setprio 0
	s_waitcnt lgkmcnt(0)
	v_mfma_f32_16x16x32_f16 v[156:159], v[80:83], v[160:163], v[156:159]
	v_mfma_f32_16x16x32_f16 v[152:155], v[88:91], v[160:163], v[152:155]
	v_mfma_f32_16x16x32_f16 v[140:143], v[80:83], v[168:171], v[140:143]
	v_mfma_f32_16x16x32_f16 v[136:139], v[88:91], v[168:171], v[136:139]
	v_mfma_f32_16x16x32_f16 v[124:127], v[80:83], v[194:197], v[124:127]
	v_mfma_f32_16x16x32_f16 v[120:123], v[88:91], v[194:197], v[120:123]
	v_mfma_f32_16x16x32_f16 v[76:79], v[80:83], v[212:215], v[76:79]
	v_mfma_f32_16x16x32_f16 v[72:75], v[88:91], v[212:215], v[72:75]
	v_mfma_f32_16x16x32_f16 v[156:159], v[84:87], v[164:167], v[156:159]
	v_mfma_f32_16x16x32_f16 v[152:155], v[92:95], v[164:167], v[152:155]
	v_mfma_f32_16x16x32_f16 v[140:143], v[84:87], v[172:175], v[140:143]
	v_mfma_f32_16x16x32_f16 v[136:139], v[92:95], v[172:175], v[136:139]
	v_mfma_f32_16x16x32_f16 v[124:127], v[84:87], v[198:201], v[124:127]
	v_mfma_f32_16x16x32_f16 v[120:123], v[92:95], v[198:201], v[120:123]
	v_mfma_f32_16x16x32_f16 v[76:79], v[84:87], v[216:219], v[76:79]
	v_mfma_f32_16x16x32_f16 v[72:75], v[92:95], v[216:219], v[72:75]
	s_setprio 1
	s_setprio 0
	v_mfma_f32_16x16x32_f16 v[148:151], v[96:99], v[160:163], v[148:151]
	v_mfma_f32_16x16x32_f16 v[144:147], v[108:111], v[160:163], v[144:147]
	v_mfma_f32_16x16x32_f16 v[132:135], v[96:99], v[168:171], v[132:135]
	v_mfma_f32_16x16x32_f16 v[128:131], v[108:111], v[168:171], v[128:131]
	v_mfma_f32_16x16x32_f16 v[116:119], v[96:99], v[194:197], v[116:119]
	v_mfma_f32_16x16x32_f16 v[100:103], v[108:111], v[194:197], v[100:103]
	v_mfma_f32_16x16x32_f16 v[68:71], v[96:99], v[212:215], v[68:71]
	v_mfma_f32_16x16x32_f16 v[64:67], v[108:111], v[212:215], v[64:67]
	v_mfma_f32_16x16x32_f16 v[148:151], v[104:107], v[164:167], v[148:151]
	v_mfma_f32_16x16x32_f16 v[144:147], v[112:115], v[164:167], v[144:147]
	v_mfma_f32_16x16x32_f16 v[132:135], v[104:107], v[172:175], v[132:135]
	v_mfma_f32_16x16x32_f16 v[128:131], v[112:115], v[172:175], v[128:131]
	v_mfma_f32_16x16x32_f16 v[116:119], v[104:107], v[198:201], v[116:119]
	v_mfma_f32_16x16x32_f16 v[100:103], v[112:115], v[198:201], v[100:103]
	v_mfma_f32_16x16x32_f16 v[68:71], v[104:107], v[216:219], v[68:71]
	v_mfma_f32_16x16x32_f16 v[64:67], v[112:115], v[216:219], v[64:67]
	s_setprio 1
	s_barrier
	s_add_i32 s66, s60, s47
	v_lshl_add_u64 v[202:203], s[40:41], 0, v[180:181]
	s_mov_b32 m0, s66
	ds_read_b128 v[160:163], v210 offset:16384
	ds_read_b128 v[164:167], v210 offset:17408
	ds_read_b128 v[168:171], v210 offset:18432
	ds_read_b128 v[172:175], v210 offset:19456
	ds_read_b128 v[194:197], v210 offset:20480
	ds_read_b128 v[198:201], v210 offset:21504
	ds_read_b128 v[212:215], v210 offset:22528
	ds_read_b128 v[216:219], v210 offset:23552
	global_load_lds_dwordx4 v[202:203], off
	s_add_i32 m0, s66, 0x2000
	s_add_u32 s66, s40, 0x40000
	v_lshl_add_u64 v[220:221], s[40:41], 0, v[184:185]
	s_addc_u32 s67, s41, 0
	s_add_i32 s68, s61, s47
	global_load_lds_dwordx4 v[220:221], off
	v_lshl_add_u64 v[222:223], s[66:67], 0, v[180:181]
	s_mov_b32 m0, s68
	v_lshl_add_u64 v[224:225], s[44:45], 0, v[182:183]
	global_load_lds_dwordx4 v[222:223], off
	v_lshl_add_u64 v[222:223], s[66:67], 0, v[184:185]
	s_add_i32 m0, s68, 0x2000
	s_nop 0
	global_load_lds_dwordx4 v[222:223], off
	v_lshl_add_u64 v[222:223], s[44:45], 0, v[178:179]
	s_mov_b32 m0, s27
	s_nop 0
	global_load_lds_dwordx4 v[222:223], off
	s_mov_b32 m0, s48
	s_nop 0
	global_load_lds_dwordx4 v[224:225], off
	s_waitcnt vmcnt(8)
	s_waitcnt lgkmcnt(0)
	s_barrier
	s_setprio 0
	s_waitcnt lgkmcnt(0)
	v_mfma_f32_16x16x32_f16 v[60:63], v[80:83], v[160:163], v[60:63]
	v_mfma_f32_16x16x32_f16 v[56:59], v[88:91], v[160:163], v[56:59]
	v_mfma_f32_16x16x32_f16 v[44:47], v[80:83], v[168:171], v[44:47]
	v_mfma_f32_16x16x32_f16 v[40:43], v[88:91], v[168:171], v[40:43]
	v_mfma_f32_16x16x32_f16 v[28:31], v[80:83], v[194:197], v[28:31]
	v_mfma_f32_16x16x32_f16 v[24:27], v[88:91], v[194:197], v[24:27]
	v_mfma_f32_16x16x32_f16 v[12:15], v[80:83], v[212:215], v[12:15]
	v_mfma_f32_16x16x32_f16 v[8:11], v[88:91], v[212:215], v[8:11]
	v_mfma_f32_16x16x32_f16 v[60:63], v[84:87], v[164:167], v[60:63]
	v_mfma_f32_16x16x32_f16 v[56:59], v[92:95], v[164:167], v[56:59]
	v_mfma_f32_16x16x32_f16 v[44:47], v[84:87], v[172:175], v[44:47]
	v_mfma_f32_16x16x32_f16 v[40:43], v[92:95], v[172:175], v[40:43]
	v_mfma_f32_16x16x32_f16 v[28:31], v[84:87], v[198:201], v[28:31]
	v_mfma_f32_16x16x32_f16 v[24:27], v[92:95], v[198:201], v[24:27]
	v_mfma_f32_16x16x32_f16 v[12:15], v[84:87], v[216:219], v[12:15]
	v_mfma_f32_16x16x32_f16 v[8:11], v[92:95], v[216:219], v[8:11]
	s_setprio 1
	s_setprio 0
	v_mfma_f32_16x16x32_f16 v[52:55], v[96:99], v[160:163], v[52:55]
	v_mfma_f32_16x16x32_f16 v[48:51], v[108:111], v[160:163], v[48:51]
	v_mfma_f32_16x16x32_f16 v[36:39], v[96:99], v[168:171], v[36:39]
	v_mfma_f32_16x16x32_f16 v[32:35], v[108:111], v[168:171], v[32:35]
	v_mfma_f32_16x16x32_f16 v[20:23], v[96:99], v[194:197], v[20:23]
	v_mfma_f32_16x16x32_f16 v[16:19], v[108:111], v[194:197], v[16:19]
	v_mfma_f32_16x16x32_f16 v[4:7], v[96:99], v[212:215], v[4:7]
	v_mfma_f32_16x16x32_f16 v[0:3], v[108:111], v[212:215], v[0:3]
	v_mfma_f32_16x16x32_f16 v[52:55], v[104:107], v[164:167], v[52:55]
	v_mfma_f32_16x16x32_f16 v[48:51], v[112:115], v[164:167], v[48:51]
	v_mfma_f32_16x16x32_f16 v[36:39], v[104:107], v[172:175], v[36:39]
	v_mfma_f32_16x16x32_f16 v[32:35], v[112:115], v[172:175], v[32:35]
	v_mfma_f32_16x16x32_f16 v[20:23], v[104:107], v[198:201], v[20:23]
	v_mfma_f32_16x16x32_f16 v[16:19], v[112:115], v[198:201], v[16:19]
	v_mfma_f32_16x16x32_f16 v[4:7], v[104:107], v[216:219], v[4:7]
	v_mfma_f32_16x16x32_f16 v[0:3], v[112:115], v[216:219], v[0:3]
	s_setprio 1
	s_barrier
	s_add_i32 s66, 0, 0x18000
	s_add_i32 s67, 0, 0x1c000
	v_add_u32_e32 v92, s66, v206
	v_add_u32_e32 v112, s67, v206
	ds_read_b128 v[80:83], v92
	ds_read_b128 v[84:87], v92 offset:1024
	ds_read_b128 v[88:91], v92 offset:2048
	ds_read_b128 v[92:95], v92 offset:3072
	ds_read_b128 v[96:99], v112
	ds_read_b128 v[104:107], v112 offset:1024
	ds_read_b128 v[108:111], v112 offset:2048
	ds_read_b128 v[112:115], v112 offset:3072
	s_add_u32 s44, s44, 0x40000
	s_addc_u32 s45, s45, 0
	s_mov_b32 m0, s49
	v_lshl_add_u64 v[226:227], s[44:45], 0, v[178:179]
	ds_read_b128 v[160:163], v210 offset:32768
	ds_read_b128 v[164:167], v210 offset:33792
	ds_read_b128 v[168:171], v210 offset:34816
	ds_read_b128 v[172:175], v210 offset:35840
	ds_read_b128 v[194:197], v210 offset:36864
	ds_read_b128 v[198:201], v210 offset:37888
	ds_read_b128 v[212:215], v210 offset:38912
	ds_read_b128 v[216:219], v210 offset:39936
	global_load_lds_dwordx4 v[226:227], off
	v_lshl_add_u64 v[226:227], s[44:45], 0, v[182:183]
	s_mov_b32 m0, s50
	s_nop 0
	global_load_lds_dwordx4 v[226:227], off
	s_waitcnt vmcnt(8)
	s_waitcnt lgkmcnt(0)
	s_barrier
	s_setprio 0
	s_waitcnt lgkmcnt(0)
	v_mfma_f32_16x16x32_f16 v[156:159], v[80:83], v[160:163], v[156:159]
	v_mfma_f32_16x16x32_f16 v[152:155], v[88:91], v[160:163], v[152:155]
	v_mfma_f32_16x16x32_f16 v[140:143], v[80:83], v[168:171], v[140:143]
	v_mfma_f32_16x16x32_f16 v[136:139], v[88:91], v[168:171], v[136:139]
	v_mfma_f32_16x16x32_f16 v[124:127], v[80:83], v[194:197], v[124:127]
	v_mfma_f32_16x16x32_f16 v[120:123], v[88:91], v[194:197], v[120:123]
	v_mfma_f32_16x16x32_f16 v[76:79], v[80:83], v[212:215], v[76:79]
	v_mfma_f32_16x16x32_f16 v[72:75], v[88:91], v[212:215], v[72:75]
	v_mfma_f32_16x16x32_f16 v[156:159], v[84:87], v[164:167], v[156:159]
	v_mfma_f32_16x16x32_f16 v[152:155], v[92:95], v[164:167], v[152:155]
	v_mfma_f32_16x16x32_f16 v[140:143], v[84:87], v[172:175], v[140:143]
	v_mfma_f32_16x16x32_f16 v[136:139], v[92:95], v[172:175], v[136:139]
	v_mfma_f32_16x16x32_f16 v[124:127], v[84:87], v[198:201], v[124:127]
	v_mfma_f32_16x16x32_f16 v[120:123], v[92:95], v[198:201], v[120:123]
	v_mfma_f32_16x16x32_f16 v[76:79], v[84:87], v[216:219], v[76:79]
	v_mfma_f32_16x16x32_f16 v[72:75], v[92:95], v[216:219], v[72:75]
	s_setprio 1
	s_setprio 0
	v_mfma_f32_16x16x32_f16 v[148:151], v[96:99], v[160:163], v[148:151]
	v_mfma_f32_16x16x32_f16 v[144:147], v[108:111], v[160:163], v[144:147]
	v_mfma_f32_16x16x32_f16 v[132:135], v[96:99], v[168:171], v[132:135]
	v_mfma_f32_16x16x32_f16 v[128:131], v[108:111], v[168:171], v[128:131]
	v_mfma_f32_16x16x32_f16 v[116:119], v[96:99], v[194:197], v[116:119]
	v_mfma_f32_16x16x32_f16 v[100:103], v[108:111], v[194:197], v[100:103]
	v_mfma_f32_16x16x32_f16 v[68:71], v[96:99], v[212:215], v[68:71]
	v_mfma_f32_16x16x32_f16 v[64:67], v[108:111], v[212:215], v[64:67]
	v_mfma_f32_16x16x32_f16 v[148:151], v[104:107], v[164:167], v[148:151]
	v_mfma_f32_16x16x32_f16 v[144:147], v[112:115], v[164:167], v[144:147]
	v_mfma_f32_16x16x32_f16 v[132:135], v[104:107], v[172:175], v[132:135]
	v_mfma_f32_16x16x32_f16 v[128:131], v[112:115], v[172:175], v[128:131]
	v_mfma_f32_16x16x32_f16 v[116:119], v[104:107], v[198:201], v[116:119]
	v_mfma_f32_16x16x32_f16 v[100:103], v[112:115], v[198:201], v[100:103]
	v_mfma_f32_16x16x32_f16 v[68:71], v[104:107], v[216:219], v[68:71]
	v_mfma_f32_16x16x32_f16 v[64:67], v[112:115], v[216:219], v[64:67]
	s_setprio 1
	s_barrier
	s_add_i32 s44, s66, s47
	v_lshl_add_u64 v[202:203], v[202:203], 0, s[12:13]
	s_mov_b32 m0, s44
	ds_read_b128 v[160:163], v210 offset:49152
	ds_read_b128 v[164:167], v210 offset:50176
	ds_read_b128 v[168:171], v210 offset:51200
	ds_read_b128 v[172:175], v210 offset:52224
	ds_read_b128 v[194:197], v210 offset:53248
	ds_read_b128 v[198:201], v210 offset:54272
	ds_read_b128 v[212:215], v210 offset:55296
	ds_read_b128 v[216:219], v210 offset:56320
	global_load_lds_dwordx4 v[202:203], off
	s_add_i32 m0, s44, 0x2000
	s_add_u32 s40, s40, 0x40080
	v_lshl_add_u64 v[202:203], v[220:221], 0, s[12:13]
	s_addc_u32 s41, s41, 0
	s_add_i32 s44, s67, s47
	global_load_lds_dwordx4 v[202:203], off
	v_lshl_add_u64 v[202:203], s[40:41], 0, v[180:181]
	s_mov_b32 m0, s44
	s_nop 0
	global_load_lds_dwordx4 v[202:203], off
	v_lshl_add_u64 v[202:203], s[40:41], 0, v[184:185]
	s_add_i32 m0, s44, 0x2000
	s_nop 0
	global_load_lds_dwordx4 v[202:203], off
	v_lshl_add_u64 v[202:203], v[222:223], 0, s[12:13]
	s_mov_b32 m0, s56
	s_nop 0
	global_load_lds_dwordx4 v[202:203], off
	v_lshl_add_u64 v[202:203], v[224:225], 0, s[12:13]
	s_mov_b32 m0, s57
	s_nop 0
	global_load_lds_dwordx4 v[202:203], off
	s_waitcnt vmcnt(8)
	s_waitcnt lgkmcnt(0)
	s_barrier
	s_setprio 0
	s_waitcnt lgkmcnt(0)
	v_mfma_f32_16x16x32_f16 v[60:63], v[80:83], v[160:163], v[60:63]
	v_mfma_f32_16x16x32_f16 v[56:59], v[88:91], v[160:163], v[56:59]
	v_mfma_f32_16x16x32_f16 v[44:47], v[80:83], v[168:171], v[44:47]
	v_mfma_f32_16x16x32_f16 v[40:43], v[88:91], v[168:171], v[40:43]
	v_mfma_f32_16x16x32_f16 v[28:31], v[80:83], v[194:197], v[28:31]
	v_mfma_f32_16x16x32_f16 v[24:27], v[88:91], v[194:197], v[24:27]
	v_mfma_f32_16x16x32_f16 v[12:15], v[80:83], v[212:215], v[12:15]
	v_mfma_f32_16x16x32_f16 v[8:11], v[88:91], v[212:215], v[8:11]
	v_mfma_f32_16x16x32_f16 v[60:63], v[84:87], v[164:167], v[60:63]
	v_mfma_f32_16x16x32_f16 v[56:59], v[92:95], v[164:167], v[56:59]
	v_mfma_f32_16x16x32_f16 v[44:47], v[84:87], v[172:175], v[44:47]
	v_mfma_f32_16x16x32_f16 v[40:43], v[92:95], v[172:175], v[40:43]
	v_mfma_f32_16x16x32_f16 v[28:31], v[84:87], v[198:201], v[28:31]
	v_mfma_f32_16x16x32_f16 v[24:27], v[92:95], v[198:201], v[24:27]
	v_mfma_f32_16x16x32_f16 v[12:15], v[84:87], v[216:219], v[12:15]
	v_mfma_f32_16x16x32_f16 v[8:11], v[92:95], v[216:219], v[8:11]
	s_setprio 1
	s_setprio 0
	v_mfma_f32_16x16x32_f16 v[52:55], v[96:99], v[160:163], v[52:55]
	v_mfma_f32_16x16x32_f16 v[48:51], v[108:111], v[160:163], v[48:51]
	v_mfma_f32_16x16x32_f16 v[36:39], v[96:99], v[168:171], v[36:39]
	v_mfma_f32_16x16x32_f16 v[32:35], v[108:111], v[168:171], v[32:35]
	v_mfma_f32_16x16x32_f16 v[20:23], v[96:99], v[194:197], v[20:23]
	v_mfma_f32_16x16x32_f16 v[16:19], v[108:111], v[194:197], v[16:19]
	v_mfma_f32_16x16x32_f16 v[4:7], v[96:99], v[212:215], v[4:7]
	v_mfma_f32_16x16x32_f16 v[0:3], v[108:111], v[212:215], v[0:3]
	v_mfma_f32_16x16x32_f16 v[52:55], v[104:107], v[164:167], v[52:55]
	v_mfma_f32_16x16x32_f16 v[48:51], v[112:115], v[164:167], v[48:51]
	v_mfma_f32_16x16x32_f16 v[36:39], v[104:107], v[172:175], v[36:39]
	v_mfma_f32_16x16x32_f16 v[32:35], v[112:115], v[172:175], v[32:35]
	v_mfma_f32_16x16x32_f16 v[20:23], v[104:107], v[198:201], v[20:23]
	v_mfma_f32_16x16x32_f16 v[16:19], v[112:115], v[198:201], v[16:19]
	v_mfma_f32_16x16x32_f16 v[4:7], v[104:107], v[216:219], v[4:7]
	v_mfma_f32_16x16x32_f16 v[0:3], v[112:115], v[216:219], v[0:3]
	s_setprio 1
	s_barrier
	s_add_i32 s65, s65, 2
	s_add_u32 s34, s34, 0x100
	s_addc_u32 s35, s35, 0
	s_add_u32 s63, s63, 0x100
	s_addc_u32 s64, s64, 0
	s_cmp_gt_u32 s65, 13
	s_cbranch_scc0 .LBB0_1498
	s_and_b64 vcc, exec, s[14:15]
	s_cbranch_vccz .LBB0_1501
	s_barrier

.LBB0_1585:
	ds_read_b128 v[104:107], v171
	ds_read_b128 v[108:111], v171 offset:1024
	ds_read_b128 v[112:115], v171 offset:2048
	ds_read_b128 v[116:119], v171 offset:3072
	ds_read_b128 v[160:163], v172
	ds_read_b128 v[164:167], v172 offset:1024
	ds_read_b128 v[178:181], v172 offset:2048
	ds_read_b128 v[182:185], v172 offset:3072
	s_add_u32 s26, s24, 0xfffc0080
	s_addc_u32 s27, s25, -1
	s_cmp_eq_u32 s64, 12
	s_cselect_b32 s35, s17, s27
	s_cselect_b32 s34, s60, s26
	s_cselect_b32 s27, s15, s63
	s_cselect_b32 s26, s61, s62
	v_lshl_add_u64 v[202:203], s[24:25], 0, v[152:153]
	s_add_i32 m0, s23, 0xc000
	ds_read_b128 v[186:189], v173
	ds_read_b128 v[190:193], v173 offset:1024
	ds_read_b128 v[194:197], v173 offset:2048
	ds_read_b128 v[198:201], v173 offset:3072
	ds_read_b128 v[206:209], v173 offset:4096
	ds_read_b128 v[210:213], v173 offset:5120
	ds_read_b128 v[214:217], v173 offset:6144
	ds_read_b128 v[218:221], v173 offset:7168
	global_load_lds_dwordx4 v[202:203], off
	v_lshl_add_u64 v[202:203], s[24:25], 0, v[154:155]
	s_add_i32 m0, s23, 0xe000
	s_nop 0
	global_load_lds_dwordx4 v[202:203], off
	s_waitcnt vmcnt(8)
	s_waitcnt lgkmcnt(0)
	s_barrier
	s_setprio 0
	s_waitcnt lgkmcnt(0)
	v_mfma_f32_16x16x32_f16 v[140:143], v[104:107], v[186:189], v[140:143]
	v_mfma_f32_16x16x32_f16 v[136:139], v[112:115], v[186:189], v[136:139]
	v_mfma_f32_16x16x32_f16 v[124:127], v[104:107], v[194:197], v[124:127]
	v_mfma_f32_16x16x32_f16 v[120:123], v[112:115], v[194:197], v[120:123]
	v_mfma_f32_16x16x32_f16 v[92:95], v[104:107], v[206:209], v[92:95]
	v_mfma_f32_16x16x32_f16 v[88:91], v[112:115], v[206:209], v[88:91]
	v_mfma_f32_16x16x32_f16 v[76:79], v[104:107], v[214:217], v[76:79]
	v_mfma_f32_16x16x32_f16 v[72:75], v[112:115], v[214:217], v[72:75]
	v_mfma_f32_16x16x32_f16 v[140:143], v[108:111], v[190:193], v[140:143]
	v_mfma_f32_16x16x32_f16 v[136:139], v[116:119], v[190:193], v[136:139]
	v_mfma_f32_16x16x32_f16 v[124:127], v[108:111], v[198:201], v[124:127]
	v_mfma_f32_16x16x32_f16 v[120:123], v[116:119], v[198:201], v[120:123]
	v_mfma_f32_16x16x32_f16 v[92:95], v[108:111], v[210:213], v[92:95]
	v_mfma_f32_16x16x32_f16 v[88:91], v[116:119], v[210:213], v[88:91]
	v_mfma_f32_16x16x32_f16 v[76:79], v[108:111], v[218:221], v[76:79]
	v_mfma_f32_16x16x32_f16 v[72:75], v[116:119], v[218:221], v[72:75]
	s_setprio 1
	s_setprio 0
	v_mfma_f32_16x16x32_f16 v[132:135], v[160:163], v[186:189], v[132:135]
	v_mfma_f32_16x16x32_f16 v[128:131], v[178:181], v[186:189], v[128:131]
	v_mfma_f32_16x16x32_f16 v[100:103], v[160:163], v[194:197], v[100:103]
	v_mfma_f32_16x16x32_f16 v[96:99], v[178:181], v[194:197], v[96:99]
	v_mfma_f32_16x16x32_f16 v[84:87], v[160:163], v[206:209], v[84:87]
	v_mfma_f32_16x16x32_f16 v[80:83], v[178:181], v[206:209], v[80:83]
	v_mfma_f32_16x16x32_f16 v[68:71], v[160:163], v[214:217], v[68:71]
	v_mfma_f32_16x16x32_f16 v[64:67], v[178:181], v[214:217], v[64:67]
	v_mfma_f32_16x16x32_f16 v[132:135], v[164:167], v[190:193], v[132:135]
	v_mfma_f32_16x16x32_f16 v[128:131], v[182:185], v[190:193], v[128:131]
	v_mfma_f32_16x16x32_f16 v[100:103], v[164:167], v[198:201], v[100:103]
	v_mfma_f32_16x16x32_f16 v[96:99], v[182:185], v[198:201], v[96:99]
	v_mfma_f32_16x16x32_f16 v[84:87], v[164:167], v[210:213], v[84:87]
	v_mfma_f32_16x16x32_f16 v[80:83], v[182:185], v[210:213], v[80:83]
	v_mfma_f32_16x16x32_f16 v[68:71], v[164:167], v[218:221], v[68:71]
	v_mfma_f32_16x16x32_f16 v[64:67], v[182:185], v[218:221], v[64:67]
	s_setprio 1
	s_barrier
	s_add_i32 s65, s55, s41
	v_lshl_add_u64 v[202:203], s[26:27], 0, v[148:149]
	s_mov_b32 m0, s65
	ds_read_b128 v[186:189], v173 offset:16384
	ds_read_b128 v[190:193], v173 offset:17408
	ds_read_b128 v[194:197], v173 offset:18432
	ds_read_b128 v[198:201], v173 offset:19456
	ds_read_b128 v[206:209], v173 offset:20480
	ds_read_b128 v[210:213], v173 offset:21504
	ds_read_b128 v[214:217], v173 offset:22528
	ds_read_b128 v[218:221], v173 offset:23552
	global_load_lds_dwordx4 v[202:203], off
	s_add_i32 m0, s65, 0x2000
	s_add_u32 s66, s26, 0x40000
	v_lshl_add_u64 v[222:223], s[26:27], 0, v[144:145]
	s_addc_u32 s67, s27, 0
	s_add_i32 s65, s56, s41
	global_load_lds_dwordx4 v[222:223], off
	v_lshl_add_u64 v[224:225], s[66:67], 0, v[148:149]
	s_mov_b32 m0, s65
	v_lshl_add_u64 v[226:227], s[34:35], 0, v[146:147]
	global_load_lds_dwordx4 v[224:225], off
	v_lshl_add_u64 v[224:225], s[66:67], 0, v[144:145]
	s_add_i32 m0, s65, 0x2000
	s_nop 0
	global_load_lds_dwordx4 v[224:225], off
	v_lshl_add_u64 v[224:225], s[34:35], 0, v[150:151]
	s_mov_b32 m0, s23
	s_nop 0
	global_load_lds_dwordx4 v[224:225], off
	s_mov_b32 m0, s46
	s_nop 0
	global_load_lds_dwordx4 v[226:227], off
	s_waitcnt vmcnt(8)
	s_waitcnt lgkmcnt(0)
	s_barrier
	s_setprio 0
	s_waitcnt lgkmcnt(0)
	v_mfma_f32_16x16x32_f16 v[60:63], v[104:107], v[186:189], v[60:63]
	v_mfma_f32_16x16x32_f16 v[56:59], v[112:115], v[186:189], v[56:59]
	v_mfma_f32_16x16x32_f16 v[44:47], v[104:107], v[194:197], v[44:47]
	v_mfma_f32_16x16x32_f16 v[40:43], v[112:115], v[194:197], v[40:43]
	v_mfma_f32_16x16x32_f16 v[28:31], v[104:107], v[206:209], v[28:31]
	v_mfma_f32_16x16x32_f16 v[24:27], v[112:115], v[206:209], v[24:27]
	v_mfma_f32_16x16x32_f16 v[12:15], v[104:107], v[214:217], v[12:15]
	v_mfma_f32_16x16x32_f16 v[8:11], v[112:115], v[214:217], v[8:11]
	v_mfma_f32_16x16x32_f16 v[60:63], v[108:111], v[190:193], v[60:63]
	v_mfma_f32_16x16x32_f16 v[56:59], v[116:119], v[190:193], v[56:59]
	v_mfma_f32_16x16x32_f16 v[44:47], v[108:111], v[198:201], v[44:47]
	v_mfma_f32_16x16x32_f16 v[40:43], v[116:119], v[198:201], v[40:43]
	v_mfma_f32_16x16x32_f16 v[28:31], v[108:111], v[210:213], v[28:31]
	v_mfma_f32_16x16x32_f16 v[24:27], v[116:119], v[210:213], v[24:27]
	v_mfma_f32_16x16x32_f16 v[12:15], v[108:111], v[218:221], v[12:15]
	v_mfma_f32_16x16x32_f16 v[8:11], v[116:119], v[218:221], v[8:11]
	s_setprio 1
	s_setprio 0
	v_mfma_f32_16x16x32_f16 v[52:55], v[160:163], v[186:189], v[52:55]
	v_mfma_f32_16x16x32_f16 v[48:51], v[178:181], v[186:189], v[48:51]
	v_mfma_f32_16x16x32_f16 v[36:39], v[160:163], v[194:197], v[36:39]
	v_mfma_f32_16x16x32_f16 v[32:35], v[178:181], v[194:197], v[32:35]
	v_mfma_f32_16x16x32_f16 v[20:23], v[160:163], v[206:209], v[20:23]
	v_mfma_f32_16x16x32_f16 v[16:19], v[178:181], v[206:209], v[16:19]
	v_mfma_f32_16x16x32_f16 v[4:7], v[160:163], v[214:217], v[4:7]
	v_mfma_f32_16x16x32_f16 v[0:3], v[178:181], v[214:217], v[0:3]
	v_mfma_f32_16x16x32_f16 v[52:55], v[164:167], v[190:193], v[52:55]
	v_mfma_f32_16x16x32_f16 v[48:51], v[182:185], v[190:193], v[48:51]
	v_mfma_f32_16x16x32_f16 v[36:39], v[164:167], v[198:201], v[36:39]
	v_mfma_f32_16x16x32_f16 v[32:35], v[182:185], v[198:201], v[32:35]
	v_mfma_f32_16x16x32_f16 v[20:23], v[164:167], v[210:213], v[20:23]
	v_mfma_f32_16x16x32_f16 v[16:19], v[182:185], v[210:213], v[16:19]
	v_mfma_f32_16x16x32_f16 v[4:7], v[164:167], v[218:221], v[4:7]
	v_mfma_f32_16x16x32_f16 v[0:3], v[182:185], v[218:221], v[0:3]
	s_setprio 1
	s_barrier
	s_add_i32 s65, 0, 0x18000
	s_add_i32 s66, 0, 0x1c000
	v_add_u32_e32 v116, s65, v169
	v_add_u32_e32 v177, s66, v169
	ds_read_b128 v[104:107], v116
	ds_read_b128 v[108:111], v116 offset:1024
	ds_read_b128 v[112:115], v116 offset:2048
	ds_read_b128 v[116:119], v116 offset:3072
	ds_read_b128 v[160:163], v177
	ds_read_b128 v[164:167], v177 offset:1024
	ds_read_b128 v[178:181], v177 offset:2048
	ds_read_b128 v[182:185], v177 offset:3072
	s_add_u32 s34, s34, 0x40000
	s_addc_u32 s35, s35, 0
	s_mov_b32 m0, s47
	v_lshl_add_u64 v[228:229], s[34:35], 0, v[150:151]
	ds_read_b128 v[186:189], v173 offset:32768
	ds_read_b128 v[190:193], v173 offset:33792
	ds_read_b128 v[194:197], v173 offset:34816
	ds_read_b128 v[198:201], v173 offset:35840
	ds_read_b128 v[206:209], v173 offset:36864
	ds_read_b128 v[210:213], v173 offset:37888
	ds_read_b128 v[214:217], v173 offset:38912
	ds_read_b128 v[218:221], v173 offset:39936
	global_load_lds_dwordx4 v[228:229], off
	v_lshl_add_u64 v[228:229], s[34:35], 0, v[146:147]
	s_mov_b32 m0, s48
	s_nop 0
	global_load_lds_dwordx4 v[228:229], off
	s_waitcnt vmcnt(8)
	s_waitcnt lgkmcnt(0)
	s_barrier
	s_setprio 0
	s_waitcnt lgkmcnt(0)
	v_mfma_f32_16x16x32_f16 v[140:143], v[104:107], v[186:189], v[140:143]
	v_mfma_f32_16x16x32_f16 v[136:139], v[112:115], v[186:189], v[136:139]
	v_mfma_f32_16x16x32_f16 v[124:127], v[104:107], v[194:197], v[124:127]
	v_mfma_f32_16x16x32_f16 v[120:123], v[112:115], v[194:197], v[120:123]
	v_mfma_f32_16x16x32_f16 v[92:95], v[104:107], v[206:209], v[92:95]
	v_mfma_f32_16x16x32_f16 v[88:91], v[112:115], v[206:209], v[88:91]
	v_mfma_f32_16x16x32_f16 v[76:79], v[104:107], v[214:217], v[76:79]
	v_mfma_f32_16x16x32_f16 v[72:75], v[112:115], v[214:217], v[72:75]
	v_mfma_f32_16x16x32_f16 v[140:143], v[108:111], v[190:193], v[140:143]
	v_mfma_f32_16x16x32_f16 v[136:139], v[116:119], v[190:193], v[136:139]
	v_mfma_f32_16x16x32_f16 v[124:127], v[108:111], v[198:201], v[124:127]
	v_mfma_f32_16x16x32_f16 v[120:123], v[116:119], v[198:201], v[120:123]
	v_mfma_f32_16x16x32_f16 v[92:95], v[108:111], v[210:213], v[92:95]
	v_mfma_f32_16x16x32_f16 v[88:91], v[116:119], v[210:213], v[88:91]
	v_mfma_f32_16x16x32_f16 v[76:79], v[108:111], v[218:221], v[76:79]
	v_mfma_f32_16x16x32_f16 v[72:75], v[116:119], v[218:221], v[72:75]
	s_setprio 1
	s_setprio 0
	v_mfma_f32_16x16x32_f16 v[132:135], v[160:163], v[186:189], v[132:135]
	v_mfma_f32_16x16x32_f16 v[128:131], v[178:181], v[186:189], v[128:131]
	v_mfma_f32_16x16x32_f16 v[100:103], v[160:163], v[194:197], v[100:103]
	v_mfma_f32_16x16x32_f16 v[96:99], v[178:181], v[194:197], v[96:99]
	v_mfma_f32_16x16x32_f16 v[84:87], v[160:163], v[206:209], v[84:87]
	v_mfma_f32_16x16x32_f16 v[80:83], v[178:181], v[206:209], v[80:83]
	v_mfma_f32_16x16x32_f16 v[68:71], v[160:163], v[214:217], v[68:71]
	v_mfma_f32_16x16x32_f16 v[64:67], v[178:181], v[214:217], v[64:67]
	v_mfma_f32_16x16x32_f16 v[132:135], v[164:167], v[190:193], v[132:135]
	v_mfma_f32_16x16x32_f16 v[128:131], v[182:185], v[190:193], v[128:131]
	v_mfma_f32_16x16x32_f16 v[100:103], v[164:167], v[198:201], v[100:103]
	v_mfma_f32_16x16x32_f16 v[96:99], v[182:185], v[198:201], v[96:99]
	v_mfma_f32_16x16x32_f16 v[84:87], v[164:167], v[210:213], v[84:87]
	v_mfma_f32_16x16x32_f16 v[80:83], v[182:185], v[210:213], v[80:83]
	v_mfma_f32_16x16x32_f16 v[68:71], v[164:167], v[218:221], v[68:71]
	v_mfma_f32_16x16x32_f16 v[64:67], v[182:185], v[218:221], v[64:67]
	s_setprio 1
	s_barrier
	s_add_i32 s34, s65, s41
	v_lshl_add_u64 v[202:203], v[202:203], 0, s[10:11]
	s_mov_b32 m0, s34
	ds_read_b128 v[186:189], v173 offset:49152
	ds_read_b128 v[190:193], v173 offset:50176
	ds_read_b128 v[194:197], v173 offset:51200
	ds_read_b128 v[198:201], v173 offset:52224
	ds_read_b128 v[206:209], v173 offset:53248
	ds_read_b128 v[210:213], v173 offset:54272
	ds_read_b128 v[214:217], v173 offset:55296
	ds_read_b128 v[218:221], v173 offset:56320
	global_load_lds_dwordx4 v[202:203], off
	s_add_i32 m0, s34, 0x2000
	s_add_u32 s26, s26, 0x40080
	v_lshl_add_u64 v[202:203], v[222:223], 0, s[10:11]
	s_addc_u32 s27, s27, 0
	s_add_i32 s34, s66, s41
	global_load_lds_dwordx4 v[202:203], off
	v_lshl_add_u64 v[202:203], s[26:27], 0, v[148:149]
	s_mov_b32 m0, s34
	s_nop 0
	global_load_lds_dwordx4 v[202:203], off
	v_lshl_add_u64 v[202:203], s[26:27], 0, v[144:145]
	s_add_i32 m0, s34, 0x2000
	s_nop 0
	global_load_lds_dwordx4 v[202:203], off
	v_lshl_add_u64 v[202:203], v[224:225], 0, s[10:11]
	s_mov_b32 m0, s52
	s_nop 0
	global_load_lds_dwordx4 v[202:203], off
	v_lshl_add_u64 v[202:203], v[226:227], 0, s[10:11]
	s_mov_b32 m0, s53
	s_nop 0
	global_load_lds_dwordx4 v[202:203], off
	s_waitcnt vmcnt(8)
	s_waitcnt lgkmcnt(0)
	s_barrier
	s_setprio 0
	s_waitcnt lgkmcnt(0)
	v_mfma_f32_16x16x32_f16 v[60:63], v[104:107], v[186:189], v[60:63]
	v_mfma_f32_16x16x32_f16 v[56:59], v[112:115], v[186:189], v[56:59]
	v_mfma_f32_16x16x32_f16 v[44:47], v[104:107], v[194:197], v[44:47]
	v_mfma_f32_16x16x32_f16 v[40:43], v[112:115], v[194:197], v[40:43]
	v_mfma_f32_16x16x32_f16 v[28:31], v[104:107], v[206:209], v[28:31]
	v_mfma_f32_16x16x32_f16 v[24:27], v[112:115], v[206:209], v[24:27]
	v_mfma_f32_16x16x32_f16 v[12:15], v[104:107], v[214:217], v[12:15]
	v_mfma_f32_16x16x32_f16 v[8:11], v[112:115], v[214:217], v[8:11]
	v_mfma_f32_16x16x32_f16 v[60:63], v[108:111], v[190:193], v[60:63]
	v_mfma_f32_16x16x32_f16 v[56:59], v[116:119], v[190:193], v[56:59]
	v_mfma_f32_16x16x32_f16 v[44:47], v[108:111], v[198:201], v[44:47]
	v_mfma_f32_16x16x32_f16 v[40:43], v[116:119], v[198:201], v[40:43]
	v_mfma_f32_16x16x32_f16 v[28:31], v[108:111], v[210:213], v[28:31]
	v_mfma_f32_16x16x32_f16 v[24:27], v[116:119], v[210:213], v[24:27]
	v_mfma_f32_16x16x32_f16 v[12:15], v[108:111], v[218:221], v[12:15]
	v_mfma_f32_16x16x32_f16 v[8:11], v[116:119], v[218:221], v[8:11]
	s_setprio 1
	s_setprio 0
	v_mfma_f32_16x16x32_f16 v[52:55], v[160:163], v[186:189], v[52:55]
	v_mfma_f32_16x16x32_f16 v[48:51], v[178:181], v[186:189], v[48:51]
	v_mfma_f32_16x16x32_f16 v[36:39], v[160:163], v[194:197], v[36:39]
	v_mfma_f32_16x16x32_f16 v[32:35], v[178:181], v[194:197], v[32:35]
	v_mfma_f32_16x16x32_f16 v[20:23], v[160:163], v[206:209], v[20:23]
	v_mfma_f32_16x16x32_f16 v[16:19], v[178:181], v[206:209], v[16:19]
	v_mfma_f32_16x16x32_f16 v[4:7], v[160:163], v[214:217], v[4:7]
	v_mfma_f32_16x16x32_f16 v[0:3], v[178:181], v[214:217], v[0:3]
	v_mfma_f32_16x16x32_f16 v[52:55], v[164:167], v[190:193], v[52:55]
	v_mfma_f32_16x16x32_f16 v[48:51], v[182:185], v[190:193], v[48:51]
	v_mfma_f32_16x16x32_f16 v[36:39], v[164:167], v[198:201], v[36:39]
	v_mfma_f32_16x16x32_f16 v[32:35], v[182:185], v[198:201], v[32:35]
	v_mfma_f32_16x16x32_f16 v[20:23], v[164:167], v[210:213], v[20:23]
	v_mfma_f32_16x16x32_f16 v[16:19], v[182:185], v[210:213], v[16:19]
	v_mfma_f32_16x16x32_f16 v[4:7], v[164:167], v[218:221], v[4:7]
	v_mfma_f32_16x16x32_f16 v[0:3], v[182:185], v[218:221], v[0:3]
	s_setprio 1
	s_barrier
	s_add_i32 s64, s64, 2
	s_add_u32 s24, s24, 0x100
	s_addc_u32 s25, s25, 0
	s_add_u32 s62, s62, 0x100
	s_addc_u32 s63, s63, 0
	s_cmp_gt_u32 s64, 13
	s_cbranch_scc0 .LBB0_1585
	s_and_b64 vcc, exec, s[12:13]
	s_cbranch_vccz .LBB0_1588
	s_barrier

.LBB0_1668:
	ds_read_b128 v[144:147], v169
	ds_read_b128 v[148:151], v169 offset:1024
	ds_read_b128 v[152:155], v169 offset:2048
	ds_read_b128 v[156:159], v169 offset:3072
	ds_read_b128 v[160:163], v170
	ds_read_b128 v[172:175], v170 offset:1024
	ds_read_b128 v[176:179], v170 offset:2048
	ds_read_b128 v[180:183], v170 offset:3072
	s_add_u32 s24, s22, 0x100
	s_addc_u32 s25, s23, 0
	s_cmp_eq_u32 s60, 40
	s_cselect_b32 s31, s3, s25
	s_cselect_b32 s30, s2, s24
	s_cselect_b32 s27, s21, s59
	s_cselect_b32 s26, s20, s58
	v_lshl_add_u64 v[164:165], s[22:23], 0, v[136:137]
	s_add_i32 m0, s41, 0xc000
	ds_read_b128 v[184:187], v171
	ds_read_b128 v[188:191], v171 offset:1024
	ds_read_b128 v[192:195], v171 offset:2048
	ds_read_b128 v[196:199], v171 offset:3072
	ds_read_b128 v[200:203], v171 offset:4096
	ds_read_b128 v[204:207], v171 offset:5120
	ds_read_b128 v[208:211], v171 offset:6144
	ds_read_b128 v[212:215], v171 offset:7168
	global_load_lds_dwordx4 v[164:165], off
	v_lshl_add_u64 v[164:165], s[22:23], 0, v[138:139]
	s_add_i32 m0, s41, 0xe000
	s_nop 0
	global_load_lds_dwordx4 v[164:165], off
	s_waitcnt vmcnt(8)
	s_waitcnt lgkmcnt(0)
	s_barrier
	s_setprio 0
	s_waitcnt lgkmcnt(0)
	v_mfma_f32_16x16x32_f16 v[124:127], v[144:147], v[184:187], v[124:127]
	v_mfma_f32_16x16x32_f16 v[120:123], v[152:155], v[184:187], v[120:123]
	v_mfma_f32_16x16x32_f16 v[116:119], v[144:147], v[192:195], v[116:119]
	v_mfma_f32_16x16x32_f16 v[112:115], v[152:155], v[192:195], v[112:115]
	v_mfma_f32_16x16x32_f16 v[92:95], v[144:147], v[200:203], v[92:95]
	v_mfma_f32_16x16x32_f16 v[88:91], v[152:155], v[200:203], v[88:91]
	v_mfma_f32_16x16x32_f16 v[84:87], v[144:147], v[208:211], v[84:87]
	v_mfma_f32_16x16x32_f16 v[80:83], v[152:155], v[208:211], v[80:83]
	v_mfma_f32_16x16x32_f16 v[124:127], v[148:151], v[188:191], v[124:127]
	v_mfma_f32_16x16x32_f16 v[120:123], v[156:159], v[188:191], v[120:123]
	v_mfma_f32_16x16x32_f16 v[116:119], v[148:151], v[196:199], v[116:119]
	v_mfma_f32_16x16x32_f16 v[112:115], v[156:159], v[196:199], v[112:115]
	v_mfma_f32_16x16x32_f16 v[92:95], v[148:151], v[204:207], v[92:95]
	v_mfma_f32_16x16x32_f16 v[88:91], v[156:159], v[204:207], v[88:91]
	v_mfma_f32_16x16x32_f16 v[84:87], v[148:151], v[212:215], v[84:87]
	v_mfma_f32_16x16x32_f16 v[80:83], v[156:159], v[212:215], v[80:83]
	s_setprio 1
	s_setprio 0
	v_mfma_f32_16x16x32_f16 v[108:111], v[160:163], v[184:187], v[108:111]
	v_mfma_f32_16x16x32_f16 v[104:107], v[176:179], v[184:187], v[104:107]
	v_mfma_f32_16x16x32_f16 v[100:103], v[160:163], v[192:195], v[100:103]
	v_mfma_f32_16x16x32_f16 v[96:99], v[176:179], v[192:195], v[96:99]
	v_mfma_f32_16x16x32_f16 v[76:79], v[160:163], v[200:203], v[76:79]
	v_mfma_f32_16x16x32_f16 v[72:75], v[176:179], v[200:203], v[72:75]
	v_mfma_f32_16x16x32_f16 v[68:71], v[160:163], v[208:211], v[68:71]
	v_mfma_f32_16x16x32_f16 v[64:67], v[176:179], v[208:211], v[64:67]
	v_mfma_f32_16x16x32_f16 v[108:111], v[172:175], v[188:191], v[108:111]
	v_mfma_f32_16x16x32_f16 v[104:107], v[180:183], v[188:191], v[104:107]
	v_mfma_f32_16x16x32_f16 v[100:103], v[172:175], v[196:199], v[100:103]
	v_mfma_f32_16x16x32_f16 v[96:99], v[180:183], v[196:199], v[96:99]
	v_mfma_f32_16x16x32_f16 v[76:79], v[172:175], v[204:207], v[76:79]
	v_mfma_f32_16x16x32_f16 v[72:75], v[180:183], v[204:207], v[72:75]
	v_mfma_f32_16x16x32_f16 v[68:71], v[172:175], v[212:215], v[68:71]
	v_mfma_f32_16x16x32_f16 v[64:67], v[180:183], v[212:215], v[64:67]
	s_setprio 1
	s_barrier
	s_add_i32 s22, s51, s40
	v_lshl_add_u64 v[164:165], s[26:27], 0, v[130:131]
	s_mov_b32 m0, s22
	ds_read_b128 v[184:187], v171 offset:16384
	ds_read_b128 v[188:191], v171 offset:17408
	ds_read_b128 v[192:195], v171 offset:18432
	ds_read_b128 v[196:199], v171 offset:19456
	ds_read_b128 v[200:203], v171 offset:20480
	ds_read_b128 v[204:207], v171 offset:21504
	ds_read_b128 v[208:211], v171 offset:22528
	ds_read_b128 v[212:215], v171 offset:23552
	global_load_lds_dwordx4 v[164:165], off
	s_add_i32 m0, s22, 0x2000
	s_add_u32 s22, s26, 0xb0000
	v_lshl_add_u64 v[216:217], s[26:27], 0, v[134:135]
	s_addc_u32 s23, s27, 0
	s_add_i32 s61, s52, s40
	global_load_lds_dwordx4 v[216:217], off
	v_lshl_add_u64 v[218:219], s[22:23], 0, v[130:131]
	s_mov_b32 m0, s61
	v_lshl_add_u64 v[220:221], s[30:31], 0, v[132:133]
	global_load_lds_dwordx4 v[218:219], off
	v_lshl_add_u64 v[218:219], s[22:23], 0, v[134:135]
	s_add_i32 m0, s61, 0x2000
	s_nop 0
	global_load_lds_dwordx4 v[218:219], off
	v_lshl_add_u64 v[218:219], s[30:31], 0, v[128:129]
	s_mov_b32 m0, s41
	s_nop 0
	global_load_lds_dwordx4 v[218:219], off
	s_mov_b32 m0, s42
	s_nop 0
	global_load_lds_dwordx4 v[220:221], off
	s_waitcnt vmcnt(8)
	s_waitcnt lgkmcnt(0)
	s_barrier
	s_setprio 0
	s_waitcnt lgkmcnt(0)
	v_mfma_f32_16x16x32_f16 v[60:63], v[144:147], v[184:187], v[60:63]
	v_mfma_f32_16x16x32_f16 v[56:59], v[152:155], v[184:187], v[56:59]
	v_mfma_f32_16x16x32_f16 v[52:55], v[144:147], v[192:195], v[52:55]
	v_mfma_f32_16x16x32_f16 v[48:51], v[152:155], v[192:195], v[48:51]
	v_mfma_f32_16x16x32_f16 v[28:31], v[144:147], v[200:203], v[28:31]
	v_mfma_f32_16x16x32_f16 v[24:27], v[152:155], v[200:203], v[24:27]
	v_mfma_f32_16x16x32_f16 v[20:23], v[144:147], v[208:211], v[20:23]
	v_mfma_f32_16x16x32_f16 v[16:19], v[152:155], v[208:211], v[16:19]
	v_mfma_f32_16x16x32_f16 v[60:63], v[148:151], v[188:191], v[60:63]
	v_mfma_f32_16x16x32_f16 v[56:59], v[156:159], v[188:191], v[56:59]
	v_mfma_f32_16x16x32_f16 v[52:55], v[148:151], v[196:199], v[52:55]
	v_mfma_f32_16x16x32_f16 v[48:51], v[156:159], v[196:199], v[48:51]
	v_mfma_f32_16x16x32_f16 v[28:31], v[148:151], v[204:207], v[28:31]
	v_mfma_f32_16x16x32_f16 v[24:27], v[156:159], v[204:207], v[24:27]
	v_mfma_f32_16x16x32_f16 v[20:23], v[148:151], v[212:215], v[20:23]
	v_mfma_f32_16x16x32_f16 v[16:19], v[156:159], v[212:215], v[16:19]
	s_setprio 1
	s_setprio 0
	v_mfma_f32_16x16x32_f16 v[44:47], v[160:163], v[184:187], v[44:47]
	v_mfma_f32_16x16x32_f16 v[40:43], v[176:179], v[184:187], v[40:43]
	v_mfma_f32_16x16x32_f16 v[36:39], v[160:163], v[192:195], v[36:39]
	v_mfma_f32_16x16x32_f16 v[32:35], v[176:179], v[192:195], v[32:35]
	v_mfma_f32_16x16x32_f16 v[12:15], v[160:163], v[200:203], v[12:15]
	v_mfma_f32_16x16x32_f16 v[8:11], v[176:179], v[200:203], v[8:11]
	v_mfma_f32_16x16x32_f16 v[4:7], v[160:163], v[208:211], v[4:7]
	v_mfma_f32_16x16x32_f16 v[0:3], v[176:179], v[208:211], v[0:3]
	v_mfma_f32_16x16x32_f16 v[44:47], v[172:175], v[188:191], v[44:47]
	v_mfma_f32_16x16x32_f16 v[40:43], v[180:183], v[188:191], v[40:43]
	v_mfma_f32_16x16x32_f16 v[36:39], v[172:175], v[196:199], v[36:39]
	v_mfma_f32_16x16x32_f16 v[32:35], v[180:183], v[196:199], v[32:35]
	v_mfma_f32_16x16x32_f16 v[12:15], v[172:175], v[204:207], v[12:15]
	v_mfma_f32_16x16x32_f16 v[8:11], v[180:183], v[204:207], v[8:11]
	v_mfma_f32_16x16x32_f16 v[4:7], v[172:175], v[212:215], v[4:7]
	v_mfma_f32_16x16x32_f16 v[0:3], v[180:183], v[212:215], v[0:3]
	s_setprio 1
	s_barrier
	s_add_i32 s61, 0, 0x18000
	s_add_i32 s62, 0, 0x1c000
	v_add_u32_e32 v156, s61, v167
	v_add_u32_e32 v180, s62, v167
	ds_read_b128 v[144:147], v156
	ds_read_b128 v[148:151], v156 offset:1024
	ds_read_b128 v[152:155], v156 offset:2048
	ds_read_b128 v[156:159], v156 offset:3072
	ds_read_b128 v[160:163], v180
	ds_read_b128 v[172:175], v180 offset:1024
	ds_read_b128 v[176:179], v180 offset:2048
	ds_read_b128 v[180:183], v180 offset:3072
	s_add_u32 s22, s30, 0xb0000
	s_addc_u32 s23, s31, 0
	s_mov_b32 m0, s43
	v_lshl_add_u64 v[222:223], s[22:23], 0, v[128:129]
	ds_read_b128 v[184:187], v171 offset:32768
	ds_read_b128 v[188:191], v171 offset:33792
	ds_read_b128 v[192:195], v171 offset:34816
	ds_read_b128 v[196:199], v171 offset:35840
	ds_read_b128 v[200:203], v171 offset:36864
	ds_read_b128 v[204:207], v171 offset:37888
	ds_read_b128 v[208:211], v171 offset:38912
	ds_read_b128 v[212:215], v171 offset:39936
	global_load_lds_dwordx4 v[222:223], off
	v_lshl_add_u64 v[222:223], s[22:23], 0, v[132:133]
	s_mov_b32 m0, s44
	s_nop 0
	global_load_lds_dwordx4 v[222:223], off
	s_waitcnt vmcnt(8)
	s_waitcnt lgkmcnt(0)
	s_barrier
	s_setprio 0
	s_waitcnt lgkmcnt(0)
	v_mfma_f32_16x16x32_f16 v[124:127], v[144:147], v[184:187], v[124:127]
	v_mfma_f32_16x16x32_f16 v[120:123], v[152:155], v[184:187], v[120:123]
	v_mfma_f32_16x16x32_f16 v[116:119], v[144:147], v[192:195], v[116:119]
	v_mfma_f32_16x16x32_f16 v[112:115], v[152:155], v[192:195], v[112:115]
	v_mfma_f32_16x16x32_f16 v[92:95], v[144:147], v[200:203], v[92:95]
	v_mfma_f32_16x16x32_f16 v[88:91], v[152:155], v[200:203], v[88:91]
	v_mfma_f32_16x16x32_f16 v[84:87], v[144:147], v[208:211], v[84:87]
	v_mfma_f32_16x16x32_f16 v[80:83], v[152:155], v[208:211], v[80:83]
	v_mfma_f32_16x16x32_f16 v[124:127], v[148:151], v[188:191], v[124:127]
	v_mfma_f32_16x16x32_f16 v[120:123], v[156:159], v[188:191], v[120:123]
	v_mfma_f32_16x16x32_f16 v[116:119], v[148:151], v[196:199], v[116:119]
	v_mfma_f32_16x16x32_f16 v[112:115], v[156:159], v[196:199], v[112:115]
	v_mfma_f32_16x16x32_f16 v[92:95], v[148:151], v[204:207], v[92:95]
	v_mfma_f32_16x16x32_f16 v[88:91], v[156:159], v[204:207], v[88:91]
	v_mfma_f32_16x16x32_f16 v[84:87], v[148:151], v[212:215], v[84:87]
	v_mfma_f32_16x16x32_f16 v[80:83], v[156:159], v[212:215], v[80:83]
	s_setprio 1
	s_setprio 0
	v_mfma_f32_16x16x32_f16 v[108:111], v[160:163], v[184:187], v[108:111]
	v_mfma_f32_16x16x32_f16 v[104:107], v[176:179], v[184:187], v[104:107]
	v_mfma_f32_16x16x32_f16 v[100:103], v[160:163], v[192:195], v[100:103]
	v_mfma_f32_16x16x32_f16 v[96:99], v[176:179], v[192:195], v[96:99]
	v_mfma_f32_16x16x32_f16 v[76:79], v[160:163], v[200:203], v[76:79]
	v_mfma_f32_16x16x32_f16 v[72:75], v[176:179], v[200:203], v[72:75]
	v_mfma_f32_16x16x32_f16 v[68:71], v[160:163], v[208:211], v[68:71]
	v_mfma_f32_16x16x32_f16 v[64:67], v[176:179], v[208:211], v[64:67]
	v_mfma_f32_16x16x32_f16 v[108:111], v[172:175], v[188:191], v[108:111]
	v_mfma_f32_16x16x32_f16 v[104:107], v[180:183], v[188:191], v[104:107]
	v_mfma_f32_16x16x32_f16 v[100:103], v[172:175], v[196:199], v[100:103]
	v_mfma_f32_16x16x32_f16 v[96:99], v[180:183], v[196:199], v[96:99]
	v_mfma_f32_16x16x32_f16 v[76:79], v[172:175], v[204:207], v[76:79]
	v_mfma_f32_16x16x32_f16 v[72:75], v[180:183], v[204:207], v[72:75]
	v_mfma_f32_16x16x32_f16 v[68:71], v[172:175], v[212:215], v[68:71]
	v_mfma_f32_16x16x32_f16 v[64:67], v[180:183], v[212:215], v[64:67]
	s_setprio 1
	s_barrier
	s_add_i32 s22, s61, s40
	v_lshl_add_u64 v[164:165], v[164:165], 0, s[10:11]
	s_mov_b32 m0, s22
	ds_read_b128 v[184:187], v171 offset:49152
	ds_read_b128 v[188:191], v171 offset:50176
	ds_read_b128 v[192:195], v171 offset:51200
	ds_read_b128 v[196:199], v171 offset:52224
	ds_read_b128 v[200:203], v171 offset:53248
	ds_read_b128 v[204:207], v171 offset:54272
	ds_read_b128 v[208:211], v171 offset:55296
	ds_read_b128 v[212:215], v171 offset:56320
	global_load_lds_dwordx4 v[164:165], off
	s_add_i32 m0, s22, 0x2000
	s_add_u32 s22, s26, 0xb0080
	v_lshl_add_u64 v[164:165], v[216:217], 0, s[10:11]
	s_addc_u32 s23, s27, 0
	s_add_i32 s26, s62, s40
	global_load_lds_dwordx4 v[164:165], off
	v_lshl_add_u64 v[164:165], s[22:23], 0, v[130:131]
	s_mov_b32 m0, s26
	s_nop 0
	global_load_lds_dwordx4 v[164:165], off
	v_lshl_add_u64 v[164:165], s[22:23], 0, v[134:135]
	s_add_i32 m0, s26, 0x2000
	s_nop 0
	global_load_lds_dwordx4 v[164:165], off
	v_lshl_add_u64 v[164:165], v[218:219], 0, s[10:11]
	s_mov_b32 m0, s48
	s_nop 0
	global_load_lds_dwordx4 v[164:165], off
	v_lshl_add_u64 v[164:165], v[220:221], 0, s[10:11]
	s_mov_b32 m0, s49
	s_nop 0
	global_load_lds_dwordx4 v[164:165], off
	s_waitcnt vmcnt(8)
	s_waitcnt lgkmcnt(0)
	s_barrier
	s_setprio 0
	s_waitcnt lgkmcnt(0)
	v_mfma_f32_16x16x32_f16 v[60:63], v[144:147], v[184:187], v[60:63]
	v_mfma_f32_16x16x32_f16 v[56:59], v[152:155], v[184:187], v[56:59]
	v_mfma_f32_16x16x32_f16 v[52:55], v[144:147], v[192:195], v[52:55]
	v_mfma_f32_16x16x32_f16 v[48:51], v[152:155], v[192:195], v[48:51]
	v_mfma_f32_16x16x32_f16 v[28:31], v[144:147], v[200:203], v[28:31]
	v_mfma_f32_16x16x32_f16 v[24:27], v[152:155], v[200:203], v[24:27]
	v_mfma_f32_16x16x32_f16 v[20:23], v[144:147], v[208:211], v[20:23]
	v_mfma_f32_16x16x32_f16 v[16:19], v[152:155], v[208:211], v[16:19]
	v_mfma_f32_16x16x32_f16 v[60:63], v[148:151], v[188:191], v[60:63]
	v_mfma_f32_16x16x32_f16 v[56:59], v[156:159], v[188:191], v[56:59]
	v_mfma_f32_16x16x32_f16 v[52:55], v[148:151], v[196:199], v[52:55]
	v_mfma_f32_16x16x32_f16 v[48:51], v[156:159], v[196:199], v[48:51]
	v_mfma_f32_16x16x32_f16 v[28:31], v[148:151], v[204:207], v[28:31]
	v_mfma_f32_16x16x32_f16 v[24:27], v[156:159], v[204:207], v[24:27]
	v_mfma_f32_16x16x32_f16 v[20:23], v[148:151], v[212:215], v[20:23]
	v_mfma_f32_16x16x32_f16 v[16:19], v[156:159], v[212:215], v[16:19]
	s_setprio 1
	s_setprio 0
	v_mfma_f32_16x16x32_f16 v[44:47], v[160:163], v[184:187], v[44:47]
	v_mfma_f32_16x16x32_f16 v[40:43], v[176:179], v[184:187], v[40:43]
	v_mfma_f32_16x16x32_f16 v[36:39], v[160:163], v[192:195], v[36:39]
	v_mfma_f32_16x16x32_f16 v[32:35], v[176:179], v[192:195], v[32:35]
	v_mfma_f32_16x16x32_f16 v[12:15], v[160:163], v[200:203], v[12:15]
	v_mfma_f32_16x16x32_f16 v[8:11], v[176:179], v[200:203], v[8:11]
	v_mfma_f32_16x16x32_f16 v[4:7], v[160:163], v[208:211], v[4:7]
	v_mfma_f32_16x16x32_f16 v[0:3], v[176:179], v[208:211], v[0:3]
	v_mfma_f32_16x16x32_f16 v[44:47], v[172:175], v[188:191], v[44:47]
	v_mfma_f32_16x16x32_f16 v[40:43], v[180:183], v[188:191], v[40:43]
	v_mfma_f32_16x16x32_f16 v[36:39], v[172:175], v[196:199], v[36:39]
	v_mfma_f32_16x16x32_f16 v[32:35], v[180:183], v[196:199], v[32:35]
	v_mfma_f32_16x16x32_f16 v[12:15], v[172:175], v[204:207], v[12:15]
	v_mfma_f32_16x16x32_f16 v[8:11], v[180:183], v[204:207], v[8:11]
	v_mfma_f32_16x16x32_f16 v[4:7], v[172:175], v[212:215], v[4:7]
	v_mfma_f32_16x16x32_f16 v[0:3], v[180:183], v[212:215], v[0:3]
	s_setprio 1
	s_barrier
	s_add_i32 s60, s60, 2
	s_add_u32 s58, s58, 0x100
	s_addc_u32 s59, s59, 0
	s_cmp_gt_u32 s60, 41
	s_mov_b64 s[22:23], s[24:25]
	s_cbranch_scc0 .LBB0_1668
	s_and_b64 vcc, exec, s[12:13]
	s_cbranch_vccz .LBB0_1671
	s_barrier
